# wave reductions in norm / forget-gate / SGU-stat code: ds_bpermute butterflies replaced by bit-identical DPP quad_perm/row_mirror adds and v_permlane16/32_swap (no LDS round trips); GEMM phase prologu
# speedup vs baseline: 1.0102x; 1.0093x over previous
; __device__ __forceinline__ float bf_lo(unsigned w) { return __uint_as_float(w << 16); }
; __device__ __forceinline__ float bf_hi(unsigned w) { return __uint_as_float(w & 0xffff0000u); }
; __device__ __forceinline__ float wave_sum(float v) {
; #pragma unroll
;     for (int o = 1; o < 64; o <<= 1) v += __shfl_xor(v, o);
;     return v;
; }
; template <int MODE, bool INBF> ...
;     ...
;             for (int q = 0; q < RB; ++q) { const int row = blk * 64 + wave + 8 * (i0 + q);
;                 if (INBF) { const u32x2* xr = (const u32x2*)((const bf16*)xin_ + (size_t)row * DM) + lane;
; #pragma unroll
;                     for (int j = 0; j < 8; ++j) { const u32x2 w = xr[64 * j]; v[q][j] = (f32x4){bf_lo(w.x), bf_hi(w.x), bf_lo(w.y), bf_hi(w.y)}; }
;                 } else { const f32x4* xr = (const f32x4*)((const float*)xin_ + (size_t)row * DM) + lane;
; #pragma unroll
;                     for (int j = 0; j < 8; ++j) v[q][j] = xr[64 * j]; } }
; #pragma unroll
;             for (int q = 0; q < RB; ++q) { const int row = blk * 64 + wave + 8 * (i0 + q); float ss = 0.f;
; #pragma unroll
;                 for (int j = 0; j < 8; ++j) ss += (v[q][j].x * v[q][j].x + v[q][j].y * v[q][j].y) + (v[q][j].z * v[q][j].z + v[q][j].w * v[q][j].w);
;                 const float rstd = 1.0f / sqrtf(wave_sum(ss) * (1.0f / DM) + EPS);
.LBB0_121:
	v_add_co_u32_e32 v68, vcc, 0xfffff000, v66
	v_lshl_add_u64 v[106:107], v[64:65], 0, s[16:17]
	s_nop 0
	v_addc_co_u32_e32 v69, vcc, -1, v67, vcc
	v_add_co_u32_e32 v110, vcc, 0xfffff400, v66
	flat_load_dwordx4 v[12:15], v[66:67]
	flat_load_dwordx4 v[8:11], v[66:67] offset:1024
	flat_load_dwordx4 v[4:7], v[66:67] offset:2048
	flat_load_dwordx4 v[0:3], v[66:67] offset:3072
	v_add_co_u32_e64 v122, s[6:7], s21, v106
	v_addc_co_u32_e32 v111, vcc, -1, v67, vcc
	ds_read_b128 v[16:19], v76
	ds_read_b128 v[20:23], v76 offset:1024
	ds_read_b128 v[24:27], v76 offset:8192
	ds_read_b128 v[28:31], v76 offset:9216
	ds_read_b128 v[32:35], v76 offset:2048
	ds_read_b128 v[36:39], v76 offset:3072
	ds_read_b128 v[40:43], v76 offset:10240
	ds_read_b128 v[44:47], v76 offset:11264
	ds_read_b128 v[48:51], v76 offset:4096
	ds_read_b128 v[52:55], v76 offset:5120
	ds_read_b128 v[82:85], v76 offset:12288
	ds_read_b128 v[86:89], v76 offset:13312
	ds_read_b128 v[90:93], v76 offset:6144
	ds_read_b128 v[94:97], v76 offset:7168
	ds_read_b128 v[98:101], v76 offset:14336
	ds_read_b128 v[102:105], v76 offset:15360
	v_addc_co_u32_e64 v123, s[6:7], 0, v107, s[6:7]
	flat_load_dwordx4 v[106:109], v[68:69]
	s_add_u32 s16, s16, 0x8000
	flat_load_dwordx4 v[110:113], v[110:111]
	v_add_co_u32_e32 v68, vcc, 0xfffff800, v66
	s_addc_u32 s17, s17, 0
	s_nop 0
	v_addc_co_u32_e32 v69, vcc, -1, v67, vcc
	v_add_co_u32_e32 v118, vcc, 0xfffffc00, v66
	flat_load_dwordx4 v[114:117], v[68:69]
	s_nop 0
	v_addc_co_u32_e32 v119, vcc, -1, v67, vcc
	flat_load_dwordx4 v[118:121], v[118:119]
	s_cmp_lg_u32 s16, 0x40000
	v_lshl_add_u64 v[66:67], v[66:67], 0, s[14:15]
	s_waitcnt vmcnt(0) lgkmcnt(0)
	v_mul_f32_e32 v138, v14, v14
	v_pk_mul_f32 v[68:69], v[10:11], v[10:11]
	v_pk_mul_f32 v[124:125], v[8:9], v[8:9]
	v_mul_f32_e32 v129, v2, v2
	v_mul_f32_e32 v126, v5, v5
	v_mul_f32_e32 v128, v7, v7
	v_mul_f32_e32 v133, v3, v3
	v_pk_mov_b32 v[130:131], v[124:125], v[68:69] op_sel:[1,0]
	v_mov_b32_e32 v125, v69
	v_pk_fma_f32 v[68:69], v[4:5], v[4:5], v[126:127] op_sel_hi:[1,1,0]
	v_pk_fma_f32 v[126:127], v[6:7], v[6:7], v[128:129] op_sel_hi:[1,1,0]
	v_mov_b32_e32 v132, v107
	v_mov_b32_e32 v69, v129
	v_mov_b32_e32 v127, v133
	v_mov_b32_e32 v134, v109
	v_mov_b32_e32 v133, v111
	v_mov_b32_e32 v135, v113
	v_mov_b32_e32 v128, v106
	v_pk_add_f32 v[124:125], v[130:131], v[124:125]
	v_mov_b32_e32 v130, v108
	v_mov_b32_e32 v129, v110
	v_mov_b32_e32 v131, v112
	v_pk_add_f32 v[68:69], v[68:69], v[126:127]
	v_pk_mul_f32 v[126:127], v[132:133], v[132:133]
	v_pk_mul_f32 v[132:133], v[134:135], v[134:135]
	v_pk_mul_f32 v[134:135], v[116:117], v[116:117]
	v_pk_mul_f32 v[136:137], v[114:115], v[114:115]
	v_pk_fma_f32 v[126:127], v[128:129], v[128:129], v[126:127]
	v_pk_fma_f32 v[128:129], v[130:131], v[130:131], v[132:133]
	v_pk_mov_b32 v[130:131], v[136:137], v[134:135] op_sel:[1,0]
	v_mov_b32_e32 v137, v135
	v_mul_f32_e32 v132, v119, v119
	v_mul_f32_e32 v134, v121, v121
	v_pk_add_f32 v[126:127], v[126:127], v[128:129]
	v_pk_add_f32 v[128:129], v[130:131], v[136:137]
	v_mul_f32_e32 v139, v15, v15
	v_mul_f32_e32 v140, v12, v12
	v_mul_f32_e32 v141, v13, v13
	v_pk_fma_f32 v[130:131], v[118:119], v[118:119], v[132:133] op_sel_hi:[1,1,0]
	v_pk_fma_f32 v[132:133], v[120:121], v[120:121], v[134:135] op_sel_hi:[1,1,0]
	v_pk_add_f32 v[126:127], v[126:127], v[126:127] op_sel:[0,1] op_sel_hi:[1,0]
	v_pk_add_f32 v[128:129], v[128:129], v[128:129] op_sel:[0,1] op_sel_hi:[1,0]
	v_mov_b32_e32 v131, v138
	v_mov_b32_e32 v133, v139
	v_mov_b32_e32 v127, v140
	v_mov_b32_e32 v129, v141
	v_pk_add_f32 v[130:131], v[130:131], v[132:133]
	v_pk_add_f32 v[126:127], v[126:127], v[128:129]
	v_mul_f32_e32 v142, v1, v1
	v_pk_add_f32 v[126:127], v[126:127], v[130:131]
	v_mul_f32_e32 v143, v0, v0
	v_pk_add_f32 v[124:125], v[124:125], v[124:125] op_sel:[0,1] op_sel_hi:[1,0]
	v_pk_add_f32 v[126:127], v[126:127], v[126:127] op_sel:[0,1] op_sel_hi:[1,0]
	v_mov_b32_e32 v125, v142
	v_mov_b32_e32 v127, v143
	v_pk_add_f32 v[124:125], v[126:127], v[124:125]
	s_nop 0
	v_pk_add_f32 v[68:69], v[124:125], v[68:69]
	s_nop 0
	v_add_f32_e32 v68, v68, v69
	s_nop 0
	s_waitcnt lgkmcnt(0)
	s_nop 1
	v_add_f32_dpp v68, v68, v68 quad_perm:[1,0,3,2] row_mask:0xf bank_mask:0xf
	s_nop 0
	s_waitcnt lgkmcnt(0)
	s_nop 1
	v_add_f32_dpp v68, v68, v68 quad_perm:[2,3,0,1] row_mask:0xf bank_mask:0xf
	s_nop 0
	s_waitcnt lgkmcnt(0)
; #define LAS __attribute__((address_space(3)))
; __device__ __forceinline__ unsigned pk_bf16(float lo, float hi) { unsigned r; asm volatile("v_cvt_pk_bf16_f32 %0, %1, %2" : "=v"(r) : "v"(lo), "v"(hi)); return r; }
; __device__ __forceinline__ float wave_sum(float v) {
; #pragma unroll
;     for (int o = 1; o < 64; o <<= 1) v += __shfl_xor(v, o);
;     return v;
; }
; template <int MODE, bool INBF> ...
;     ...
;                 const float rstd = 1.0f / sqrtf(wave_sum(ss) * (1.0f / DM) + EPS);
; #pragma unroll
;                 for (int j = 0; j < 8; ++j) { const f32x4 a = *(const LAS f32x4*)(cA + 4 * (64 * j + lane)), bb = *(const LAS f32x4*)(cB + 4 * (64 * j + lane)); v[q][j] = (v[q][j] * rstd) * a + bb; }
;                 if (MODE == 1) { f32x4* o = (f32x4*)(outf + (size_t)row * DM) + lane;
; #pragma unroll
;                     for (int j = 0; j < 8; ++j) o[64 * j] = v[q][j];
;                 } else { u32x2* o = (u32x2*)(outb + (size_t)row * DM) + lane;
; #pragma unroll
;                     for (int j = 0; j < 8; ++j) { u32x2 w; w.x = pk_bf16(v[q][j].x, v[q][j].y); w.y = pk_bf16(v[q][j].z, v[q][j].w); o[64 * j] = w; } } }
	s_nop 1
	v_add_f32_dpp v68, v68, v68 row_half_mirror row_mask:0xf bank_mask:0xf
	s_nop 0
	s_waitcnt lgkmcnt(0)
	s_nop 1
	v_add_f32_dpp v68, v68, v68 row_mirror row_mask:0xf bank_mask:0xf
	v_mov_b32_e32 v69, v68
	s_waitcnt lgkmcnt(0)
	s_nop 1
	v_permlane16_swap_b32_e32 v68, v69
	v_add_f32_e32 v68, v68, v69
	v_mov_b32_e32 v69, v68
	s_waitcnt lgkmcnt(0)
	s_nop 1
	v_permlane32_swap_b32_e32 v68, v69
	v_add_f32_e32 v68, v68, v69
	v_fmamk_f32 v68, v68, 0x3a000000, v79
	v_mul_f32_e32 v69, 0x4f800000, v68
	v_cmp_gt_f32_e32 vcc, s20, v68
	s_nop 1
	v_cndmask_b32_e32 v68, v68, v69, vcc
	v_sqrt_f32_e32 v69, v68
	s_nop 0
	v_add_u32_e32 v124, -1, v69
	v_add_u32_e32 v125, 1, v69
	v_fma_f32 v126, -v124, v69, v68
	v_fma_f32 v127, -v125, v69, v68
	v_cmp_ge_f32_e64 s[6:7], 0, v126
	s_nop 1
	v_cndmask_b32_e64 v69, v69, v124, s[6:7]
	v_cmp_lt_f32_e64 s[6:7], 0, v127
	s_nop 1
	v_cndmask_b32_e64 v69, v69, v125, s[6:7]
	v_mul_f32_e32 v124, 0x37800000, v69
	v_cndmask_b32_e32 v69, v69, v124, vcc
	v_cmp_class_f32_e32 vcc, v68, v80
	s_nop 1
	v_cndmask_b32_e32 v68, v69, v68, vcc
	v_div_scale_f32 v69, s[6:7], v68, v68, 1.0
	v_rcp_f32_e32 v125, v69
	v_div_scale_f32 v124, vcc, 1.0, v68, 1.0
	v_fma_f32 v126, -v69, v125, 1.0
	v_fmac_f32_e32 v125, v126, v125
	v_mul_f32_e32 v126, v124, v125
	v_fma_f32 v127, -v69, v126, v124
	v_fmac_f32_e32 v126, v127, v125
	v_fma_f32 v69, -v69, v126, v124
	v_div_fmas_f32 v69, v69, v125, v126
	v_div_fixup_f32 v68, v69, v68, 1.0
	v_pk_mul_f32 v[106:107], v[106:107], v[68:69] op_sel_hi:[1,0]
	v_pk_mul_f32 v[108:109], v[108:109], v[68:69] op_sel_hi:[1,0]
	v_pk_fma_f32 v[16:17], v[16:17], v[106:107], v[24:25]
	v_pk_mul_f32 v[110:111], v[110:111], v[68:69] op_sel_hi:[1,0]
	v_pk_mul_f32 v[112:113], v[112:113], v[68:69] op_sel_hi:[1,0]
	v_pk_fma_f32 v[18:19], v[18:19], v[108:109], v[26:27]
	v_cvt_pk_bf16_f32 v16, v16, v17
	v_pk_mul_f32 v[114:115], v[114:115], v[68:69] op_sel_hi:[1,0]
	v_cvt_pk_bf16_f32 v17, v18, v19
	v_pk_mul_f32 v[116:117], v[116:117], v[68:69] op_sel_hi:[1,0]
	v_pk_mul_f32 v[12:13], v[12:13], v[68:69] op_sel_hi:[1,0]
	v_pk_mul_f32 v[8:9], v[8:9], v[68:69] op_sel_hi:[1,0]
	v_pk_mul_f32 v[4:5], v[4:5], v[68:69] op_sel_hi:[1,0]
	v_pk_mul_f32 v[0:1], v[0:1], v[68:69] op_sel_hi:[1,0]
	v_pk_fma_f32 v[22:23], v[22:23], v[112:113], v[30:31]
	v_pk_fma_f32 v[20:21], v[20:21], v[110:111], v[28:29]
	flat_store_dwordx2 v[122:123], v[16:17]
	v_cvt_pk_bf16_f32 v16, v20, v21
	v_cvt_pk_bf16_f32 v17, v22, v23
	v_pk_mul_f32 v[118:119], v[118:119], v[68:69] op_sel_hi:[1,0]
	v_pk_mul_f32 v[120:121], v[120:121], v[68:69] op_sel_hi:[1,0]
	v_pk_mul_f32 v[14:15], v[14:15], v[68:69] op_sel_hi:[1,0]
	v_pk_mul_f32 v[10:11], v[10:11], v[68:69] op_sel_hi:[1,0]
	v_pk_mul_f32 v[6:7], v[6:7], v[68:69] op_sel_hi:[1,0]
	v_pk_mul_f32 v[2:3], v[2:3], v[68:69] op_sel_hi:[1,0]
	v_pk_fma_f32 v[24:25], v[34:35], v[116:117], v[42:43]
	v_pk_fma_f32 v[26:27], v[32:33], v[114:115], v[40:41]
	v_pk_fma_f32 v[12:13], v[48:49], v[12:13], v[82:83]
	v_pk_fma_f32 v[8:9], v[52:53], v[8:9], v[86:87]
	v_pk_fma_f32 v[4:5], v[4:5], v[90:91], v[98:99]
	v_pk_fma_f32 v[0:1], v[0:1], v[94:95], v[102:103]
	flat_store_dwordx2 v[122:123], v[16:17] offset:512
	v_cvt_pk_bf16_f32 v16, v26, v27
	v_cvt_pk_bf16_f32 v17, v24, v25
	v_pk_fma_f32 v[28:29], v[38:39], v[120:121], v[46:47]
	v_pk_fma_f32 v[30:31], v[36:37], v[118:119], v[44:45]
	v_pk_fma_f32 v[14:15], v[50:51], v[14:15], v[84:85]
	v_pk_fma_f32 v[10:11], v[54:55], v[10:11], v[88:89]
	v_pk_fma_f32 v[6:7], v[6:7], v[92:93], v[100:101]
	v_pk_fma_f32 v[2:3], v[2:3], v[96:97], v[104:105]
	flat_store_dwordx2 v[122:123], v[16:17] offset:1024
	v_cvt_pk_bf16_f32 v16, v30, v31
	v_cvt_pk_bf16_f32 v17, v28, v29
	flat_store_dwordx2 v[122:123], v[16:17] offset:1536
	v_cvt_pk_bf16_f32 v12, v12, v13
	v_cvt_pk_bf16_f32 v13, v14, v15
	flat_store_dwordx2 v[122:123], v[12:13] offset:2048
	v_cvt_pk_bf16_f32 v8, v8, v9
	v_cvt_pk_bf16_f32 v9, v10, v11
	flat_store_dwordx2 v[122:123], v[8:9] offset:2560
	v_cvt_pk_bf16_f32 v4, v4, v5
	v_cvt_pk_bf16_f32 v5, v6, v7
	flat_store_dwordx2 v[122:123], v[4:5] offset:3072
	v_cvt_pk_bf16_f32 v0, v0, v1
	v_cvt_pk_bf16_f32 v1, v2, v3
	flat_store_dwordx2 v[122:123], v[0:1] offset:3584
	s_cbranch_scc1 .LBB0_121
	s_add_i32 s22, s22, s3
	s_add_i32 s10, s10, s18
	s_cmpk_lt_i32 s22, 0x100
	s_cbranch_scc1 .LBB0_117

; #define PG8_STAGE(bufoff, gbase, voff) do { _Pragma("unroll") for (int _i = 0; _i < 2; ++_i) \
;         __builtin_amdgcn_global_load_lds((const unsigned*)((const char*)(gbase) + (voff)[_i]), (PG8_LAS unsigned*)(lds + (bufoff) + ldsw + _i * 8192), 16, 0, 0); } while (0)
; #define PG8_WAIT_V(n) asm volatile("s_waitcnt vmcnt(" #n ")" ::: "memory")
; #define PG8_BAR __builtin_amdgcn_s_barrier()
; template <class Epi, class Sched, bool ALIGN_EPI = false, bool SP2 = false>
; __device__ __forceinline__ void gemm_phase(PG8_LAS unsigned char* lds, const Gemm g, const Sched& S, const Epi& E) {
;     ...
;         PG8_STAGE(PG8_SB(0, 0), cB, voffB); PG8_STAGE(PG8_SB(0, 1), cB + hstep, voffB); PG8_STAGE(PG8_SA(0, 0), cA, voffA); PG8_STAGE(PG8_SA(0, 1), cA + hstep, voffA);
;         if (wr == 1) PG8_BAR;
;         PG8_WAIT_V(2); PG8_BAR;
;         PG8_STAGE(PG8_SB(1, 0), cB + kstep, voffB); PG8_STAGE(PG8_SA(1, 0), cA + kstep, voffA); PG8_STAGE(PG8_SB(1, 1), cB + hstep + kstep, voffB);
;         PG8_WAIT_V(6); PG8_BAR;
.LBB0_182:
	s_add_u32 s73, s4, 0x10400000
	s_addc_u32 s74, s5, 0
	s_lshl_b32 s4, s16, 5
	s_mov_b64 s[16:17], 0x80
	s_and_b32 s21, s4, 0x60
	s_add_i32 m0, s63, 0x18000
	v_lshl_add_u64 v[6:7], v[6:7], 0, s[16:17]
	s_lshl_b32 s20, s19, 13
	s_lshl_b32 s22, s21, 7
	global_load_lds_dwordx4 v[6:7], off
	v_lshl_add_u64 v[2:3], v[2:3], 0, s[16:17]
	s_add_i32 m0, s63, 0x1a000
	s_add_i32 s75, s63, 0x8000
	s_add_i32 s76, s63, 0xa000
	global_load_lds_dwordx4 v[2:3], off
	v_lshl_add_u64 v[0:1], v[0:1], 0, s[16:17]
	s_mov_b32 m0, s75
	s_add_u32 s4, s6, 0x80080
	global_load_lds_dwordx4 v[0:1], off
	v_lshl_add_u64 v[0:1], v[4:5], 0, s[16:17]
	s_mov_b32 m0, s76
	s_addc_u32 s5, s7, 0
	global_load_lds_dwordx4 v[0:1], off
	s_add_i32 m0, s63, 0x1c000
	v_lshl_add_u64 v[0:1], s[4:5], 0, v[146:147]
	global_load_lds_dwordx4 v[0:1], off
	v_lshl_add_u64 v[0:1], s[4:5], 0, v[150:151]
	s_add_i32 m0, s63, 0x1e000
	s_cmpk_lt_u32 s18, 0x100
	global_load_lds_dwordx4 v[0:1], off
	s_waitcnt vmcnt(8)
	s_barrier
	v_lshrrev_b32_e32 v1, 1, v8
	v_and_b32_e32 v1, 24, v1
	v_and_b32_e32 v0, 15, v8
	v_lshlrev_b32_e32 v2, 1, v1
	v_lshl_or_b32 v166, s19, 6, v0
	v_lshl_or_b32 v0, v0, 6, v2
	v_lshlrev_b32_e32 v2, 2, v8
	v_and_b32_e32 v2, 32, v2
	v_bitop3_b32 v3, v0, s20, v2 bitop3:0xde
	v_bitop3_b32 v167, v0, s22, v2 bitop3:0xde
	v_lshlrev_b32_e32 v0, 15, v12
	v_and_b32_e32 v0, 0xffff0000, v0
	v_or_b32_e32 v168, s21, v1
	v_lshl_add_u32 v0, v13, 12, v0
	v_and_b32_e32 v1, 1, v12
	v_lshl_or_b32 v0, v1, 6, v0
	v_lshl_add_u32 v152, v14, 1, v0
	v_lshlrev_b32_e32 v0, 15, v9
	s_cselect_b64 s[18:19], -1, 0
	s_ashr_i32 s77, s3, 31
	v_and_b32_e32 v0, 0xffff0000, v0
	s_waitcnt vmcnt(6)
	s_waitcnt lgkmcnt(0)
	s_cmp_lg_u64 s[10:11], 0
	v_lshl_add_u32 v0, v10, 12, v0
	v_and_b32_e32 v1, 1, v9
	s_cselect_b64 s[20:21], -1, 0
	v_lshl_or_b32 v0, v1, 6, v0
	s_add_i32 s78, 0, 0x10000
	s_add_i32 s79, 0, 0x14000
	v_mov_b32_e32 v153, v147
	v_lshl_add_u32 v154, v11, 1, v0
	v_mov_b32_e32 v155, v147
	v_mov_b64_e32 v[156:157], 0x400
	v_mov_b64_e32 v[158:159], 0x3ff
	v_add_u32_e32 v169, s78, v167
	v_add_u32_e32 v170, s79, v167
	v_add_u32_e32 v171, 0, v3
	s_mov_b32 s22, 0x3e6d3388
	s_mov_b32 s24, 0x3f07dc22
	s_mov_b32 s26, 0xbf3a00e3
	s_mov_b32 s28, 0x3f35f0e3
	s_mov_b32 s30, 0xbe11a98e
	s_mov_b32 s34, 0x3e027906
	s_mov_b32 s36, 0xbf38aa3b
	s_mov_b32 s80, 0x80000
	s_mov_b64 s[48:49], 0x90000
	s_mov_b32 s81, 0x90000
	s_mov_b64 s[50:51], 0xa0000
	s_mov_b32 s82, 0xa0000
	s_mov_b64 s[52:53], 0xb0000
	s_mov_b32 s83, 0xb0000
	s_barrier
	s_branch .LBB0_185

; __device__ __forceinline__ float bf_lo(unsigned w) { return __uint_as_float(w << 16); }
; __device__ __forceinline__ float bf_hi(unsigned w) { return __uint_as_float(w & 0xffff0000u); }
; __device__ __forceinline__ float wave_sum(float v) {
; #pragma unroll
;     for (int o = 1; o < 64; o <<= 1) v += __shfl_xor(v, o);
;     return v;
; }
; __device__ __forceinline__ void sgu_phase(LAS unsigned char* lds, const bf16* __restrict__ U, const bf16* __restrict__ V, bf16* __restrict__ Y, const bf16* __restrict__ Wm, ...
;     ...
;         for (int rb = 0; rb < 16; rb += 4) { u32x4 sw[4][4];
; #pragma unroll
;             for (int q = 0; q < 4; ++q) { const u32x4* vp = (const u32x4*)(V + (size_t)(row0 + wave * 16 + rb + q) * DM) + lane;
; #pragma unroll
;                 for (int j = 0; j < 4; ++j) sw[q][j] = vp[64 * j]; }
; #pragma unroll
;             for (int q = 0; q < 4; ++q) { const int rl = wave * 16 + rb + q; float s = 0.f, qq = 0.f;
; #pragma unroll
;                 for (int j = 0; j < 4; ++j) { const u32x4 w = sw[q][j];
;                     const float x0 = bf_lo(w.x), x1 = bf_hi(w.x), x2 = bf_lo(w.y), x3 = bf_hi(w.y), x4 = bf_lo(w.z), x5 = bf_hi(w.z), x6 = bf_lo(w.w), x7 = bf_hi(w.w);
;                     s += ((x0 + x1) + (x2 + x3)) + ((x4 + x5) + (x6 + x7)); qq += ((x0 * x0 + x1 * x1) + (x2 * x2 + x3 * x3)) + ((x4 * x4 + x5 * x5) + (x6 * x6 + x7 * x7)); }
;                 s = wave_sum(s); qq = wave_sum(qq); const float mean = s * (1.0f / DM); const float var = fmaxf(qq * (1.0f / DM) - mean * mean, 0.f);
;                 if (lane == 0) { st[2 * rl] = mean; st[2 * rl + 1] = 1.0f / sqrtf(var + EPS); } } }
.LBB0_264:
	s_waitcnt vmcnt(0)
	v_add_co_u32_e32 v0, vcc, 0xffffc400, v48
	s_waitcnt lgkmcnt(1)
	s_nop 0
	v_addc_co_u32_e32 v1, vcc, -1, v49, vcc
	v_add_co_u32_e32 v2, vcc, 0xffffc800, v48
	s_waitcnt lgkmcnt(0)
	s_nop 0
	v_addc_co_u32_e32 v3, vcc, -1, v49, vcc
	flat_load_dwordx4 v[50:53], v[0:1]
	flat_load_dwordx4 v[54:57], v[2:3]
	v_add_co_u32_e32 v0, vcc, 0xffffcc00, v48
	s_waitcnt vmcnt(0) lgkmcnt(0)
	v_lshlrev_b32_e32 v66, 16, v50
	v_addc_co_u32_e32 v1, vcc, -1, v49, vcc
	v_add_co_u32_e32 v2, vcc, 0xffffd000, v48
	v_and_b32_e32 v50, 0xffff0000, v50
	s_nop 0
	v_addc_co_u32_e32 v3, vcc, -1, v49, vcc
	flat_load_dwordx4 v[58:61], v[0:1]
	flat_load_dwordx4 v[62:65], v[2:3]
	v_add_co_u32_e32 v0, vcc, 0xffffd400, v48
	v_lshlrev_b32_e32 v67, 16, v51
	s_nop 0
	v_addc_co_u32_e32 v1, vcc, -1, v49, vcc
	v_add_co_u32_e32 v2, vcc, 0xffffd800, v48
	v_and_b32_e32 v51, 0xffff0000, v51
	s_nop 0
	v_addc_co_u32_e32 v3, vcc, -1, v49, vcc
	flat_load_dwordx4 v[44:47], v[0:1]
	flat_load_dwordx4 v[40:43], v[2:3]
	v_add_co_u32_e32 v0, vcc, 0xffffdc00, v48
	v_add_f32_e32 v83, v66, v50
	s_nop 0
	v_addc_co_u32_e32 v1, vcc, -1, v49, vcc
	v_add_co_u32_e32 v2, vcc, 0xffffe000, v48
	v_add_f32_e32 v84, v67, v51
	s_nop 0
	v_addc_co_u32_e32 v3, vcc, -1, v49, vcc
	flat_load_dwordx4 v[36:39], v[0:1]
	flat_load_dwordx4 v[32:35], v[2:3]
	v_add_co_u32_e32 v0, vcc, 0xffffe400, v48
	v_mul_f32_e32 v50, v50, v50
	s_nop 0
	v_addc_co_u32_e32 v1, vcc, -1, v49, vcc
	v_add_co_u32_e32 v2, vcc, 0xffffe800, v48
	v_mul_f32_e32 v51, v51, v51
	s_nop 0
	v_addc_co_u32_e32 v3, vcc, -1, v49, vcc
	flat_load_dwordx4 v[28:31], v[0:1]
	flat_load_dwordx4 v[24:27], v[2:3]
	v_add_co_u32_e32 v0, vcc, 0xffffec00, v48
	v_lshlrev_b32_e32 v70, 16, v52
	s_nop 0
	v_addc_co_u32_e32 v1, vcc, -1, v49, vcc
	v_add_co_u32_e32 v2, vcc, 0xfffff000, v48
	v_and_b32_e32 v52, 0xffff0000, v52
	s_nop 0
	v_addc_co_u32_e32 v3, vcc, -1, v49, vcc
	flat_load_dwordx4 v[20:23], v[0:1]
	flat_load_dwordx4 v[16:19], v[2:3]
	v_add_co_u32_e32 v0, vcc, 0xfffff400, v48
	v_lshlrev_b32_e32 v82, 16, v53
	s_nop 0
	v_addc_co_u32_e32 v1, vcc, -1, v49, vcc
	v_add_co_u32_e32 v2, vcc, 0xfffff800, v48
	v_and_b32_e32 v53, 0xffff0000, v53
	s_nop 0
	v_addc_co_u32_e32 v3, vcc, -1, v49, vcc
	flat_load_dwordx4 v[12:15], v[0:1]
	flat_load_dwordx4 v[8:11], v[2:3]
	v_add_co_u32_e32 v0, vcc, 0xfffffc00, v48
	v_fmac_f32_e32 v50, v66, v66
	s_nop 0
	v_addc_co_u32_e32 v1, vcc, -1, v49, vcc
	flat_load_dwordx4 v[4:7], v[0:1]
	s_nop 0
	flat_load_dwordx4 v[0:3], v[48:49]
	v_fmac_f32_e32 v51, v67, v67
	v_add_f32_e32 v83, v83, v84
	v_add_f32_e32 v84, v70, v52
	v_add_f32_e32 v50, v50, v51
	v_mul_f32_e32 v51, v52, v52
	v_mul_f32_e32 v52, v53, v53
	v_fmac_f32_e32 v51, v70, v70
	v_fmac_f32_e32 v52, v82, v82
	v_add_f32_e32 v51, v51, v52
	v_add_f32_e32 v50, v50, v51
	v_lshlrev_b32_e32 v51, 16, v54
	v_and_b32_e32 v52, 0xffff0000, v54
	v_and_b32_e32 v54, 0xffff0000, v55
	v_add_f32_e32 v67, v51, v52
	v_mul_f32_e32 v52, v52, v52
	v_add_f32_e32 v85, v82, v53
	v_lshlrev_b32_e32 v53, 16, v55
	v_fmac_f32_e32 v52, v51, v51
	v_mul_f32_e32 v51, v54, v54
	v_lshlrev_b32_e32 v55, 16, v56
	v_and_b32_e32 v56, 0xffff0000, v56
	v_lshlrev_b32_e32 v66, 16, v57
	v_and_b32_e32 v57, 0xffff0000, v57
	v_fmac_f32_e32 v51, v53, v53
	v_add_f32_e32 v70, v53, v54
	v_add_f32_e32 v51, v52, v51
	v_mul_f32_e32 v52, v56, v56
	v_mul_f32_e32 v53, v57, v57
	v_fmac_f32_e32 v52, v55, v55
	v_fmac_f32_e32 v53, v66, v66
	v_add_f32_e32 v52, v52, v53
	v_add_f32_e32 v51, v51, v52
	v_add_f32_e32 v50, v50, v51
	s_waitcnt vmcnt(0) lgkmcnt(0)
	v_lshlrev_b32_e32 v51, 16, v58
	v_and_b32_e32 v52, 0xffff0000, v58
	v_lshlrev_b32_e32 v53, 16, v59
	v_and_b32_e32 v54, 0xffff0000, v59
	v_add_f32_e32 v59, v51, v52
	v_mul_f32_e32 v52, v52, v52
	v_fmac_f32_e32 v52, v51, v51
	v_mul_f32_e32 v51, v54, v54
	v_add_f32_e32 v67, v67, v70
	v_add_f32_e32 v70, v55, v56
	v_and_b32_e32 v56, 0xffff0000, v60
	v_and_b32_e32 v58, 0xffff0000, v61
	v_fmac_f32_e32 v51, v53, v53
	v_add_f32_e32 v82, v66, v57
	v_lshlrev_b32_e32 v55, 16, v60
	v_lshlrev_b32_e32 v57, 16, v61
	v_add_f32_e32 v60, v53, v54
	v_add_f32_e32 v51, v52, v51
	v_mul_f32_e32 v52, v56, v56
	v_mul_f32_e32 v53, v58, v58
	v_fmac_f32_e32 v52, v55, v55
	v_fmac_f32_e32 v53, v57, v57
	v_add_f32_e32 v52, v52, v53
	v_add_f32_e32 v59, v59, v60
	v_add_f32_e32 v60, v55, v56
	v_add_f32_e32 v61, v57, v58
	v_add_f32_e32 v51, v51, v52
	v_add_f32_e32 v60, v60, v61
	v_add_f32_e32 v50, v50, v51
	v_lshlrev_b32_e32 v51, 16, v62
	v_and_b32_e32 v52, 0xffff0000, v62
	v_add_f32_e32 v59, v59, v60
	v_and_b32_e32 v54, 0xffff0000, v63
	v_add_f32_e32 v60, v51, v52
	v_mul_f32_e32 v52, v52, v52
	v_lshlrev_b32_e32 v53, 16, v63
	v_fmac_f32_e32 v52, v51, v51
	v_mul_f32_e32 v51, v54, v54
	v_add_f32_e32 v84, v84, v85
	v_and_b32_e32 v56, 0xffff0000, v64
	v_and_b32_e32 v58, 0xffff0000, v65
	v_fmac_f32_e32 v51, v53, v53
	v_add_f32_e32 v83, v83, v84
	v_add_f32_e32 v70, v70, v82
	v_lshlrev_b32_e32 v55, 16, v64
	v_lshlrev_b32_e32 v57, 16, v65
	v_add_f32_e32 v61, v53, v54
	v_add_f32_e32 v51, v52, v51
	v_mul_f32_e32 v52, v56, v56
	v_mul_f32_e32 v53, v58, v58
	v_add_f32_e32 v83, 0, v83
	v_add_f32_e32 v67, v67, v70
	v_add_f32_e32 v60, v60, v61
	v_add_f32_e32 v61, v55, v56
	v_add_f32_e32 v62, v57, v58
	v_fmac_f32_e32 v52, v55, v55
	v_fmac_f32_e32 v53, v57, v57
	v_add_f32_e32 v67, v83, v67
	v_add_f32_e32 v61, v61, v62
	v_add_f32_e32 v52, v52, v53
	v_add_f32_e32 v59, v67, v59
	v_add_f32_e32 v60, v60, v61
	v_add_f32_e32 v51, v51, v52
	v_add_f32_e32 v59, v59, v60
	v_add_f32_e32 v50, v50, v51
	s_nop 0
	s_nop 0
	s_waitcnt lgkmcnt(1)
	s_nop 1
	v_add_f32_dpp v52, v59, v59 quad_perm:[1,0,3,2] row_mask:0xf bank_mask:0xf
	s_waitcnt lgkmcnt(0)
	s_nop 1
	v_add_f32_dpp v50, v50, v50 quad_perm:[1,0,3,2] row_mask:0xf bank_mask:0xf
	s_nop 0
	s_nop 0
	s_waitcnt lgkmcnt(1)
	s_nop 1
	v_add_f32_dpp v52, v52, v52 quad_perm:[2,3,0,1] row_mask:0xf bank_mask:0xf
	s_waitcnt lgkmcnt(0)
	s_nop 1
	v_add_f32_dpp v50, v50, v50 quad_perm:[2,3,0,1] row_mask:0xf bank_mask:0xf
	s_nop 0
	s_nop 0
	s_waitcnt lgkmcnt(1)
	s_nop 1
	v_add_f32_dpp v52, v52, v52 row_half_mirror row_mask:0xf bank_mask:0xf
	s_waitcnt lgkmcnt(0)
	s_nop 1
	v_add_f32_dpp v50, v50, v50 row_half_mirror row_mask:0xf bank_mask:0xf
	s_nop 0
	s_nop 0
	s_waitcnt lgkmcnt(1)
	s_nop 1
	v_add_f32_dpp v52, v52, v52 row_mirror row_mask:0xf bank_mask:0xf
	s_waitcnt lgkmcnt(0)
	s_nop 1
	v_add_f32_dpp v54, v50, v50 row_mirror row_mask:0xf bank_mask:0xf
	v_mov_b32_e32 v53, v52
	ds_bpermute_b32 v55, v109, v54
	s_waitcnt lgkmcnt(1)
	s_nop 1
	v_permlane16_swap_b32_e32 v52, v53
	v_add_f32_e32 v50, v52, v53
	s_waitcnt lgkmcnt(0)
	v_add_f32_e32 v52, v54, v55
	ds_bpermute_b32 v51, v110, v50
	ds_bpermute_b32 v53, v110, v52
	s_and_saveexec_b64 s[34:35], s[6:7]
	s_cbranch_execz .LBB0_266
; __device__ __forceinline__ float bf_lo(unsigned w) { return __uint_as_float(w << 16); }
; __device__ __forceinline__ float bf_hi(unsigned w) { return __uint_as_float(w & 0xffff0000u); }
; __device__ __forceinline__ void sgu_phase(LAS unsigned char* lds, const bf16* __restrict__ U, const bf16* __restrict__ V, bf16* __restrict__ Y, const bf16* __restrict__ Wm, ...
;     ...
;             for (int q = 0; q < 4; ++q) { const int rl = wave * 16 + rb + q; float s = 0.f, qq = 0.f;
; #pragma unroll
;                 for (int j = 0; j < 4; ++j) { const u32x4 w = sw[q][j];
;                     const float x0 = bf_lo(w.x), x1 = bf_hi(w.x), x2 = bf_lo(w.y), x3 = bf_hi(w.y), x4 = bf_lo(w.z), x5 = bf_hi(w.z), x6 = bf_lo(w.w), x7 = bf_hi(w.w);
;                     s += ((x0 + x1) + (x2 + x3)) + ((x4 + x5) + (x6 + x7)); qq += ((x0 * x0 + x1 * x1) + (x2 * x2 + x3 * x3)) + ((x4 * x4 + x5 * x5) + (x6 * x6 + x7 * x7)); }
;                 s = wave_sum(s); qq = wave_sum(qq); const float mean = s * (1.0f / DM); const float var = fmaxf(qq * (1.0f / DM) - mean * mean, 0.f);
;                 if (lane == 0) { st[2 * rl] = mean; st[2 * rl + 1] = 1.0f / sqrtf(var + EPS); } } }
	s_waitcnt lgkmcnt(1)
	v_add_f32_e32 v50, v50, v51
	v_mul_f32_e32 v50, 0x3a000000, v50
	s_waitcnt lgkmcnt(0)
	v_add_f32_e32 v52, v52, v53
	v_mul_f32_e32 v51, v50, v50
	v_fma_f32 v51, v52, s55, -v51
	v_max_f32_e32 v51, 0, v51
	v_add_f32_e32 v51, 0x358637bd, v51
	v_mul_f32_e32 v52, 0x4f800000, v51
	v_cmp_gt_f32_e32 vcc, s56, v51
	s_nop 1
	v_cndmask_b32_e32 v51, v51, v52, vcc
	v_sqrt_f32_e32 v52, v51
	s_nop 0
	v_add_u32_e32 v53, -1, v52
	v_fma_f32 v54, -v53, v52, v51
	v_cmp_ge_f32_e64 s[8:9], 0, v54
	v_add_u32_e32 v54, 1, v52
	s_nop 0
	v_cndmask_b32_e64 v53, v52, v53, s[8:9]
	v_fma_f32 v52, -v54, v52, v51
	v_cmp_lt_f32_e64 s[8:9], 0, v52
	s_nop 1
	v_cndmask_b32_e64 v52, v53, v54, s[8:9]
	v_mul_f32_e32 v53, 0x37800000, v52
	v_cndmask_b32_e32 v52, v52, v53, vcc
	v_cmp_class_f32_e32 vcc, v51, v69
	s_nop 1
	v_cndmask_b32_e32 v51, v52, v51, vcc
	v_div_scale_f32 v52, s[8:9], v51, v51, 1.0
	v_rcp_f32_e32 v53, v52
	s_nop 0
	v_fma_f32 v54, -v52, v53, 1.0
	v_fmac_f32_e32 v53, v54, v53
	v_div_scale_f32 v54, vcc, 1.0, v51, 1.0
	v_mul_f32_e32 v55, v54, v53
	v_fma_f32 v56, -v52, v55, v54
	v_fmac_f32_e32 v55, v56, v53
	v_fma_f32 v52, -v52, v55, v54
	v_div_fmas_f32 v52, v52, v53, v55
	v_div_fixup_f32 v51, v52, v51, 1.0
	v_mov_b32_e32 v52, s37
	ds_write_b64 v52, v[50:51]
.LBB0_266:
	s_or_b64 exec, exec, s[34:35]
	v_lshlrev_b32_e32 v50, 16, v44
	v_and_b32_e32 v44, 0xffff0000, v44
	s_waitcnt lgkmcnt(1)
	v_lshlrev_b32_e32 v51, 16, v45
	v_and_b32_e32 v45, 0xffff0000, v45
	v_add_f32_e32 v54, v50, v44
	v_add_f32_e32 v55, v51, v45
	v_mul_f32_e32 v44, v44, v44
	v_mul_f32_e32 v45, v45, v45
	v_lshlrev_b32_e32 v52, 16, v46
	v_and_b32_e32 v46, 0xffff0000, v46
	s_waitcnt lgkmcnt(0)
	v_lshlrev_b32_e32 v53, 16, v47
	v_and_b32_e32 v47, 0xffff0000, v47
	v_fmac_f32_e32 v44, v50, v50
	v_fmac_f32_e32 v45, v51, v51
	v_add_f32_e32 v54, v54, v55
	v_add_f32_e32 v55, v52, v46
	v_add_f32_e32 v44, v44, v45
	v_mul_f32_e32 v45, v46, v46
	v_mul_f32_e32 v46, v47, v47
	v_fmac_f32_e32 v45, v52, v52
	v_fmac_f32_e32 v46, v53, v53
	v_add_f32_e32 v45, v45, v46
	v_add_f32_e32 v44, v44, v45
	v_lshlrev_b32_e32 v45, 16, v40
	v_and_b32_e32 v40, 0xffff0000, v40
	v_lshlrev_b32_e32 v46, 16, v41
	v_and_b32_e32 v41, 0xffff0000, v41
	v_add_f32_e32 v51, v45, v40
	v_add_f32_e32 v52, v46, v41
	v_mul_f32_e32 v40, v40, v40
	v_mul_f32_e32 v41, v41, v41
	v_add_f32_e32 v56, v53, v47
	v_lshlrev_b32_e32 v47, 16, v42
	v_and_b32_e32 v42, 0xffff0000, v42
	v_lshlrev_b32_e32 v50, 16, v43
	v_and_b32_e32 v43, 0xffff0000, v43
	v_fmac_f32_e32 v40, v45, v45
	v_fmac_f32_e32 v41, v46, v46
	v_add_f32_e32 v51, v51, v52
	v_add_f32_e32 v52, v47, v42
	v_add_f32_e32 v40, v40, v41
	v_mul_f32_e32 v41, v42, v42
	v_mul_f32_e32 v42, v43, v43
	v_fmac_f32_e32 v41, v47, v47
	v_fmac_f32_e32 v42, v50, v50
	v_add_f32_e32 v41, v41, v42
	v_add_f32_e32 v40, v40, v41
	v_lshlrev_b32_e32 v41, 16, v36
	v_and_b32_e32 v36, 0xffff0000, v36
	v_lshlrev_b32_e32 v42, 16, v37
	v_and_b32_e32 v37, 0xffff0000, v37
	v_add_f32_e32 v45, v41, v36
	v_add_f32_e32 v46, v42, v37
	v_mul_f32_e32 v36, v36, v36
	v_mul_f32_e32 v37, v37, v37
	v_add_f32_e32 v53, v50, v43
	v_add_f32_e32 v40, v44, v40
	v_lshlrev_b32_e32 v43, 16, v38
	v_and_b32_e32 v38, 0xffff0000, v38
	v_lshlrev_b32_e32 v44, 16, v39
	v_and_b32_e32 v39, 0xffff0000, v39
	v_fmac_f32_e32 v36, v41, v41
	v_fmac_f32_e32 v37, v42, v42
	v_add_f32_e32 v45, v45, v46
	v_add_f32_e32 v46, v43, v38
	v_add_f32_e32 v36, v36, v37
	v_mul_f32_e32 v37, v38, v38
	v_mul_f32_e32 v38, v39, v39
	v_fmac_f32_e32 v37, v43, v43
	v_fmac_f32_e32 v38, v44, v44
	v_add_f32_e32 v37, v37, v38
	v_add_f32_e32 v36, v36, v37
	v_lshlrev_b32_e32 v37, 16, v32
	v_and_b32_e32 v32, 0xffff0000, v32
	v_lshlrev_b32_e32 v38, 16, v33
	v_and_b32_e32 v33, 0xffff0000, v33
	v_add_f32_e32 v41, v37, v32
	v_add_f32_e32 v42, v38, v33
	v_mul_f32_e32 v32, v32, v32
	v_mul_f32_e32 v33, v33, v33
	v_add_f32_e32 v55, v55, v56
	v_add_f32_e32 v47, v44, v39
	v_add_f32_e32 v36, v40, v36
	v_lshlrev_b32_e32 v39, 16, v34
	v_and_b32_e32 v34, 0xffff0000, v34
	v_lshlrev_b32_e32 v40, 16, v35
	v_and_b32_e32 v35, 0xffff0000, v35
	v_fmac_f32_e32 v32, v37, v37
	v_fmac_f32_e32 v33, v38, v38
	v_add_f32_e32 v54, v54, v55
	v_add_f32_e32 v52, v52, v53
	v_add_f32_e32 v41, v41, v42
	v_add_f32_e32 v42, v39, v34
	v_add_f32_e32 v32, v32, v33
	v_mul_f32_e32 v33, v34, v34
	v_mul_f32_e32 v34, v35, v35
	v_add_f32_e32 v54, 0, v54
	v_add_f32_e32 v51, v51, v52
	v_add_f32_e32 v46, v46, v47
	v_add_f32_e32 v43, v40, v35
	v_fmac_f32_e32 v33, v39, v39
	v_fmac_f32_e32 v34, v40, v40
	v_add_f32_e32 v51, v54, v51
	v_add_f32_e32 v45, v45, v46
	v_add_f32_e32 v42, v42, v43
	v_add_f32_e32 v33, v33, v34
	v_add_f32_e32 v45, v51, v45
	v_add_f32_e32 v41, v41, v42
	v_add_f32_e32 v32, v32, v33
	v_add_f32_e32 v41, v45, v41
	v_add_f32_e32 v32, v36, v32
	s_nop 0
	s_nop 0
	s_waitcnt lgkmcnt(1)
	s_nop 1
	v_add_f32_dpp v33, v41, v41 quad_perm:[1,0,3,2] row_mask:0xf bank_mask:0xf
	s_waitcnt lgkmcnt(0)
	s_nop 1
	v_add_f32_dpp v32, v32, v32 quad_perm:[1,0,3,2] row_mask:0xf bank_mask:0xf
	s_nop 0
	s_nop 0
	s_waitcnt lgkmcnt(1)
	s_nop 1
	v_add_f32_dpp v33, v33, v33 quad_perm:[2,3,0,1] row_mask:0xf bank_mask:0xf
	s_waitcnt lgkmcnt(0)
	s_nop 1
	v_add_f32_dpp v32, v32, v32 quad_perm:[2,3,0,1] row_mask:0xf bank_mask:0xf
	s_nop 0
	s_nop 0
	s_waitcnt lgkmcnt(1)
	s_nop 1
	v_add_f32_dpp v33, v33, v33 row_half_mirror row_mask:0xf bank_mask:0xf
	s_waitcnt lgkmcnt(0)
	s_nop 1
	v_add_f32_dpp v32, v32, v32 row_half_mirror row_mask:0xf bank_mask:0xf
	s_nop 0
	s_nop 0
	s_waitcnt lgkmcnt(1)
	s_nop 1
	v_add_f32_dpp v33, v33, v33 row_mirror row_mask:0xf bank_mask:0xf
	s_waitcnt lgkmcnt(0)
	s_nop 1
	v_add_f32_dpp v34, v32, v32 row_mirror row_mask:0xf bank_mask:0xf
	v_mov_b32_e32 v35, v33
	v_mov_b32_e32 v36, v34
	s_waitcnt lgkmcnt(1)
	s_nop 1
	v_permlane16_swap_b32_e32 v33, v35
	v_add_f32_e32 v32, v33, v35
	s_waitcnt lgkmcnt(0)
	s_nop 1
	v_permlane16_swap_b32_e32 v34, v36
	v_add_f32_e32 v34, v34, v36
	ds_bpermute_b32 v33, v110, v32
	ds_bpermute_b32 v35, v110, v34
	s_and_saveexec_b64 s[34:35], s[6:7]
	s_cbranch_execz .LBB0_268
; __device__ __forceinline__ float bf_lo(unsigned w) { return __uint_as_float(w << 16); }
; __device__ __forceinline__ float bf_hi(unsigned w) { return __uint_as_float(w & 0xffff0000u); }
; __device__ __forceinline__ void sgu_phase(LAS unsigned char* lds, const bf16* __restrict__ U, const bf16* __restrict__ V, bf16* __restrict__ Y, const bf16* __restrict__ Wm, ...
;     ...
;             for (int q = 0; q < 4; ++q) { const int rl = wave * 16 + rb + q; float s = 0.f, qq = 0.f;
; #pragma unroll
;                 for (int j = 0; j < 4; ++j) { const u32x4 w = sw[q][j];
;                     const float x0 = bf_lo(w.x), x1 = bf_hi(w.x), x2 = bf_lo(w.y), x3 = bf_hi(w.y), x4 = bf_lo(w.z), x5 = bf_hi(w.z), x6 = bf_lo(w.w), x7 = bf_hi(w.w);
;                     s += ((x0 + x1) + (x2 + x3)) + ((x4 + x5) + (x6 + x7)); qq += ((x0 * x0 + x1 * x1) + (x2 * x2 + x3 * x3)) + ((x4 * x4 + x5 * x5) + (x6 * x6 + x7 * x7)); }
;                 s = wave_sum(s); qq = wave_sum(qq); const float mean = s * (1.0f / DM); const float var = fmaxf(qq * (1.0f / DM) - mean * mean, 0.f);
;                 if (lane == 0) { st[2 * rl] = mean; st[2 * rl + 1] = 1.0f / sqrtf(var + EPS); } } }
	s_waitcnt lgkmcnt(1)
	v_add_f32_e32 v32, v32, v33
	v_mul_f32_e32 v32, 0x3a000000, v32
	s_waitcnt lgkmcnt(0)
	v_add_f32_e32 v34, v34, v35
	v_mul_f32_e32 v33, v32, v32
	v_fma_f32 v33, v34, s55, -v33
	v_max_f32_e32 v33, 0, v33
	v_add_f32_e32 v33, 0x358637bd, v33
	v_mul_f32_e32 v34, 0x4f800000, v33
	v_cmp_gt_f32_e32 vcc, s56, v33
	s_nop 1
	v_cndmask_b32_e32 v33, v33, v34, vcc
	v_sqrt_f32_e32 v34, v33
	s_nop 0
	v_add_u32_e32 v35, -1, v34
	v_fma_f32 v36, -v35, v34, v33
	v_cmp_ge_f32_e64 s[8:9], 0, v36
	v_add_u32_e32 v36, 1, v34
	s_nop 0
	v_cndmask_b32_e64 v35, v34, v35, s[8:9]
	v_fma_f32 v34, -v36, v34, v33
	v_cmp_lt_f32_e64 s[8:9], 0, v34
	s_nop 1
	v_cndmask_b32_e64 v34, v35, v36, s[8:9]
	v_mul_f32_e32 v35, 0x37800000, v34
	v_cndmask_b32_e32 v34, v34, v35, vcc
	v_cmp_class_f32_e32 vcc, v33, v69
	s_nop 1
	v_cndmask_b32_e32 v33, v34, v33, vcc
	v_div_scale_f32 v34, s[8:9], v33, v33, 1.0
	v_rcp_f32_e32 v35, v34
	s_nop 0
	v_fma_f32 v36, -v34, v35, 1.0
	v_fmac_f32_e32 v35, v36, v35
	v_div_scale_f32 v36, vcc, 1.0, v33, 1.0
	v_mul_f32_e32 v37, v36, v35
	v_fma_f32 v38, -v34, v37, v36
	v_fmac_f32_e32 v37, v38, v35
	v_fma_f32 v34, -v34, v37, v36
	v_div_fmas_f32 v34, v34, v35, v37
	v_div_fixup_f32 v33, v34, v33, 1.0
	v_mov_b32_e32 v34, s37
	ds_write_b64 v34, v[32:33] offset:8
.LBB0_268:
	s_or_b64 exec, exec, s[34:35]
	v_lshlrev_b32_e32 v32, 16, v28
	v_and_b32_e32 v28, 0xffff0000, v28
	s_waitcnt lgkmcnt(1)
	v_lshlrev_b32_e32 v33, 16, v29
	v_and_b32_e32 v29, 0xffff0000, v29
	v_add_f32_e32 v36, v32, v28
	v_add_f32_e32 v37, v33, v29
	v_mul_f32_e32 v28, v28, v28
	v_mul_f32_e32 v29, v29, v29
	v_lshlrev_b32_e32 v34, 16, v30
	v_and_b32_e32 v30, 0xffff0000, v30
	s_waitcnt lgkmcnt(0)
	v_lshlrev_b32_e32 v35, 16, v31
	v_and_b32_e32 v31, 0xffff0000, v31
	v_fmac_f32_e32 v28, v32, v32
	v_fmac_f32_e32 v29, v33, v33
	v_add_f32_e32 v36, v36, v37
	v_add_f32_e32 v37, v34, v30
	v_add_f32_e32 v28, v28, v29
	v_mul_f32_e32 v29, v30, v30
	v_mul_f32_e32 v30, v31, v31
	v_fmac_f32_e32 v29, v34, v34
	v_fmac_f32_e32 v30, v35, v35
	v_add_f32_e32 v29, v29, v30
	v_add_f32_e32 v28, v28, v29
	v_lshlrev_b32_e32 v29, 16, v24
	v_and_b32_e32 v24, 0xffff0000, v24
	v_lshlrev_b32_e32 v30, 16, v25
	v_and_b32_e32 v25, 0xffff0000, v25
	v_add_f32_e32 v33, v29, v24
	v_add_f32_e32 v34, v30, v25
	v_mul_f32_e32 v24, v24, v24
	v_mul_f32_e32 v25, v25, v25
	v_add_f32_e32 v38, v35, v31
	v_lshlrev_b32_e32 v31, 16, v26
	v_and_b32_e32 v26, 0xffff0000, v26
	v_lshlrev_b32_e32 v32, 16, v27
	v_and_b32_e32 v27, 0xffff0000, v27
	v_fmac_f32_e32 v24, v29, v29
	v_fmac_f32_e32 v25, v30, v30
	v_add_f32_e32 v33, v33, v34
	v_add_f32_e32 v34, v31, v26
	v_add_f32_e32 v24, v24, v25
	v_mul_f32_e32 v25, v26, v26
	v_mul_f32_e32 v26, v27, v27
	v_fmac_f32_e32 v25, v31, v31
	v_fmac_f32_e32 v26, v32, v32
	v_add_f32_e32 v25, v25, v26
	v_add_f32_e32 v24, v24, v25
	v_lshlrev_b32_e32 v25, 16, v20
	v_and_b32_e32 v20, 0xffff0000, v20
	v_lshlrev_b32_e32 v26, 16, v21
	v_and_b32_e32 v21, 0xffff0000, v21
	v_add_f32_e32 v29, v25, v20
	v_add_f32_e32 v30, v26, v21
	v_mul_f32_e32 v20, v20, v20
	v_mul_f32_e32 v21, v21, v21
	v_add_f32_e32 v35, v32, v27
	v_add_f32_e32 v24, v28, v24
	v_lshlrev_b32_e32 v27, 16, v22
	v_and_b32_e32 v22, 0xffff0000, v22
	v_lshlrev_b32_e32 v28, 16, v23
	v_and_b32_e32 v23, 0xffff0000, v23
	v_fmac_f32_e32 v20, v25, v25
	v_fmac_f32_e32 v21, v26, v26
	v_add_f32_e32 v29, v29, v30
	v_add_f32_e32 v30, v27, v22
	v_add_f32_e32 v20, v20, v21
	v_mul_f32_e32 v21, v22, v22
	v_mul_f32_e32 v22, v23, v23
	v_fmac_f32_e32 v21, v27, v27
	v_fmac_f32_e32 v22, v28, v28
	v_add_f32_e32 v21, v21, v22
	v_add_f32_e32 v20, v20, v21
	v_lshlrev_b32_e32 v21, 16, v16
	v_and_b32_e32 v16, 0xffff0000, v16
	v_lshlrev_b32_e32 v22, 16, v17
	v_and_b32_e32 v17, 0xffff0000, v17
	v_add_f32_e32 v25, v21, v16
	v_add_f32_e32 v26, v22, v17
	v_mul_f32_e32 v16, v16, v16
	v_mul_f32_e32 v17, v17, v17
	v_add_f32_e32 v37, v37, v38
	v_add_f32_e32 v31, v28, v23
	v_add_f32_e32 v20, v24, v20
	v_lshlrev_b32_e32 v23, 16, v18
	v_and_b32_e32 v18, 0xffff0000, v18
	v_lshlrev_b32_e32 v24, 16, v19
	v_and_b32_e32 v19, 0xffff0000, v19
	v_fmac_f32_e32 v16, v21, v21
	v_fmac_f32_e32 v17, v22, v22
	v_add_f32_e32 v36, v36, v37
	v_add_f32_e32 v34, v34, v35
	v_add_f32_e32 v25, v25, v26
	v_add_f32_e32 v26, v23, v18
	v_add_f32_e32 v16, v16, v17
	v_mul_f32_e32 v17, v18, v18
	v_mul_f32_e32 v18, v19, v19
	v_add_f32_e32 v36, 0, v36
	v_add_f32_e32 v33, v33, v34
	v_add_f32_e32 v30, v30, v31
	v_add_f32_e32 v27, v24, v19
	v_fmac_f32_e32 v17, v23, v23
	v_fmac_f32_e32 v18, v24, v24
	v_add_f32_e32 v33, v36, v33
	v_add_f32_e32 v29, v29, v30
	v_add_f32_e32 v26, v26, v27
	v_add_f32_e32 v17, v17, v18
	v_add_f32_e32 v29, v33, v29
	v_add_f32_e32 v25, v25, v26
	v_add_f32_e32 v16, v16, v17
	v_add_f32_e32 v25, v29, v25
	v_add_f32_e32 v16, v20, v16
	s_nop 0
	s_nop 0
	s_waitcnt lgkmcnt(1)
	s_nop 1
	v_add_f32_dpp v17, v25, v25 quad_perm:[1,0,3,2] row_mask:0xf bank_mask:0xf
	s_waitcnt lgkmcnt(0)
	s_nop 1
	v_add_f32_dpp v16, v16, v16 quad_perm:[1,0,3,2] row_mask:0xf bank_mask:0xf
	s_nop 0
	s_nop 0
	s_waitcnt lgkmcnt(1)
	s_nop 1
	v_add_f32_dpp v17, v17, v17 quad_perm:[2,3,0,1] row_mask:0xf bank_mask:0xf
	s_waitcnt lgkmcnt(0)
	s_nop 1
	v_add_f32_dpp v16, v16, v16 quad_perm:[2,3,0,1] row_mask:0xf bank_mask:0xf
	s_nop 0
	s_nop 0
	s_waitcnt lgkmcnt(1)
	s_nop 1
	v_add_f32_dpp v17, v17, v17 row_half_mirror row_mask:0xf bank_mask:0xf
	s_waitcnt lgkmcnt(0)
	s_nop 1
	v_add_f32_dpp v16, v16, v16 row_half_mirror row_mask:0xf bank_mask:0xf
	s_nop 0
	s_nop 0
	s_waitcnt lgkmcnt(1)
	s_nop 1
	v_add_f32_dpp v17, v17, v17 row_mirror row_mask:0xf bank_mask:0xf
	s_waitcnt lgkmcnt(0)
	s_nop 1
	v_add_f32_dpp v18, v16, v16 row_mirror row_mask:0xf bank_mask:0xf
	v_mov_b32_e32 v19, v17
	v_mov_b32_e32 v20, v18
	s_waitcnt lgkmcnt(1)
	s_nop 1
	v_permlane16_swap_b32_e32 v17, v19
	v_add_f32_e32 v16, v17, v19
	s_waitcnt lgkmcnt(0)
	s_nop 1
	v_permlane16_swap_b32_e32 v18, v20
	v_add_f32_e32 v18, v18, v20
	ds_bpermute_b32 v17, v110, v16
	ds_bpermute_b32 v19, v110, v18
	s_and_saveexec_b64 s[34:35], s[6:7]
	s_cbranch_execz .LBB0_270
; __device__ __forceinline__ void sgu_phase(LAS unsigned char* lds, const bf16* __restrict__ U, const bf16* __restrict__ V, bf16* __restrict__ Y, const bf16* __restrict__ Wm, ...
;     ...
;                 s = wave_sum(s); qq = wave_sum(qq); const float mean = s * (1.0f / DM); const float var = fmaxf(qq * (1.0f / DM) - mean * mean, 0.f);
;                 if (lane == 0) { st[2 * rl] = mean; st[2 * rl + 1] = 1.0f / sqrtf(var + EPS); } } }
	s_waitcnt lgkmcnt(1)
	v_add_f32_e32 v16, v16, v17
	v_mul_f32_e32 v16, 0x3a000000, v16
	s_waitcnt lgkmcnt(0)
	v_add_f32_e32 v18, v18, v19
	v_mul_f32_e32 v17, v16, v16
	v_fma_f32 v17, v18, s55, -v17
	v_max_f32_e32 v17, 0, v17
	v_add_f32_e32 v17, 0x358637bd, v17
	v_mul_f32_e32 v18, 0x4f800000, v17
	v_cmp_gt_f32_e32 vcc, s56, v17
	s_nop 1
	v_cndmask_b32_e32 v17, v17, v18, vcc
	v_sqrt_f32_e32 v18, v17
	s_nop 0
	v_add_u32_e32 v19, -1, v18
	v_fma_f32 v20, -v19, v18, v17
	v_cmp_ge_f32_e64 s[8:9], 0, v20
	v_add_u32_e32 v20, 1, v18
	s_nop 0
	v_cndmask_b32_e64 v19, v18, v19, s[8:9]
	v_fma_f32 v18, -v20, v18, v17
	v_cmp_lt_f32_e64 s[8:9], 0, v18
	s_nop 1
	v_cndmask_b32_e64 v18, v19, v20, s[8:9]
	v_mul_f32_e32 v19, 0x37800000, v18
	v_cndmask_b32_e32 v18, v18, v19, vcc
	v_cmp_class_f32_e32 vcc, v17, v69
	s_nop 1
	v_cndmask_b32_e32 v17, v18, v17, vcc
	v_div_scale_f32 v18, s[8:9], v17, v17, 1.0
	v_rcp_f32_e32 v19, v18
	s_nop 0
	v_fma_f32 v20, -v18, v19, 1.0
	v_fmac_f32_e32 v19, v20, v19
	v_div_scale_f32 v20, vcc, 1.0, v17, 1.0
	v_mul_f32_e32 v21, v20, v19
	v_fma_f32 v22, -v18, v21, v20
	v_fmac_f32_e32 v21, v22, v19
	v_fma_f32 v18, -v18, v21, v20
	v_div_fmas_f32 v18, v18, v19, v21
	v_div_fixup_f32 v17, v18, v17, 1.0
	v_mov_b32_e32 v18, s37
	ds_write_b64 v18, v[16:17] offset:16
; __device__ __forceinline__ float bf_lo(unsigned w) { return __uint_as_float(w << 16); }
; __device__ __forceinline__ float bf_hi(unsigned w) { return __uint_as_float(w & 0xffff0000u); }
; __device__ __forceinline__ void sgu_phase(LAS unsigned char* lds, const bf16* __restrict__ U, const bf16* __restrict__ V, bf16* __restrict__ Y, const bf16* __restrict__ Wm, ...
;     ...
;             for (int q = 0; q < 4; ++q) { const int rl = wave * 16 + rb + q; float s = 0.f, qq = 0.f;
; #pragma unroll
;                 for (int j = 0; j < 4; ++j) { const u32x4 w = sw[q][j];
;                     const float x0 = bf_lo(w.x), x1 = bf_hi(w.x), x2 = bf_lo(w.y), x3 = bf_hi(w.y), x4 = bf_lo(w.z), x5 = bf_hi(w.z), x6 = bf_lo(w.w), x7 = bf_hi(w.w);
;                     s += ((x0 + x1) + (x2 + x3)) + ((x4 + x5) + (x6 + x7)); qq += ((x0 * x0 + x1 * x1) + (x2 * x2 + x3 * x3)) + ((x4 * x4 + x5 * x5) + (x6 * x6 + x7 * x7)); }
;                 s = wave_sum(s); qq = wave_sum(qq); const float mean = s * (1.0f / DM); const float var = fmaxf(qq * (1.0f / DM) - mean * mean, 0.f);
;                 if (lane == 0) { st[2 * rl] = mean; st[2 * rl + 1] = 1.0f / sqrtf(var + EPS); } } }
.LBB0_270:
	s_or_b64 exec, exec, s[34:35]
	v_lshlrev_b32_e32 v16, 16, v12
	v_and_b32_e32 v12, 0xffff0000, v12
	s_waitcnt lgkmcnt(1)
	v_lshlrev_b32_e32 v17, 16, v13
	v_and_b32_e32 v13, 0xffff0000, v13
	v_add_f32_e32 v20, v16, v12
	v_add_f32_e32 v21, v17, v13
	v_mul_f32_e32 v12, v12, v12
	v_mul_f32_e32 v13, v13, v13
	v_lshlrev_b32_e32 v18, 16, v14
	v_and_b32_e32 v14, 0xffff0000, v14
	s_waitcnt lgkmcnt(0)
	v_lshlrev_b32_e32 v19, 16, v15
	v_and_b32_e32 v15, 0xffff0000, v15
	v_fmac_f32_e32 v12, v16, v16
	v_fmac_f32_e32 v13, v17, v17
	v_add_f32_e32 v20, v20, v21
	v_add_f32_e32 v21, v18, v14
	v_add_f32_e32 v12, v12, v13
	v_mul_f32_e32 v13, v14, v14
	v_mul_f32_e32 v14, v15, v15
	v_fmac_f32_e32 v13, v18, v18
	v_fmac_f32_e32 v14, v19, v19
	v_add_f32_e32 v13, v13, v14
	v_add_f32_e32 v12, v12, v13
	v_lshlrev_b32_e32 v13, 16, v8
	v_and_b32_e32 v8, 0xffff0000, v8
	v_lshlrev_b32_e32 v14, 16, v9
	v_and_b32_e32 v9, 0xffff0000, v9
	v_add_f32_e32 v17, v13, v8
	v_add_f32_e32 v18, v14, v9
	v_mul_f32_e32 v8, v8, v8
	v_mul_f32_e32 v9, v9, v9
	v_add_f32_e32 v22, v19, v15
	v_lshlrev_b32_e32 v15, 16, v10
	v_and_b32_e32 v10, 0xffff0000, v10
	v_lshlrev_b32_e32 v16, 16, v11
	v_and_b32_e32 v11, 0xffff0000, v11
	v_fmac_f32_e32 v8, v13, v13
	v_fmac_f32_e32 v9, v14, v14
	v_add_f32_e32 v17, v17, v18
	v_add_f32_e32 v18, v15, v10
	v_add_f32_e32 v8, v8, v9
	v_mul_f32_e32 v9, v10, v10
	v_mul_f32_e32 v10, v11, v11
	v_fmac_f32_e32 v9, v15, v15
	v_fmac_f32_e32 v10, v16, v16
	v_add_f32_e32 v9, v9, v10
	v_add_f32_e32 v8, v8, v9
	v_lshlrev_b32_e32 v9, 16, v4
	v_and_b32_e32 v4, 0xffff0000, v4
	v_lshlrev_b32_e32 v10, 16, v5
	v_and_b32_e32 v5, 0xffff0000, v5
	v_add_f32_e32 v13, v9, v4
	v_add_f32_e32 v14, v10, v5
	v_mul_f32_e32 v4, v4, v4
	v_mul_f32_e32 v5, v5, v5
	v_add_f32_e32 v19, v16, v11
	v_add_f32_e32 v8, v12, v8
	v_lshlrev_b32_e32 v11, 16, v6
	v_and_b32_e32 v6, 0xffff0000, v6
	v_lshlrev_b32_e32 v12, 16, v7
	v_and_b32_e32 v7, 0xffff0000, v7
	v_fmac_f32_e32 v4, v9, v9
	v_fmac_f32_e32 v5, v10, v10
	v_add_f32_e32 v13, v13, v14
	v_add_f32_e32 v14, v11, v6
	v_add_f32_e32 v4, v4, v5
	v_mul_f32_e32 v5, v6, v6
	v_mul_f32_e32 v6, v7, v7
	v_fmac_f32_e32 v5, v11, v11
	v_fmac_f32_e32 v6, v12, v12
	v_add_f32_e32 v5, v5, v6
	v_add_f32_e32 v4, v4, v5
	v_lshlrev_b32_e32 v5, 16, v0
	v_and_b32_e32 v0, 0xffff0000, v0
	v_lshlrev_b32_e32 v6, 16, v1
	v_and_b32_e32 v1, 0xffff0000, v1
	v_add_f32_e32 v9, v5, v0
	v_add_f32_e32 v10, v6, v1
	v_mul_f32_e32 v0, v0, v0
	v_mul_f32_e32 v1, v1, v1
	v_add_f32_e32 v21, v21, v22
	v_add_f32_e32 v15, v12, v7
	v_add_f32_e32 v4, v8, v4
	v_lshlrev_b32_e32 v7, 16, v2
	v_and_b32_e32 v2, 0xffff0000, v2
	v_lshlrev_b32_e32 v8, 16, v3
	v_and_b32_e32 v3, 0xffff0000, v3
	v_fmac_f32_e32 v0, v5, v5
	v_fmac_f32_e32 v1, v6, v6
	v_add_f32_e32 v20, v20, v21
	v_add_f32_e32 v18, v18, v19
	v_add_f32_e32 v9, v9, v10
	v_add_f32_e32 v10, v7, v2
	v_add_f32_e32 v0, v0, v1
	v_mul_f32_e32 v1, v2, v2
	v_mul_f32_e32 v2, v3, v3
	v_add_f32_e32 v20, 0, v20
	v_add_f32_e32 v17, v17, v18
	v_add_f32_e32 v14, v14, v15
	v_add_f32_e32 v11, v8, v3
	v_fmac_f32_e32 v1, v7, v7
	v_fmac_f32_e32 v2, v8, v8
	v_add_f32_e32 v17, v20, v17
	v_add_f32_e32 v13, v13, v14
	v_add_f32_e32 v10, v10, v11
	v_add_f32_e32 v1, v1, v2
	v_add_f32_e32 v13, v17, v13
	v_add_f32_e32 v9, v9, v10
	v_add_f32_e32 v0, v0, v1
	v_add_f32_e32 v9, v13, v9
	v_add_f32_e32 v0, v4, v0
	s_nop 0
	s_nop 0
	s_waitcnt lgkmcnt(1)
	s_nop 1
	v_add_f32_dpp v1, v9, v9 quad_perm:[1,0,3,2] row_mask:0xf bank_mask:0xf
	s_waitcnt lgkmcnt(0)
	s_nop 1
	v_add_f32_dpp v0, v0, v0 quad_perm:[1,0,3,2] row_mask:0xf bank_mask:0xf
	s_nop 0
	s_nop 0
	s_waitcnt lgkmcnt(1)
	s_nop 1
	v_add_f32_dpp v1, v1, v1 quad_perm:[2,3,0,1] row_mask:0xf bank_mask:0xf
	s_waitcnt lgkmcnt(0)
	s_nop 1
	v_add_f32_dpp v0, v0, v0 quad_perm:[2,3,0,1] row_mask:0xf bank_mask:0xf
	s_nop 0
	s_nop 0
	s_waitcnt lgkmcnt(1)
	s_nop 1
	v_add_f32_dpp v1, v1, v1 row_half_mirror row_mask:0xf bank_mask:0xf
	s_waitcnt lgkmcnt(0)
	s_nop 1
	v_add_f32_dpp v0, v0, v0 row_half_mirror row_mask:0xf bank_mask:0xf
	s_nop 0
	s_nop 0
	s_waitcnt lgkmcnt(1)
	s_nop 1
	v_add_f32_dpp v1, v1, v1 row_mirror row_mask:0xf bank_mask:0xf
	s_waitcnt lgkmcnt(0)
	s_nop 1
	v_add_f32_dpp v2, v0, v0 row_mirror row_mask:0xf bank_mask:0xf
	v_mov_b32_e32 v3, v1
	v_mov_b32_e32 v4, v2
	s_waitcnt lgkmcnt(1)
	s_nop 1
	v_permlane16_swap_b32_e32 v1, v3
	v_add_f32_e32 v0, v1, v3
	s_waitcnt lgkmcnt(0)
	s_nop 1
	v_permlane16_swap_b32_e32 v2, v4
	v_add_f32_e32 v2, v2, v4
	ds_bpermute_b32 v1, v110, v0
	ds_bpermute_b32 v3, v110, v2
	s_and_saveexec_b64 s[34:35], s[6:7]
	s_cbranch_execz .LBB0_263
	s_waitcnt lgkmcnt(1)
	v_add_f32_e32 v0, v0, v1
	v_mul_f32_e32 v0, 0x3a000000, v0
	s_waitcnt lgkmcnt(0)
	v_add_f32_e32 v2, v2, v3
	v_mul_f32_e32 v1, v0, v0
	v_fma_f32 v1, v2, s55, -v1
	v_max_f32_e32 v1, 0, v1
	v_add_f32_e32 v1, 0x358637bd, v1
	v_mul_f32_e32 v2, 0x4f800000, v1
	v_cmp_gt_f32_e32 vcc, s56, v1
	s_nop 1
	v_cndmask_b32_e32 v1, v1, v2, vcc
	v_sqrt_f32_e32 v2, v1
	s_nop 0
	v_add_u32_e32 v3, -1, v2
	v_fma_f32 v4, -v3, v2, v1
	v_cmp_ge_f32_e64 s[8:9], 0, v4
	v_add_u32_e32 v4, 1, v2
	s_nop 0
	v_cndmask_b32_e64 v3, v2, v3, s[8:9]
	v_fma_f32 v2, -v4, v2, v1
	v_cmp_lt_f32_e64 s[8:9], 0, v2
	s_nop 1
	v_cndmask_b32_e64 v2, v3, v4, s[8:9]
	v_mul_f32_e32 v3, 0x37800000, v2
	v_cndmask_b32_e32 v2, v2, v3, vcc
	v_cmp_class_f32_e32 vcc, v1, v69
	s_nop 1
	v_cndmask_b32_e32 v1, v2, v1, vcc
	v_div_scale_f32 v2, s[8:9], v1, v1, 1.0
	v_rcp_f32_e32 v3, v2
	s_nop 0
	v_fma_f32 v4, -v2, v3, 1.0
	v_fmac_f32_e32 v3, v4, v3
	v_div_scale_f32 v4, vcc, 1.0, v1, 1.0
	v_mul_f32_e32 v5, v4, v3
	v_fma_f32 v6, -v2, v5, v4
	v_fmac_f32_e32 v5, v6, v3
	v_fma_f32 v2, -v2, v5, v4
	v_div_fmas_f32 v2, v2, v3, v5
	v_div_fixup_f32 v1, v2, v1, 1.0
	v_mov_b32_e32 v2, s37
	ds_write_b64 v2, v[0:1] offset:24
	s_branch .LBB0_263

; #define PG8_STAGE(bufoff, gbase, voff) do { _Pragma("unroll") for (int _i = 0; _i < 2; ++_i) \
;         __builtin_amdgcn_global_load_lds((const unsigned*)((const char*)(gbase) + (voff)[_i]), (PG8_LAS unsigned*)(lds + (bufoff) + ldsw + _i * 8192), 16, 0, 0); } while (0)
; #define PG8_WAIT_V(n) asm volatile("s_waitcnt vmcnt(" #n ")" ::: "memory")
; #define PG8_BAR __builtin_amdgcn_s_barrier()
; template <class Epi, class Sched, bool ALIGN_EPI = false, bool SP2 = false>
; __device__ __forceinline__ void gemm_phase(PG8_LAS unsigned char* lds, const Gemm g, const Sched& S, const Epi& E) {
;     ...
;     if constexpr (SP2) {
;         PG8_STAGE(PG8_SB(0, 0), cB, voffB); PG8_STAGE(PG8_SB(0, 1), cB + hstep, voffB); PG8_STAGE(PG8_SA(0, 0), cA, voffA); PG8_STAGE(PG8_SA(0, 1), cA + hstep, voffA);
;         if (wr == 1) PG8_BAR;
;         PG8_WAIT_V(2); PG8_BAR;
;         PG8_STAGE(PG8_SB(1, 0), cB + kstep, voffB); PG8_STAGE(PG8_SA(1, 0), cA + kstep, voffA); PG8_STAGE(PG8_SB(1, 1), cB + hstep + kstep, voffB);
;         PG8_WAIT_V(6); PG8_BAR;
.LBB0_343:
	s_add_u32 s12, s6, 0x27400000
	s_addc_u32 s13, s7, 0
	s_add_u32 s66, s6, 0x104000
	s_addc_u32 s67, s7, 0
	s_lshl_b32 s6, s14, 5
	s_mov_b64 s[14:15], 0x80
	s_and_b32 s19, s6, 0x60
	s_add_i32 m0, s37, 0x18000
	v_lshl_add_u64 v[6:7], v[6:7], 0, s[14:15]
	s_lshl_b32 s18, s17, 13
	s_lshl_b32 s20, s19, 7
	global_load_lds_dwordx4 v[6:7], off
	v_lshl_add_u64 v[4:5], v[4:5], 0, s[14:15]
	s_add_i32 m0, s37, 0x1a000
	s_add_i32 s68, s37, 0x8000
	s_add_i32 s69, s37, 0xa000
	global_load_lds_dwordx4 v[4:5], off
	v_lshl_add_u64 v[0:1], v[0:1], 0, s[14:15]
	s_mov_b32 m0, s68
	s_add_u32 s6, s50, 0x80080
	global_load_lds_dwordx4 v[0:1], off
	v_lshl_add_u64 v[0:1], v[2:3], 0, s[14:15]
	s_mov_b32 m0, s69
	s_addc_u32 s7, s51, 0
	global_load_lds_dwordx4 v[0:1], off
	s_add_i32 m0, s37, 0x1c000
	v_lshl_add_u64 v[0:1], s[6:7], 0, v[146:147]
	global_load_lds_dwordx4 v[0:1], off
	v_lshl_add_u64 v[0:1], s[6:7], 0, v[150:151]
	s_add_i32 m0, s37, 0x1e000
	s_cmpk_lt_u32 s16, 0x100
	global_load_lds_dwordx4 v[0:1], off
	s_waitcnt vmcnt(8)
	s_barrier
	v_lshrrev_b32_e32 v1, 1, v8
	v_and_b32_e32 v1, 24, v1
	v_and_b32_e32 v0, 15, v8
	v_lshlrev_b32_e32 v2, 1, v1
	v_lshl_or_b32 v166, s17, 6, v0
	v_lshl_or_b32 v0, v0, 6, v2
	v_lshlrev_b32_e32 v2, 2, v8
	v_and_b32_e32 v2, 32, v2
	v_bitop3_b32 v3, v0, s18, v2 bitop3:0xde
	v_bitop3_b32 v167, v0, s20, v2 bitop3:0xde
	v_lshlrev_b32_e32 v0, 15, v12
	v_and_b32_e32 v0, 0xffff0000, v0
	v_or_b32_e32 v168, s19, v1
	v_lshl_add_u32 v0, v13, 12, v0
	v_and_b32_e32 v1, 1, v12
	v_lshl_or_b32 v0, v1, 6, v0
	v_lshl_add_u32 v152, v14, 1, v0
	v_lshlrev_b32_e32 v0, 15, v9
	v_and_b32_e32 v0, 0xffff0000, v0
	s_waitcnt vmcnt(6)
	v_lshl_add_u32 v0, v10, 12, v0
	v_and_b32_e32 v1, 1, v9
	s_cselect_b64 s[16:17], -1, 0
	v_lshl_or_b32 v0, v1, 6, v0
	s_add_i32 s71, 0, 0x10000
	s_add_i32 s72, 0, 0x14000
	s_ashr_i32 s70, s3, 31
	v_mov_b32_e32 v153, v147
	v_lshl_add_u32 v154, v11, 1, v0
	v_mov_b32_e32 v155, v147
	v_mov_b64_e32 v[156:157], 0x200
	v_mov_b64_e32 v[158:159], 0x1ff
	v_add_u32_e32 v169, s71, v167
	v_add_u32_e32 v170, s72, v167
	v_add_u32_e32 v171, 0, v3
	s_mov_b64 s[18:19], 0x40000
	s_mov_b64 s[20:21], 0x48000
	s_mov_b64 s[22:23], 0x50000
	s_mov_b64 s[24:25], 0x58000
	s_barrier
	s_branch .LBB0_346

; __device__ __forceinline__ float bf_lo(unsigned w) { return __uint_as_float(w << 16); }
; __device__ __forceinline__ float bf_hi(unsigned w) { return __uint_as_float(w & 0xffff0000u); }
; template <int MODE, bool INBF> ...
;     ...
;         for (int i0 = 0; i0 < 8; i0 += RB) {
;             f32x4 v[RB][8];
; #pragma unroll
;             for (int q = 0; q < RB; ++q) { const int row = blk * 64 + wave + 8 * (i0 + q);
;                 if (INBF) { const u32x2* xr = (const u32x2*)((const bf16*)xin_ + (size_t)row * DM) + lane;
; #pragma unroll
;                     for (int j = 0; j < 8; ++j) { const u32x2 w = xr[64 * j]; v[q][j] = (f32x4){bf_lo(w.x), bf_hi(w.x), bf_lo(w.y), bf_hi(w.y)}; }
;                 } else { const f32x4* xr = (const f32x4*)((const float*)xin_ + (size_t)row * DM) + lane;
; #pragma unroll
;                     for (int j = 0; j < 8; ++j) v[q][j] = xr[64 * j]; } }
; #pragma unroll
;             for (int q = 0; q < RB; ++q) { const int row = blk * 64 + wave + 8 * (i0 + q); float ss = 0.f;
; #pragma unroll
;                 for (int j = 0; j < 8; ++j) ss += (v[q][j].x * v[q][j].x + v[q][j].y * v[q][j].y) + (v[q][j].z * v[q][j].z + v[q][j].w * v[q][j].w);
;                 const float rstd = 1.0f / sqrtf(wave_sum(ss) * (1.0f / DM) + EPS);
.LBB0_418:
	v_lshl_add_u64 v[60:61], v[58:59], 0, s[14:15]
	v_add_co_u32_e32 v86, vcc, 0x27400000, v60
	v_add_co_u32_e64 v88, s[8:9], s19, v60
	s_nop 0
	v_addc_co_u32_e32 v87, vcc, 0, v61, vcc
	ds_read_b128 v[0:3], v68
	ds_read_b128 v[4:7], v68 offset:1024
	ds_read_b128 v[12:15], v68 offset:8192
	ds_read_b128 v[8:11], v68 offset:9216
	ds_read_b128 v[16:19], v68 offset:2048
	ds_read_b128 v[20:23], v68 offset:3072
	ds_read_b128 v[28:31], v68 offset:10240
	ds_read_b128 v[24:27], v68 offset:11264
	ds_read_b128 v[32:35], v68 offset:4096
	ds_read_b128 v[36:39], v68 offset:5120
	ds_read_b128 v[44:47], v68 offset:12288
	ds_read_b128 v[40:43], v68 offset:13312
	ds_read_b128 v[48:51], v68 offset:6144
	ds_read_b128 v[74:77], v68 offset:7168
	ds_read_b128 v[78:81], v68 offset:14336
	ds_read_b128 v[82:85], v68 offset:15360
	v_addc_co_u32_e64 v89, s[8:9], 0, v61, s[8:9]
	flat_load_dwordx2 v[60:61], v[86:87] offset:1536
	flat_load_dwordx2 v[90:91], v[86:87] offset:3584
	flat_load_dwordx2 v[92:93], v[86:87]
	flat_load_dwordx2 v[94:95], v[86:87] offset:512
	flat_load_dwordx2 v[96:97], v[86:87] offset:1024
	flat_load_dwordx2 v[98:99], v[86:87] offset:2048
	flat_load_dwordx2 v[100:101], v[86:87] offset:2560
	flat_load_dwordx2 v[102:103], v[86:87] offset:3072
	s_add_u32 s14, s14, 0x8000
	s_addc_u32 s15, s15, 0
	s_cmp_lg_u32 s14, 0x40000
	s_waitcnt vmcnt(0) lgkmcnt(0)
	v_lshlrev_b32_e32 v87, 16, v60
	v_lshlrev_b32_e32 v107, 16, v90
	v_lshlrev_b32_e32 v110, 16, v92
	v_and_b32_e32 v111, 0xffff0000, v92
	v_lshlrev_b32_e32 v92, 16, v93
	v_and_b32_e32 v93, 0xffff0000, v93
	v_lshlrev_b32_e32 v113, 16, v95
	v_lshlrev_b32_e32 v112, 16, v94
	v_and_b32_e32 v95, 0xffff0000, v95
	v_and_b32_e32 v94, 0xffff0000, v94
	v_and_b32_e32 v115, 0xffff0000, v96
	v_mul_f32_e32 v86, v93, v93
	v_pk_mul_f32 v[122:123], v[94:95], v[94:95]
	v_mul_f32_e32 v106, v111, v111
	v_lshlrev_b32_e32 v114, 16, v96
	v_lshlrev_b32_e32 v96, 16, v97
	v_and_b32_e32 v97, 0xffff0000, v97
	v_mov_b32_e32 v125, v87
	v_mul_f32_e32 v124, v115, v115
	v_mov_b32_e32 v136, v112
	v_mov_b32_e32 v137, v94
	v_mov_b32_e32 v94, v113
	v_pk_fma_f32 v[142:143], v[92:93], v[92:93], v[86:87] op_sel_hi:[1,1,0]
	v_pk_fma_f32 v[112:113], v[112:113], v[112:113], v[122:123]
	v_pk_fma_f32 v[122:123], v[110:111], v[110:111], v[106:107] op_sel_hi:[1,1,0]
	v_and_b32_e32 v105, 0xffff0000, v60
	v_lshlrev_b32_e32 v60, 16, v61
	v_and_b32_e32 v61, 0xffff0000, v61
	v_mul_f32_e32 v126, v97, v97
	v_mov_b32_e32 v127, v107
	v_pk_fma_f32 v[144:145], v[114:115], v[114:115], v[124:125] op_sel_hi:[1,1,0]
	v_mov_b32_e32 v86, v122
	v_mov_b32_e32 v124, v142
	v_mul_f32_e32 v133, v105, v105
	v_mul_f32_e32 v135, v60, v60
	v_mul_f32_e32 v148, v61, v61
	v_mov_b32_e32 v104, v87
	v_pk_fma_f32 v[146:147], v[96:97], v[96:97], v[126:127] op_sel_hi:[1,1,0]
	v_pk_add_f32 v[122:123], v[122:123], v[142:143]
	v_pk_add_f32 v[112:113], v[112:113], v[112:113] op_sel:[0,1] op_sel_hi:[1,0]
	v_pk_mul_f32 v[86:87], v[86:87], v[124:125]
	v_lshlrev_b32_e32 v117, 16, v99
	v_lshlrev_b32_e32 v116, 16, v98
	v_and_b32_e32 v99, 0xffff0000, v99
	v_and_b32_e32 v98, 0xffff0000, v98
	v_mov_b32_e32 v145, v135
	v_mov_b32_e32 v147, v148
	v_mov_b32_e32 v113, v133
	v_mov_b32_e32 v123, v87
	v_pk_mul_f32 v[128:129], v[98:99], v[98:99]
	v_pk_add_f32 v[124:125], v[144:145], v[146:147]
	v_pk_add_f32 v[86:87], v[122:123], v[112:113]
	v_lshlrev_b32_e32 v119, 16, v101
	v_lshlrev_b32_e32 v118, 16, v100
	v_and_b32_e32 v101, 0xffff0000, v101
	v_and_b32_e32 v100, 0xffff0000, v100
	v_mov_b32_e32 v138, v116
	v_mov_b32_e32 v139, v98
	v_mov_b32_e32 v98, v117
	v_pk_fma_f32 v[116:117], v[116:117], v[116:117], v[128:129]
	v_pk_add_f32 v[86:87], v[86:87], v[124:125]
	v_lshlrev_b32_e32 v120, 16, v102
	v_and_b32_e32 v121, 0xffff0000, v102
	v_lshlrev_b32_e32 v102, 16, v103
	v_and_b32_e32 v103, 0xffff0000, v103
	v_pk_mul_f32 v[130:131], v[100:101], v[100:101]
	v_pk_add_f32 v[116:117], v[116:117], v[116:117] op_sel:[0,1] op_sel_hi:[1,0]
	v_pk_add_f32 v[86:87], v[86:87], v[86:87] op_sel:[0,1] op_sel_hi:[1,0]
	v_and_b32_e32 v109, 0xffff0000, v90
	v_lshlrev_b32_e32 v90, 16, v91
	v_and_b32_e32 v91, 0xffff0000, v91
	v_mul_f32_e32 v132, v121, v121
	v_mul_f32_e32 v134, v103, v103
	v_mov_b32_e32 v140, v118
	v_mov_b32_e32 v141, v100
	v_mov_b32_e32 v100, v119
	v_pk_fma_f32 v[118:119], v[118:119], v[118:119], v[130:131]
	v_mov_b32_e32 v126, v116
	v_mov_b32_e32 v106, v86
	v_mul_f32_e32 v149, v109, v109
	v_mul_f32_e32 v150, v90, v90
	v_mul_f32_e32 v151, v91, v91
	v_mov_b32_e32 v108, v107
	v_pk_fma_f32 v[128:129], v[120:121], v[120:121], v[132:133] op_sel_hi:[1,1,0]
	v_pk_fma_f32 v[130:131], v[102:103], v[102:103], v[134:135] op_sel_hi:[1,1,0]
	v_pk_add_f32 v[118:119], v[118:119], v[118:119] op_sel:[0,1] op_sel_hi:[1,0]
	v_pk_add_f32 v[86:87], v[86:87], v[116:117]
	v_pk_mul_f32 v[106:107], v[106:107], v[126:127]
	v_mov_b32_e32 v129, v150
	v_mov_b32_e32 v131, v151
	v_mov_b32_e32 v119, v149
	v_mov_b32_e32 v87, v107
	v_pk_add_f32 v[128:129], v[128:129], v[130:131]
	v_pk_add_f32 v[86:87], v[86:87], v[118:119]
	s_nop 0
	v_pk_add_f32 v[86:87], v[86:87], v[128:129]
	s_nop 0
	v_add_f32_e32 v86, v86, v87
	s_nop 0
	s_waitcnt lgkmcnt(0)
; #define LAS __attribute__((address_space(3)))
; __device__ __forceinline__ unsigned pk_bf16(float lo, float hi) { unsigned r; asm volatile("v_cvt_pk_bf16_f32 %0, %1, %2" : "=v"(r) : "v"(lo), "v"(hi)); return r; }
; template <int MODE, bool INBF> ...
;     ...
;             for (int q = 0; q < RB; ++q) { const int row = blk * 64 + wave + 8 * (i0 + q); float ss = 0.f;
; #pragma unroll
;                 for (int j = 0; j < 8; ++j) ss += (v[q][j].x * v[q][j].x + v[q][j].y * v[q][j].y) + (v[q][j].z * v[q][j].z + v[q][j].w * v[q][j].w);
;                 const float rstd = 1.0f / sqrtf(wave_sum(ss) * (1.0f / DM) + EPS);
; #pragma unroll
;                 for (int j = 0; j < 8; ++j) { const f32x4 a = *(const LAS f32x4*)(cA + 4 * (64 * j + lane)), bb = *(const LAS f32x4*)(cB + 4 * (64 * j + lane)); v[q][j] = (v[q][j] * rstd) * a + bb; }
;                 if (MODE == 1) { f32x4* o = (f32x4*)(outf + (size_t)row * DM) + lane;
; #pragma unroll
;                     for (int j = 0; j < 8; ++j) o[64 * j] = v[q][j];
;                 } else { u32x2* o = (u32x2*)(outb + (size_t)row * DM) + lane;
; #pragma unroll
;                     for (int j = 0; j < 8; ++j) { u32x2 w; w.x = pk_bf16(v[q][j].x, v[q][j].y); w.y = pk_bf16(v[q][j].z, v[q][j].w); o[64 * j] = w; } } }
	s_nop 1
	v_add_f32_dpp v86, v86, v86 quad_perm:[1,0,3,2] row_mask:0xf bank_mask:0xf
	s_nop 0
	s_waitcnt lgkmcnt(0)
	s_nop 1
	v_add_f32_dpp v86, v86, v86 quad_perm:[2,3,0,1] row_mask:0xf bank_mask:0xf
	s_nop 0
	s_waitcnt lgkmcnt(0)
	s_nop 1
	v_add_f32_dpp v86, v86, v86 row_half_mirror row_mask:0xf bank_mask:0xf
	s_nop 0
	s_waitcnt lgkmcnt(0)
	s_nop 1
	v_add_f32_dpp v86, v86, v86 row_mirror row_mask:0xf bank_mask:0xf
	v_mov_b32_e32 v87, v86
	s_waitcnt lgkmcnt(0)
	s_nop 1
	v_permlane16_swap_b32_e32 v86, v87
	v_add_f32_e32 v86, v86, v87
	v_mov_b32_e32 v87, v86
	s_waitcnt lgkmcnt(0)
	s_nop 1
	v_permlane32_swap_b32_e32 v86, v87
	v_add_f32_e32 v86, v86, v87
	v_fmamk_f32 v86, v86, 0x3a000000, v71
	v_mul_f32_e32 v87, 0x4f800000, v86
	v_cmp_gt_f32_e32 vcc, s18, v86
	s_nop 1
	v_cndmask_b32_e32 v86, v86, v87, vcc
	v_sqrt_f32_e32 v87, v86
	s_nop 0
	v_add_u32_e32 v106, -1, v87
	v_add_u32_e32 v107, 1, v87
	v_fma_f32 v112, -v106, v87, v86
	v_fma_f32 v113, -v107, v87, v86
	v_cmp_ge_f32_e64 s[8:9], 0, v112
	s_nop 1
	v_cndmask_b32_e64 v87, v87, v106, s[8:9]
	v_cmp_lt_f32_e64 s[8:9], 0, v113
	s_nop 1
	v_cndmask_b32_e64 v87, v87, v107, s[8:9]
	v_mul_f32_e32 v106, 0x37800000, v87
	v_cndmask_b32_e32 v87, v87, v106, vcc
	v_cmp_class_f32_e32 vcc, v86, v72
	s_nop 1
	v_cndmask_b32_e32 v86, v87, v86, vcc
	v_div_scale_f32 v87, s[8:9], v86, v86, 1.0
	v_rcp_f32_e32 v107, v87
	v_div_scale_f32 v106, vcc, 1.0, v86, 1.0
	v_fma_f32 v112, -v87, v107, 1.0
	v_fmac_f32_e32 v107, v112, v107
	v_mul_f32_e32 v112, v106, v107
	v_fma_f32 v113, -v87, v112, v106
	v_fmac_f32_e32 v112, v113, v107
	v_fma_f32 v87, -v87, v112, v106
	v_div_fmas_f32 v87, v87, v107, v112
	v_div_fixup_f32 v86, v87, v86, 1.0
	v_pk_mul_f32 v[106:107], v[86:87], v[110:111] op_sel_hi:[0,1]
	v_pk_mul_f32 v[92:93], v[86:87], v[92:93] op_sel_hi:[0,1]
	v_pk_fma_f32 v[0:1], v[0:1], v[106:107], v[12:13]
	v_pk_mul_f32 v[110:111], v[86:87], v[136:137] op_sel_hi:[0,1]
	v_pk_mul_f32 v[94:95], v[86:87], v[94:95] op_sel_hi:[0,1]
	v_pk_fma_f32 v[2:3], v[2:3], v[92:93], v[14:15]
	v_cvt_pk_bf16_f32 v0, v0, v1
	v_pk_mul_f32 v[112:113], v[86:87], v[114:115] op_sel_hi:[0,1]
	v_cvt_pk_bf16_f32 v1, v2, v3
	v_pk_mul_f32 v[96:97], v[86:87], v[96:97] op_sel_hi:[0,1]
	v_pk_fma_f32 v[6:7], v[6:7], v[94:95], v[10:11]
	v_pk_fma_f32 v[4:5], v[4:5], v[110:111], v[8:9]
	flat_store_dwordx2 v[88:89], v[0:1]
	v_cvt_pk_bf16_f32 v0, v4, v5
	v_cvt_pk_bf16_f32 v1, v6, v7
	v_pk_mul_f32 v[104:105], v[104:105], v[86:87] op_sel_hi:[1,0]
	v_pk_mul_f32 v[60:61], v[60:61], v[86:87] op_sel_hi:[1,0]
	v_pk_fma_f32 v[8:9], v[18:19], v[96:97], v[30:31]
	v_pk_fma_f32 v[10:11], v[16:17], v[112:113], v[28:29]
	flat_store_dwordx2 v[88:89], v[0:1] offset:512
	v_cvt_pk_bf16_f32 v0, v10, v11
	v_cvt_pk_bf16_f32 v1, v8, v9
	v_pk_mul_f32 v[114:115], v[86:87], v[138:139] op_sel_hi:[0,1]
	v_pk_mul_f32 v[98:99], v[86:87], v[98:99] op_sel_hi:[0,1]
	v_pk_fma_f32 v[12:13], v[22:23], v[60:61], v[26:27]
	v_pk_fma_f32 v[14:15], v[20:21], v[104:105], v[24:25]
	flat_store_dwordx2 v[88:89], v[0:1] offset:1024
	v_cvt_pk_bf16_f32 v0, v14, v15
	v_cvt_pk_bf16_f32 v1, v12, v13
	v_pk_mul_f32 v[116:117], v[86:87], v[140:141] op_sel_hi:[0,1]
	v_pk_mul_f32 v[100:101], v[86:87], v[100:101] op_sel_hi:[0,1]
	v_pk_fma_f32 v[16:17], v[34:35], v[98:99], v[46:47]
	v_pk_fma_f32 v[18:19], v[32:33], v[114:115], v[44:45]
	flat_store_dwordx2 v[88:89], v[0:1] offset:1536
	v_cvt_pk_bf16_f32 v0, v18, v19
	v_cvt_pk_bf16_f32 v1, v16, v17
	v_pk_mul_f32 v[118:119], v[86:87], v[120:121] op_sel_hi:[0,1]
	v_pk_mul_f32 v[102:103], v[86:87], v[102:103] op_sel_hi:[0,1]
	v_pk_fma_f32 v[20:21], v[38:39], v[100:101], v[42:43]
	v_pk_fma_f32 v[22:23], v[36:37], v[116:117], v[40:41]
	flat_store_dwordx2 v[88:89], v[0:1] offset:2048
	v_cvt_pk_bf16_f32 v0, v22, v23
	v_cvt_pk_bf16_f32 v1, v20, v21
	v_pk_mul_f32 v[108:109], v[108:109], v[86:87] op_sel_hi:[1,0]
	v_pk_mul_f32 v[86:87], v[90:91], v[86:87] op_sel_hi:[1,0]
	v_pk_fma_f32 v[24:25], v[50:51], v[102:103], v[80:81]
	v_pk_fma_f32 v[26:27], v[48:49], v[118:119], v[78:79]
	flat_store_dwordx2 v[88:89], v[0:1] offset:2560
	v_cvt_pk_bf16_f32 v0, v26, v27
	v_cvt_pk_bf16_f32 v1, v24, v25
	v_pk_fma_f32 v[28:29], v[86:87], v[76:77], v[84:85]
	v_pk_fma_f32 v[30:31], v[108:109], v[74:75], v[82:83]
	flat_store_dwordx2 v[88:89], v[0:1] offset:3072
	v_cvt_pk_bf16_f32 v0, v30, v31
	v_cvt_pk_bf16_f32 v1, v28, v29
	flat_store_dwordx2 v[88:89], v[0:1] offset:3584
	s_cbranch_scc1 .LBB0_418
	s_add_i32 s20, s20, s3
	s_add_i32 s10, s10, s16
	s_cmpk_lt_i32 s20, 0x100
	s_cbranch_scc1 .LBB0_414

; #define PG8_STAGE(bufoff, gbase, voff) do { _Pragma("unroll") for (int _i = 0; _i < 2; ++_i) \
;         __builtin_amdgcn_global_load_lds((const unsigned*)((const char*)(gbase) + (voff)[_i]), (PG8_LAS unsigned*)(lds + (bufoff) + ldsw + _i * 8192), 16, 0, 0); } while (0)
; #define PG8_WAIT_V(n) asm volatile("s_waitcnt vmcnt(" #n ")" ::: "memory")
; #define PG8_BAR __builtin_amdgcn_s_barrier()
; template <class Epi, class Sched, bool ALIGN_EPI = false, bool SP2 = false>
; __device__ __forceinline__ void gemm_phase(PG8_LAS unsigned char* lds, const Gemm g, const Sched& S, const Epi& E) {
;     ...
;     if constexpr (SP2) {
;         PG8_STAGE(PG8_SB(0, 0), cB, voffB); PG8_STAGE(PG8_SB(0, 1), cB + hstep, voffB); PG8_STAGE(PG8_SA(0, 0), cA, voffA); PG8_STAGE(PG8_SA(0, 1), cA + hstep, voffA);
;         if (wr == 1) PG8_BAR;
;         PG8_WAIT_V(2); PG8_BAR;
;         PG8_STAGE(PG8_SB(1, 0), cB + kstep, voffB); PG8_STAGE(PG8_SA(1, 0), cA + kstep, voffA); PG8_STAGE(PG8_SB(1, 1), cB + hstep + kstep, voffB);
;         PG8_WAIT_V(6); PG8_BAR;
.LBB0_475:
	s_add_u32 s10, s6, 0x1c400000
	s_addc_u32 s11, s7, 0
	s_lshl_b32 s6, s12, 5
	s_mov_b64 s[12:13], 0x80
	s_and_b32 s17, s6, 0x60
	s_add_i32 m0, s25, 0x18000
	v_lshl_add_u64 v[6:7], v[6:7], 0, s[12:13]
	s_lshl_b32 s16, s15, 13
	s_lshl_b32 s18, s17, 7
	global_load_lds_dwordx4 v[6:7], off
	v_lshl_add_u64 v[4:5], v[4:5], 0, s[12:13]
	s_add_i32 m0, s25, 0x1a000
	s_add_i32 s57, s25, 0x8000
	s_add_i32 s58, s25, 0xa000
	global_load_lds_dwordx4 v[4:5], off
	v_lshl_add_u64 v[0:1], v[0:1], 0, s[12:13]
	s_mov_b32 m0, s57
	s_add_u32 s6, s28, 0x80080
	global_load_lds_dwordx4 v[0:1], off
	v_lshl_add_u64 v[0:1], v[2:3], 0, s[12:13]
	s_mov_b32 m0, s58
	s_addc_u32 s7, s29, 0
	global_load_lds_dwordx4 v[0:1], off
	s_add_i32 m0, s25, 0x1c000
	v_lshl_add_u64 v[0:1], s[6:7], 0, v[132:133]
	global_load_lds_dwordx4 v[0:1], off
	v_lshl_add_u64 v[0:1], s[6:7], 0, v[128:129]
	s_add_i32 m0, s25, 0x1e000
	s_cmpk_lt_u32 s14, 0x100
	global_load_lds_dwordx4 v[0:1], off
	s_waitcnt vmcnt(8)
	s_barrier
	v_lshrrev_b32_e32 v1, 1, v8
	v_and_b32_e32 v1, 24, v1
	v_and_b32_e32 v0, 15, v8
	v_lshlrev_b32_e32 v2, 1, v1
	v_lshl_or_b32 v148, s15, 6, v0
	v_lshl_or_b32 v0, v0, 6, v2
	v_lshlrev_b32_e32 v2, 2, v8
	v_and_b32_e32 v2, 32, v2
	v_bitop3_b32 v3, v0, s16, v2 bitop3:0xde
	v_bitop3_b32 v149, v0, s18, v2 bitop3:0xde
	v_lshlrev_b32_e32 v0, 15, v9
	v_and_b32_e32 v0, 0xffff0000, v0
	v_or_b32_e32 v150, s17, v1
	v_lshl_add_u32 v0, v10, 12, v0
	v_and_b32_e32 v1, 1, v9
	v_lshl_or_b32 v0, v1, 6, v0
	v_lshl_add_u32 v136, v11, 1, v0
	v_lshlrev_b32_e32 v0, 15, v13
	v_and_b32_e32 v0, 0xffff0000, v0
	s_waitcnt vmcnt(6)
	v_lshl_add_u32 v0, v12, 12, v0
	v_and_b32_e32 v1, 1, v13
	s_cselect_b64 s[14:15], -1, 0
	v_lshl_or_b32 v0, v1, 6, v0
	s_add_i32 s60, 0, 0x10000
	s_add_i32 s61, 0, 0x14000
	s_ashr_i32 s59, s3, 31
	v_mov_b32_e32 v137, v133
	v_lshl_add_u32 v138, v14, 1, v0
	v_mov_b32_e32 v139, v133
	v_mov_b64_e32 v[140:141], 0xb00
	v_mov_b64_e32 v[142:143], 0xaff
	v_add_u32_e32 v151, s60, v149
	v_add_u32_e32 v152, s61, v149
	v_add_u32_e32 v153, 0, v3
	s_movk_i32 s62, 0x2c00
	s_barrier
	s_branch .LBB0_478

; #define PG8_STAGE(bufoff, gbase, voff) do { _Pragma("unroll") for (int _i = 0; _i < 2; ++_i) \
;         __builtin_amdgcn_global_load_lds((const unsigned*)((const char*)(gbase) + (voff)[_i]), (PG8_LAS unsigned*)(lds + (bufoff) + ldsw + _i * 8192), 16, 0, 0); } while (0)
; #define PG8_WAIT_V(n) asm volatile("s_waitcnt vmcnt(" #n ")" ::: "memory")
; #define PG8_BAR __builtin_amdgcn_s_barrier()
; template <class Epi, class Sched, bool ALIGN_EPI = false, bool SP2 = false>
; __device__ __forceinline__ void gemm_phase(PG8_LAS unsigned char* lds, const Gemm g, const Sched& S, const Epi& E) {
;     ...
;     if constexpr (SP2) {
;         PG8_STAGE(PG8_SB(0, 0), cB, voffB); PG8_STAGE(PG8_SB(0, 1), cB + hstep, voffB); PG8_STAGE(PG8_SA(0, 0), cA, voffA); PG8_STAGE(PG8_SA(0, 1), cA + hstep, voffA);
;         if (wr == 1) PG8_BAR;
;         PG8_WAIT_V(2); PG8_BAR;
;         PG8_STAGE(PG8_SB(1, 0), cB + kstep, voffB); PG8_STAGE(PG8_SA(1, 0), cA + kstep, voffA); PG8_STAGE(PG8_SB(1, 1), cB + hstep + kstep, voffB);
;         PG8_WAIT_V(6); PG8_BAR;
.LBB0_547:
	s_add_u32 s12, s6, 0x27400000
	s_addc_u32 s13, s7, 0
	s_add_u32 s60, s6, 0x10a000
	s_addc_u32 s61, s7, 0
	s_lshl_b32 s6, s9, 5
	s_mov_b64 s[14:15], 0x80
	s_and_b32 s9, s6, 0x60
	s_add_i32 m0, s55, 0x18000
	v_lshl_add_u64 v[6:7], v[6:7], 0, s[14:15]
	s_lshl_b32 s19, s17, 13
	s_lshl_b32 s20, s9, 7
	global_load_lds_dwordx4 v[6:7], off
	v_lshl_add_u64 v[2:3], v[2:3], 0, s[14:15]
	s_add_i32 m0, s55, 0x1a000
	s_add_i32 s62, s55, 0x8000
	s_add_i32 s63, s55, 0xa000
	global_load_lds_dwordx4 v[2:3], off
	v_lshl_add_u64 v[0:1], v[0:1], 0, s[14:15]
	s_mov_b32 m0, s62
	s_add_u32 s6, s30, 0x160080
	global_load_lds_dwordx4 v[0:1], off
	v_lshl_add_u64 v[0:1], v[4:5], 0, s[14:15]
	s_mov_b32 m0, s63
	s_addc_u32 s7, s31, 0
	global_load_lds_dwordx4 v[0:1], off
	s_add_i32 m0, s55, 0x1c000
	v_lshl_add_u64 v[0:1], s[6:7], 0, v[146:147]
	global_load_lds_dwordx4 v[0:1], off
	v_lshl_add_u64 v[0:1], s[6:7], 0, v[150:151]
	s_add_i32 m0, s55, 0x1e000
	s_mov_b64 s[6:7], 0x160080
	global_load_lds_dwordx4 v[0:1], off
	s_waitcnt vmcnt(8)
	s_barrier
	v_lshrrev_b32_e32 v1, 1, v8
	v_and_b32_e32 v1, 24, v1
	v_and_b32_e32 v0, 15, v8
	v_lshlrev_b32_e32 v2, 1, v1
	v_lshl_or_b32 v166, s17, 6, v0
	v_lshl_or_b32 v0, v0, 6, v2
	v_lshlrev_b32_e32 v2, 2, v8
	v_and_b32_e32 v2, 32, v2
	v_bitop3_b32 v3, v0, s19, v2 bitop3:0xde
	v_bitop3_b32 v167, v0, s20, v2 bitop3:0xde
	v_or_b32_e32 v168, s9, v1
	v_lshrrev_b32_e32 v1, 1, v13
	v_mul_lo_u32 v0, v14, s8
	v_mad_u64_u32 v[0:1], s[20:21], v1, s18, v[0:1]
	v_or_b32_e32 v0, v0, v15
	v_add_lshl_u32 v0, v0, v16, 1
	v_mov_b32_e32 v1, v147
	v_lshl_add_u64 v[152:153], v[0:1], 0, s[6:7]
	v_lshrrev_b32_e32 v1, 1, v9
	v_mul_lo_u32 v0, v10, s8
	v_mad_u64_u32 v[0:1], s[8:9], v1, s18, v[0:1]
	s_waitcnt vmcnt(6)
	s_cmpk_lt_u32 s16, 0x100
	v_or_b32_e32 v0, v0, v11
	s_cselect_b64 s[16:17], -1, 0
	v_add_lshl_u32 v0, v0, v12, 1
	v_mov_b32_e32 v1, v147
	s_add_i32 s65, 0, 0x10000
	s_add_i32 s66, 0, 0x14000
	s_ashr_i32 s64, s3, 31
	v_lshl_add_u64 v[154:155], v[0:1], 0, s[6:7]
	v_mov_b64_e32 v[156:157], 0x200
	v_mov_b64_e32 v[158:159], 0x1ff
	v_add_u32_e32 v169, s65, v167
	v_add_u32_e32 v170, s66, v167
	v_add_u32_e32 v171, 0, v3
	s_mov_b64 s[18:19], 0x80000
	s_mov_b32 s67, 0x80000
	s_mov_b64 s[20:21], 0x90000
	s_mov_b32 s68, 0x90000
	s_mov_b64 s[22:23], 0xa0000
	s_mov_b32 s69, 0xa0000
	s_mov_b64 s[24:25], 0xb0000
	s_mov_b32 s70, 0xb0000
	s_barrier
	s_branch .LBB0_550

; __device__ __forceinline__ float bf_lo(unsigned w) { return __uint_as_float(w << 16); }
; __device__ __forceinline__ float bf_hi(unsigned w) { return __uint_as_float(w & 0xffff0000u); }
; template <int MODE, bool INBF> ...
;     ...
;             for (int q = 0; q < RB; ++q) { const int row = blk * 64 + wave + 8 * (i0 + q);
;                 if (INBF) { const u32x2* xr = (const u32x2*)((const bf16*)xin_ + (size_t)row * DM) + lane;
; #pragma unroll
;                     for (int j = 0; j < 8; ++j) { const u32x2 w = xr[64 * j]; v[q][j] = (f32x4){bf_lo(w.x), bf_hi(w.x), bf_lo(w.y), bf_hi(w.y)}; }
;                 } else { const f32x4* xr = (const f32x4*)((const float*)xin_ + (size_t)row * DM) + lane;
; #pragma unroll
;                     for (int j = 0; j < 8; ++j) v[q][j] = xr[64 * j]; } }
; #pragma unroll
;             for (int q = 0; q < RB; ++q) { const int row = blk * 64 + wave + 8 * (i0 + q); float ss = 0.f;
; #pragma unroll
;                 for (int j = 0; j < 8; ++j) ss += (v[q][j].x * v[q][j].x + v[q][j].y * v[q][j].y) + (v[q][j].z * v[q][j].z + v[q][j].w * v[q][j].w);
;                 const float rstd = 1.0f / sqrtf(wave_sum(ss) * (1.0f / DM) + EPS);
.LBB0_640:
	s_lshl_b32 s18, s62, 3
	s_add_i32 s28, s18, s61
	s_ashr_i32 s29, s28, 31
	s_lshl_b64 s[34:35], s[28:29], 12
	v_lshl_add_u64 v[0:1], v[20:21], 0, s[34:35]
	flat_load_dwordx2 v[2:3], v[0:1] offset:1536
	flat_load_dwordx2 v[4:5], v[0:1] offset:3584
	flat_load_dwordx2 v[6:7], v[0:1]
	flat_load_dwordx2 v[14:15], v[0:1] offset:512
	flat_load_dwordx2 v[34:35], v[0:1] offset:1024
	flat_load_dwordx2 v[42:43], v[0:1] offset:2048
	flat_load_dwordx2 v[44:45], v[0:1] offset:2560
	s_nop 0
	flat_load_dwordx2 v[0:1], v[0:1] offset:3072
	s_add_i32 s26, s28, 8
	s_ashr_i32 s27, s26, 31
	s_lshl_b64 s[30:31], s[26:27], 12
	v_lshl_add_u64 v[46:47], v[20:21], 0, s[30:31]
	flat_load_dwordx2 v[48:49], v[46:47] offset:1536
	flat_load_dwordx2 v[50:51], v[46:47] offset:3584
	flat_load_dwordx2 v[74:75], v[46:47]
	flat_load_dwordx2 v[72:73], v[46:47] offset:512
	flat_load_dwordx2 v[70:71], v[46:47] offset:1024
	s_waitcnt vmcnt(0) lgkmcnt(0)
	v_lshlrev_b32_e32 v41, 16, v2
	v_lshlrev_b32_e32 v13, 16, v4
	v_lshlrev_b32_e32 v76, 16, v6
	v_and_b32_e32 v77, 0xffff0000, v6
	v_lshlrev_b32_e32 v6, 16, v7
	v_and_b32_e32 v7, 0xffff0000, v7
	v_and_b32_e32 v11, 0xffff0000, v4
	v_lshlrev_b32_e32 v8, 16, v5
	v_and_b32_e32 v9, 0xffff0000, v5
	v_lshlrev_b32_e32 v81, 16, v15
	v_lshlrev_b32_e32 v80, 16, v14
	v_and_b32_e32 v15, 0xffff0000, v15
	v_and_b32_e32 v14, 0xffff0000, v14
	v_lshlrev_b32_e32 v92, 16, v0
	v_and_b32_e32 v93, 0xffff0000, v0
	v_lshlrev_b32_e32 v94, 16, v1
	v_and_b32_e32 v95, 0xffff0000, v1
	v_mul_f32_e32 v0, v7, v7
	v_mul_f32_e32 v4, v77, v77
	v_mov_b32_e32 v1, v41
	v_mov_b32_e32 v5, v13
	v_and_b32_e32 v39, 0xffff0000, v2
	v_lshlrev_b32_e32 v36, 16, v3
	v_and_b32_e32 v37, 0xffff0000, v3
	v_lshlrev_b32_e32 v82, 16, v34
	v_and_b32_e32 v83, 0xffff0000, v34
	v_lshlrev_b32_e32 v34, 16, v35
	v_and_b32_e32 v35, 0xffff0000, v35
	v_pk_mul_f32 v[2:3], v[14:15], v[14:15]
	v_pk_fma_f32 v[52:53], v[6:7], v[6:7], v[0:1] op_sel_hi:[1,1,0]
	v_pk_fma_f32 v[54:55], v[76:77], v[76:77], v[4:5] op_sel_hi:[1,1,0]
	v_mul_f32_e32 v10, v83, v83
	v_mul_f32_e32 v12, v35, v35
	v_pk_fma_f32 v[2:3], v[80:81], v[80:81], v[2:3]
	v_mov_b32_e32 v40, v54
	v_mov_b32_e32 v0, v52
	v_mul_f32_e32 v38, v39, v39
	v_mul_f32_e32 v62, v36, v36
	v_mul_f32_e32 v63, v37, v37
	v_pk_fma_f32 v[56:57], v[82:83], v[82:83], v[10:11] op_sel_hi:[1,1,0]
	v_pk_fma_f32 v[58:59], v[34:35], v[34:35], v[12:13] op_sel_hi:[1,1,0]
	v_pk_add_f32 v[52:53], v[54:55], v[52:53]
	v_pk_add_f32 v[2:3], v[2:3], v[2:3] op_sel:[0,1] op_sel_hi:[1,0]
	v_pk_mul_f32 v[0:1], v[40:41], v[0:1]
	v_and_b32_e32 v87, 0xffff0000, v43
	v_and_b32_e32 v86, 0xffff0000, v42
	v_mov_b32_e32 v57, v62
	v_mov_b32_e32 v59, v63
	v_mov_b32_e32 v3, v38
	v_mov_b32_e32 v53, v1
	v_lshlrev_b32_e32 v85, 16, v43
	v_lshlrev_b32_e32 v84, 16, v42
	v_pk_mul_f32 v[42:43], v[86:87], v[86:87]
	v_pk_add_f32 v[54:55], v[56:57], v[58:59]
	v_pk_add_f32 v[0:1], v[52:53], v[2:3]
	v_pk_fma_f32 v[42:43], v[84:85], v[84:85], v[42:43]
	v_pk_add_f32 v[0:1], v[0:1], v[54:55]
	v_pk_add_f32 v[42:43], v[42:43], v[42:43] op_sel:[0,1] op_sel_hi:[1,0]
	v_pk_add_f32 v[0:1], v[0:1], v[0:1] op_sel:[0,1] op_sel_hi:[1,0]
	v_and_b32_e32 v91, 0xffff0000, v45
	v_and_b32_e32 v90, 0xffff0000, v44
	v_mov_b32_e32 v4, v42
	v_mov_b32_e32 v12, v0
	v_lshlrev_b32_e32 v89, 16, v45
	v_lshlrev_b32_e32 v88, 16, v44
	v_pk_mul_f32 v[44:45], v[90:91], v[90:91]
	v_pk_mul_f32 v[2:3], v[12:13], v[4:5]
	v_mul_f32_e32 v18, v93, v93
	v_pk_fma_f32 v[44:45], v[88:89], v[88:89], v[44:45]
	v_pk_add_f32 v[0:1], v[0:1], v[42:43]
	v_mul_f32_e32 v2, v95, v95
	v_mul_f32_e32 v64, v11, v11
	v_mul_f32_e32 v65, v8, v8
	v_mul_f32_e32 v66, v9, v9
	v_pk_fma_f32 v[60:61], v[92:93], v[92:93], v[18:19] op_sel_hi:[1,1,0]
	v_pk_add_f32 v[44:45], v[44:45], v[44:45] op_sel:[0,1] op_sel_hi:[1,0]
	v_mov_b32_e32 v1, v3
	v_pk_fma_f32 v[2:3], v[94:95], v[94:95], v[2:3] op_sel_hi:[1,1,0]
	v_mov_b32_e32 v61, v65
	v_mov_b32_e32 v45, v64
	v_mov_b32_e32 v3, v66
	v_pk_add_f32 v[0:1], v[0:1], v[44:45]
	v_pk_add_f32 v[2:3], v[60:61], v[2:3]
	flat_load_dwordx2 v[68:69], v[46:47] offset:2048
	flat_load_dwordx2 v[66:67], v[46:47] offset:2560
	flat_load_dwordx2 v[64:65], v[46:47] offset:3072
	v_pk_add_f32 v[0:1], v[0:1], v[2:3]
	ds_read_b128 v[2:5], v109
	ds_read_b128 v[42:45], v109 offset:8192
	v_add_f32_e32 v0, v0, v1
	s_nop 0
	v_lshlrev_b32_e32 v63, 16, v48
	v_and_b32_e32 v61, 0xffff0000, v48
	v_lshlrev_b32_e32 v58, 16, v49
	v_and_b32_e32 v59, 0xffff0000, v49
	s_waitcnt lgkmcnt(0)
	s_nop 1
	v_add_f32_dpp v0, v0, v0 quad_perm:[1,0,3,2] row_mask:0xf bank_mask:0xf
	s_nop 0
	v_lshlrev_b32_e32 v57, 16, v50
	v_and_b32_e32 v55, 0xffff0000, v50
	v_lshlrev_b32_e32 v52, 16, v51
	v_and_b32_e32 v53, 0xffff0000, v51
	s_waitcnt lgkmcnt(0)
	s_nop 1
	v_add_f32_dpp v0, v0, v0 quad_perm:[2,3,0,1] row_mask:0xf bank_mask:0xf
	s_nop 0
	v_mov_b32_e32 v97, v63
	v_mul_f32_e32 v54, v61, v61
	v_mul_f32_e32 v56, v58, v58
	v_mul_f32_e32 v60, v59, v59
	s_waitcnt lgkmcnt(0)
	s_nop 1
	v_add_f32_dpp v0, v0, v0 row_half_mirror row_mask:0xf bank_mask:0xf
	s_nop 0
	v_mov_b32_e32 v18, 0
	s_waitcnt lgkmcnt(0)
	s_nop 1
	v_add_f32_dpp v0, v0, v0 row_mirror row_mask:0xf bank_mask:0xf
	v_mov_b32_e32 v1, v0
	s_waitcnt lgkmcnt(0)
	s_nop 1
	v_permlane16_swap_b32_e32 v0, v1
	v_add_f32_e32 v0, v0, v1
	v_mov_b32_e32 v1, v0
	s_waitcnt lgkmcnt(0)
	s_nop 1
	v_permlane32_swap_b32_e32 v0, v1
	v_add_f32_e32 v0, v0, v1
	v_fmamk_f32 v0, v0, 0x3a000000, v111
	v_mul_f32_e32 v1, 0x4f800000, v0
	v_cmp_gt_f32_e32 vcc, s51, v0
	s_waitcnt vmcnt(0)
; #define LAS __attribute__((address_space(3)))
; __device__ __forceinline__ unsigned pk_bf16(float lo, float hi) { unsigned r; asm volatile("v_cvt_pk_bf16_f32 %0, %1, %2" : "=v"(r) : "v"(lo), "v"(hi)); return r; }
; template <int MODE, bool INBF> ...
;     ...
;             for (int q = 0; q < RB; ++q) { const int row = blk * 64 + wave + 8 * (i0 + q); float ss = 0.f;
; #pragma unroll
;                 for (int j = 0; j < 8; ++j) ss += (v[q][j].x * v[q][j].x + v[q][j].y * v[q][j].y) + (v[q][j].z * v[q][j].z + v[q][j].w * v[q][j].w);
;                 const float rstd = 1.0f / sqrtf(wave_sum(ss) * (1.0f / DM) + EPS);
; #pragma unroll
;                 for (int j = 0; j < 8; ++j) { const f32x4 a = *(const LAS f32x4*)(cA + 4 * (64 * j + lane)), bb = *(const LAS f32x4*)(cB + 4 * (64 * j + lane)); v[q][j] = (v[q][j] * rstd) * a + bb; }
;                 if (MODE == 1) { f32x4* o = (f32x4*)(outf + (size_t)row * DM) + lane;
; #pragma unroll
;                     for (int j = 0; j < 8; ++j) o[64 * j] = v[q][j];
;                 } else { u32x2* o = (u32x2*)(outb + (size_t)row * DM) + lane;
; #pragma unroll
;                     for (int j = 0; j < 8; ++j) { u32x2 w; w.x = pk_bf16(v[q][j].x, v[q][j].y); w.y = pk_bf16(v[q][j].z, v[q][j].w); o[64 * j] = w; } } }
	v_and_b32_e32 v117, 0xffff0000, v69
	v_cndmask_b32_e32 v0, v0, v1, vcc
	v_sqrt_f32_e32 v1, v0
	v_and_b32_e32 v116, 0xffff0000, v68
	v_and_b32_e32 v121, 0xffff0000, v67
	v_and_b32_e32 v120, 0xffff0000, v66
	v_add_u32_e32 v10, -1, v1
	v_add_u32_e32 v12, 1, v1
	v_fma_f32 v38, -v10, v1, v0
	v_fma_f32 v40, -v12, v1, v0
	v_cmp_ge_f32_e64 s[18:19], 0, v38
	v_lshlrev_b32_e32 v119, 16, v67
	v_lshlrev_b32_e32 v118, 16, v66
	v_cndmask_b32_e64 v1, v1, v10, s[18:19]
	v_cmp_lt_f32_e64 s[18:19], 0, v40
	v_pk_mul_f32 v[66:67], v[120:121], v[120:121]
	v_lshlrev_b32_e32 v122, 16, v64
	v_cndmask_b32_e64 v1, v1, v12, s[18:19]
	v_mul_f32_e32 v10, 0x37800000, v1
	v_cndmask_b32_e32 v1, v1, v10, vcc
	v_cmp_class_f32_e32 vcc, v0, v112
	v_and_b32_e32 v123, 0xffff0000, v64
	v_lshlrev_b32_e32 v124, 16, v65
	v_cndmask_b32_e32 v0, v1, v0, vcc
	v_div_scale_f32 v1, s[18:19], v0, v0, 1.0
	v_rcp_f32_e32 v10, v1
	v_div_scale_f32 v12, vcc, 1.0, v0, 1.0
	v_and_b32_e32 v125, 0xffff0000, v65
	v_fma_f32 v38, -v1, v10, 1.0
	v_fmac_f32_e32 v10, v38, v10
	v_mul_f32_e32 v38, v12, v10
	v_fma_f32 v40, -v1, v38, v12
	v_fmac_f32_e32 v38, v40, v10
	v_fma_f32 v1, -v1, v38, v12
	v_div_fmas_f32 v1, v1, v10, v38
	v_div_fixup_f32 v12, v1, v0, 1.0
	v_pk_mul_f32 v[50:51], v[12:13], v[76:77] op_sel_hi:[0,1]
	ds_read_b128 v[46:49], v109 offset:1024
	ds_read_b128 v[76:79], v109 offset:9216
	v_pk_mul_f32 v[0:1], v[12:13], v[6:7] op_sel_hi:[0,1]
	v_pk_fma_f32 v[0:1], v[4:5], v[0:1], v[44:45]
	v_mov_b32_e32 v4, v80
	v_mov_b32_e32 v5, v14
	v_mov_b32_e32 v14, v81
	v_pk_mul_f32 v[6:7], v[12:13], v[4:5] op_sel_hi:[0,1]
	v_pk_mul_f32 v[4:5], v[12:13], v[14:15] op_sel_hi:[0,1]
	v_pk_fma_f32 v[2:3], v[2:3], v[50:51], v[42:43]
	s_waitcnt lgkmcnt(0)
	v_pk_fma_f32 v[4:5], v[48:49], v[4:5], v[78:79]
	v_pk_fma_f32 v[6:7], v[46:47], v[6:7], v[76:77]
	ds_read_b128 v[42:45], v109 offset:2048
	ds_read_b128 v[46:49], v109 offset:10240
	v_pk_mul_f32 v[50:51], v[12:13], v[82:83] op_sel_hi:[0,1]
	ds_read_b128 v[76:79], v109 offset:3072
	ds_read_b128 v[80:83], v109 offset:11264
	v_pk_mul_f32 v[14:15], v[12:13], v[34:35] op_sel_hi:[0,1]
	v_mov_b32_e32 v38, v41
	s_waitcnt lgkmcnt(2)
	v_pk_fma_f32 v[14:15], v[44:45], v[14:15], v[48:49]
	v_pk_fma_f32 v[34:35], v[42:43], v[50:51], v[46:47]
	ds_read_b128 v[42:45], v109 offset:4096
	ds_read_b128 v[46:49], v109 offset:12288
	v_pk_mul_f32 v[38:39], v[12:13], v[38:39] op_sel_hi:[0,1]
	v_pk_mul_f32 v[36:37], v[12:13], v[36:37] op_sel_hi:[0,1]
	s_waitcnt lgkmcnt(2)
	v_pk_fma_f32 v[36:37], v[78:79], v[36:37], v[82:83]
	v_pk_fma_f32 v[38:39], v[76:77], v[38:39], v[80:81]
	ds_read_b128 v[76:79], v109 offset:5120
	ds_read_b128 v[80:83], v109 offset:13312
	v_mov_b32_e32 v40, v84
	v_mov_b32_e32 v41, v86
	v_mov_b32_e32 v86, v85
	v_pk_mul_f32 v[50:51], v[12:13], v[40:41] op_sel_hi:[0,1]
	v_pk_mul_f32 v[40:41], v[12:13], v[86:87] op_sel_hi:[0,1]
	s_waitcnt lgkmcnt(2)
	v_pk_fma_f32 v[40:41], v[44:45], v[40:41], v[48:49]
	v_mov_b32_e32 v44, v88
	v_mov_b32_e32 v45, v90
	v_mov_b32_e32 v90, v89
	v_pk_fma_f32 v[42:43], v[42:43], v[50:51], v[46:47]
	v_pk_mul_f32 v[46:47], v[12:13], v[44:45] op_sel_hi:[0,1]
	v_pk_mul_f32 v[44:45], v[12:13], v[90:91] op_sel_hi:[0,1]
	s_waitcnt lgkmcnt(0)
	v_pk_fma_f32 v[44:45], v[44:45], v[78:79], v[82:83]
	v_pk_fma_f32 v[46:47], v[46:47], v[76:77], v[80:81]
	ds_read_b128 v[76:79], v109 offset:6144
	ds_read_b128 v[80:83], v109 offset:14336
	v_pk_mul_f32 v[50:51], v[12:13], v[92:93] op_sel_hi:[0,1]
	v_pk_mul_f32 v[48:49], v[12:13], v[94:95] op_sel_hi:[0,1]
	v_lshlrev_b32_e32 v92, 16, v70
	v_and_b32_e32 v93, 0xffff0000, v70
	s_waitcnt lgkmcnt(0)
	v_pk_fma_f32 v[50:51], v[50:51], v[76:77], v[80:81]
	v_lshlrev_b32_e32 v76, 16, v74
	v_and_b32_e32 v77, 0xffff0000, v74
	v_lshlrev_b32_e32 v74, 16, v75
	v_and_b32_e32 v75, 0xffff0000, v75
	v_mul_f32_e32 v10, v75, v75
	v_pk_fma_f32 v[48:49], v[48:49], v[78:79], v[82:83]
	v_pk_fma_f32 v[78:79], v[74:75], v[74:75], v[10:11] op_sel_hi:[1,1,0]
	v_and_b32_e32 v83, 0xffff0000, v73
	v_and_b32_e32 v82, 0xffff0000, v72
	v_mul_f32_e32 v10, v77, v77
	v_lshlrev_b32_e32 v81, 16, v73
	v_lshlrev_b32_e32 v80, 16, v72
	v_pk_mul_f32 v[72:73], v[82:83], v[82:83]
	v_lshlrev_b32_e32 v94, 16, v71
	v_and_b32_e32 v95, 0xffff0000, v71
	v_pk_fma_f32 v[70:71], v[76:77], v[76:77], v[10:11] op_sel_hi:[1,1,0]
	v_pk_fma_f32 v[72:73], v[80:81], v[80:81], v[72:73]
	v_mov_b32_e32 v62, v70
	v_mov_b32_e32 v96, v78
	v_pk_add_f32 v[70:71], v[70:71], v[78:79]
	v_pk_mul_f32 v[78:79], v[62:63], v[96:97]
	v_pk_add_f32 v[72:73], v[72:73], v[72:73] op_sel:[0,1] op_sel_hi:[1,0]
	v_mov_b32_e32 v71, v79
	v_mov_b32_e32 v73, v54
	v_mul_f32_e32 v10, v93, v93
	v_pk_add_f32 v[70:71], v[70:71], v[72:73]
	v_pk_fma_f32 v[72:73], v[92:93], v[92:93], v[10:11] op_sel_hi:[1,1,0]
	v_mul_f32_e32 v10, v95, v95
	v_pk_fma_f32 v[78:79], v[94:95], v[94:95], v[10:11] op_sel_hi:[1,1,0]
	v_mov_b32_e32 v73, v56
	v_mov_b32_e32 v79, v60
	v_pk_add_f32 v[72:73], v[72:73], v[78:79]
	v_lshlrev_b32_e32 v97, 16, v69
	v_lshlrev_b32_e32 v96, 16, v68
	v_pk_mul_f32 v[68:69], v[116:117], v[116:117]
	v_pk_add_f32 v[70:71], v[70:71], v[72:73]
	v_pk_fma_f32 v[68:69], v[96:97], v[96:97], v[68:69]
	v_pk_add_f32 v[64:65], v[70:71], v[70:71] op_sel:[0,1] op_sel_hi:[1,0]
	v_pk_add_f32 v[68:69], v[68:69], v[68:69] op_sel:[0,1] op_sel_hi:[1,0]
	v_pk_fma_f32 v[66:67], v[118:119], v[118:119], v[66:67]
	v_mov_b32_e32 v56, v64
	v_mov_b32_e32 v70, v68
	v_mov_b32_e32 v71, v57
	v_mul_f32_e32 v10, v55, v55
	v_pk_add_f32 v[64:65], v[64:65], v[68:69]
	v_pk_mul_f32 v[68:69], v[56:57], v[70:71]
	v_pk_add_f32 v[66:67], v[66:67], v[66:67] op_sel:[0,1] op_sel_hi:[1,0]
	v_mov_b32_e32 v65, v69
	v_mov_b32_e32 v67, v10
	v_mul_f32_e32 v10, v123, v123
	v_pk_add_f32 v[64:65], v[64:65], v[66:67]
	v_pk_fma_f32 v[66:67], v[122:123], v[122:123], v[10:11] op_sel_hi:[1,1,0]
	v_mul_f32_e32 v10, v125, v125
	v_mul_f32_e32 v54, v52, v52
	v_mul_f32_e32 v60, v53, v53
	v_pk_fma_f32 v[68:69], v[124:125], v[124:125], v[10:11] op_sel_hi:[1,1,0]
	v_mov_b32_e32 v67, v54
	v_mov_b32_e32 v69, v60
	v_pk_add_f32 v[66:67], v[66:67], v[68:69]
	v_mov_b32_e32 v10, v13
	v_pk_add_f32 v[64:65], v[64:65], v[66:67]
	ds_read_b128 v[84:87], v109 offset:7168
	ds_read_b128 v[88:91], v109 offset:15360
	v_add_f32_e32 v54, v64, v65
	s_nop 0
	v_pk_mul_f32 v[10:11], v[12:13], v[10:11] op_sel_hi:[0,1]
	v_pk_mul_f32 v[8:9], v[12:13], v[8:9] op_sel_hi:[0,1]
	v_lshl_add_u64 v[12:13], v[22:23], 0, s[34:35]
	v_cvt_pk_bf16_f32 v64, v2, v3
	s_waitcnt lgkmcnt(0)
; #define LAS __attribute__((address_space(3)))
; __device__ __forceinline__ unsigned pk_bf16(float lo, float hi) { unsigned r; asm volatile("v_cvt_pk_bf16_f32 %0, %1, %2" : "=v"(r) : "v"(lo), "v"(hi)); return r; }
; template <int MODE, bool INBF> ...
;     ...
;             for (int q = 0; q < RB; ++q) { const int row = blk * 64 + wave + 8 * (i0 + q); float ss = 0.f;
; #pragma unroll
;                 for (int j = 0; j < 8; ++j) ss += (v[q][j].x * v[q][j].x + v[q][j].y * v[q][j].y) + (v[q][j].z * v[q][j].z + v[q][j].w * v[q][j].w);
;                 const float rstd = 1.0f / sqrtf(wave_sum(ss) * (1.0f / DM) + EPS);
; #pragma unroll
;                 for (int j = 0; j < 8; ++j) { const f32x4 a = *(const LAS f32x4*)(cA + 4 * (64 * j + lane)), bb = *(const LAS f32x4*)(cB + 4 * (64 * j + lane)); v[q][j] = (v[q][j] * rstd) * a + bb; }
;                 if (MODE == 1) { f32x4* o = (f32x4*)(outf + (size_t)row * DM) + lane;
; #pragma unroll
;                     for (int j = 0; j < 8; ++j) o[64 * j] = v[q][j];
;                 } else { u32x2* o = (u32x2*)(outb + (size_t)row * DM) + lane;
; #pragma unroll
;                     for (int j = 0; j < 8; ++j) { u32x2 w; w.x = pk_bf16(v[q][j].x, v[q][j].y); w.y = pk_bf16(v[q][j].z, v[q][j].w); o[64 * j] = w; } } }
	s_nop 1
	v_add_f32_dpp v54, v54, v54 quad_perm:[1,0,3,2] row_mask:0xf bank_mask:0xf
	s_nop 0
	v_cvt_pk_bf16_f32 v65, v0, v1
	flat_store_dwordx2 v[12:13], v[64:65]
	v_cvt_pk_bf16_f32 v64, v6, v7
	v_cvt_pk_bf16_f32 v65, v4, v5
	s_waitcnt lgkmcnt(0)
	s_nop 1
	v_add_f32_dpp v54, v54, v54 quad_perm:[2,3,0,1] row_mask:0xf bank_mask:0xf
	s_nop 0
	flat_store_dwordx2 v[12:13], v[64:65] offset:512
	v_cvt_pk_bf16_f32 v64, v34, v35
	v_cvt_pk_bf16_f32 v65, v14, v15
	flat_store_dwordx2 v[12:13], v[64:65] offset:1024
	s_waitcnt lgkmcnt(0)
	s_nop 1
	v_add_f32_dpp v54, v54, v54 row_half_mirror row_mask:0xf bank_mask:0xf
	s_nop 0
	v_cvt_pk_bf16_f32 v64, v38, v39
	v_cvt_pk_bf16_f32 v65, v36, v37
	flat_store_dwordx2 v[12:13], v[64:65] offset:1536
	v_cvt_pk_bf16_f32 v64, v42, v43
	s_waitcnt lgkmcnt(0)
	s_nop 1
	v_add_f32_dpp v54, v54, v54 row_mirror row_mask:0xf bank_mask:0xf
	v_mov_b32_e32 v56, v54
	v_cvt_pk_bf16_f32 v65, v40, v41
	flat_store_dwordx2 v[12:13], v[64:65] offset:2048
	v_cvt_pk_bf16_f32 v64, v46, v47
	v_cvt_pk_bf16_f32 v65, v44, v45
	s_waitcnt lgkmcnt(0)
	s_nop 1
	v_permlane16_swap_b32_e32 v54, v56
	v_add_f32_e32 v54, v54, v56
	v_mov_b32_e32 v56, v54
	flat_store_dwordx2 v[12:13], v[64:65] offset:2560
	v_cvt_pk_bf16_f32 v64, v50, v51
	v_cvt_pk_bf16_f32 v65, v48, v49
	v_pk_fma_f32 v[8:9], v[8:9], v[86:87], v[90:91]
	s_waitcnt lgkmcnt(0)
	s_nop 1
	v_permlane32_swap_b32_e32 v54, v56
	v_add_f32_e32 v54, v54, v56
	v_fmamk_f32 v54, v54, 0x3a000000, v111
	v_mul_f32_e32 v56, 0x4f800000, v54
	v_cmp_gt_f32_e32 vcc, s51, v54
	v_pk_fma_f32 v[10:11], v[10:11], v[84:85], v[88:89]
	flat_store_dwordx2 v[12:13], v[64:65] offset:3072
	v_cndmask_b32_e32 v54, v54, v56, vcc
	v_sqrt_f32_e32 v56, v54
	v_cvt_pk_bf16_f32 v64, v10, v11
	v_cvt_pk_bf16_f32 v65, v8, v9
	flat_store_dwordx2 v[12:13], v[64:65] offset:3584
	v_add_u32_e32 v60, -1, v56
	v_fma_f32 v62, -v60, v56, v54
	v_cmp_ge_f32_e64 s[18:19], 0, v62
	v_add_u32_e32 v62, 1, v56
	ds_read_b128 v[64:67], v109
	ds_read_b128 v[68:71], v109 offset:8192
	v_cndmask_b32_e64 v60, v56, v60, s[18:19]
	v_fma_f32 v56, -v62, v56, v54
	v_cmp_lt_f32_e64 s[18:19], 0, v56
	s_nop 1
	v_cndmask_b32_e64 v56, v60, v62, s[18:19]
	v_mul_f32_e32 v60, 0x37800000, v56
	v_cndmask_b32_e32 v56, v56, v60, vcc
	v_cmp_class_f32_e32 vcc, v54, v112
	s_nop 1
	v_cndmask_b32_e32 v54, v56, v54, vcc
	v_div_scale_f32 v56, s[18:19], v54, v54, 1.0
	v_rcp_f32_e32 v60, v56
	s_mov_b32 s18, 0
	v_fma_f32 v12, -v56, v60, 1.0
	v_fmac_f32_e32 v60, v12, v60
	v_div_scale_f32 v12, vcc, 1.0, v54, 1.0
	v_mul_f32_e32 v13, v12, v60
	v_fma_f32 v62, -v56, v13, v12
	v_fmac_f32_e32 v13, v62, v60
	v_fma_f32 v12, -v56, v13, v12
	v_div_fmas_f32 v12, v12, v60, v13
	v_div_fixup_f32 v12, v12, v54, 1.0
	v_pk_mul_f32 v[84:85], v[12:13], v[76:77] op_sel_hi:[0,1]
	v_pk_mul_f32 v[86:87], v[12:13], v[74:75] op_sel_hi:[0,1]
	ds_read_b128 v[72:75], v109 offset:1024
	ds_read_b128 v[76:79], v109 offset:9216
	s_waitcnt lgkmcnt(0)
	v_pk_fma_f32 v[84:85], v[64:65], v[84:85], v[68:69]
	v_mov_b32_e32 v64, v80
	v_mov_b32_e32 v65, v82
	v_mov_b32_e32 v82, v81
	v_pk_fma_f32 v[86:87], v[66:67], v[86:87], v[70:71]
	v_pk_mul_f32 v[64:65], v[12:13], v[64:65] op_sel_hi:[0,1]
	v_pk_mul_f32 v[66:67], v[12:13], v[82:83] op_sel_hi:[0,1]
	v_pk_fma_f32 v[90:91], v[74:75], v[66:67], v[78:79]
	v_pk_fma_f32 v[88:89], v[72:73], v[64:65], v[76:77]
	ds_read_b128 v[64:67], v109 offset:2048
	ds_read_b128 v[68:71], v109 offset:10240
	ds_read_b128 v[72:75], v109 offset:3072
	ds_read_b128 v[76:79], v109 offset:11264
	v_mov_b32_e32 v60, v63
	v_pk_mul_f32 v[80:81], v[12:13], v[92:93] op_sel_hi:[0,1]
	v_pk_mul_f32 v[60:61], v[12:13], v[60:61] op_sel_hi:[0,1]
	v_pk_mul_f32 v[58:59], v[12:13], v[58:59] op_sel_hi:[0,1]
	v_pk_mul_f32 v[82:83], v[12:13], v[94:95] op_sel_hi:[0,1]
	s_waitcnt lgkmcnt(0)
	v_pk_fma_f32 v[94:95], v[64:65], v[80:81], v[68:69]
	v_pk_fma_f32 v[126:127], v[74:75], v[58:59], v[78:79]
	v_pk_fma_f32 v[128:129], v[72:73], v[60:61], v[76:77]
	ds_read_b128 v[58:61], v109 offset:4096
	ds_read_b128 v[62:65], v109 offset:12288
	v_pk_fma_f32 v[92:93], v[66:67], v[82:83], v[70:71]
	v_mov_b32_e32 v66, v96
	v_mov_b32_e32 v67, v116
	v_pk_mul_f32 v[74:75], v[12:13], v[66:67] op_sel_hi:[0,1]
	ds_read_b128 v[66:69], v109 offset:5120
	ds_read_b128 v[70:73], v109 offset:13312
	v_mov_b32_e32 v116, v97
	v_pk_mul_f32 v[76:77], v[12:13], v[116:117] op_sel_hi:[0,1]
	s_waitcnt lgkmcnt(0)
	v_pk_fma_f32 v[116:117], v[58:59], v[74:75], v[62:63]
	v_mov_b32_e32 v58, v118
	v_mov_b32_e32 v59, v120
	v_mov_b32_e32 v120, v119
	v_pk_fma_f32 v[96:97], v[60:61], v[76:77], v[64:65]
	v_pk_mul_f32 v[58:59], v[12:13], v[58:59] op_sel_hi:[0,1]
	v_pk_mul_f32 v[60:61], v[12:13], v[120:121] op_sel_hi:[0,1]
	v_pk_fma_f32 v[118:119], v[60:61], v[68:69], v[72:73]
	v_pk_fma_f32 v[120:121], v[58:59], v[66:67], v[70:71]
	ds_read_b128 v[58:61], v109 offset:6144
	ds_read_b128 v[62:65], v109 offset:14336
	ds_read_b128 v[66:69], v109 offset:7168
	ds_read_b128 v[70:73], v109 offset:15360
	v_mov_b32_e32 v54, v57
	v_pk_mul_f32 v[54:55], v[12:13], v[54:55] op_sel_hi:[0,1]
	v_pk_mul_f32 v[74:75], v[12:13], v[122:123] op_sel_hi:[0,1]
	v_pk_mul_f32 v[76:77], v[12:13], v[124:125] op_sel_hi:[0,1]
	v_pk_mul_f32 v[12:13], v[12:13], v[52:53] op_sel_hi:[0,1]
	s_waitcnt lgkmcnt(0)
; #define LAS __attribute__((address_space(3)))
; __device__ __forceinline__ unsigned pk_bf16(float lo, float hi) { unsigned r; asm volatile("v_cvt_pk_bf16_f32 %0, %1, %2" : "=v"(r) : "v"(lo), "v"(hi)); return r; }
; template <int MODE, bool INBF> ...
;     ...
;                 } else { u32x2* o = (u32x2*)(outb + (size_t)row * DM) + lane;
; #pragma unroll
;                     for (int j = 0; j < 8; ++j) { u32x2 w; w.x = pk_bf16(v[q][j].x, v[q][j].y); w.y = pk_bf16(v[q][j].z, v[q][j].w); o[64 * j] = w; } } }
;             if (MODE == 2) {
;                 float mine[RB];
; #pragma unroll
;                 for (int q = 0; q < RB; ++q) mine[q] = 0.f;
; #pragma unroll 2
;                 for (int hh = 0; hh < 16; ++hh) { float a[RB];
; #pragma unroll
;                     for (int q = 0; q < RB; ++q) a[q] = 0.f;
; #pragma unroll
;                     for (int j = 0; j < 8; ++j) { const f32x4 w = *(const LAS f32x4*)(wT + hh * WTP + 4 * (64 * j + lane));
; #pragma unroll
;                         for (int q = 0; q < RB; ++q) a[q] += (v[q][j].x * w.x + v[q][j].y * w.y) + (v[q][j].z * w.z + v[q][j].w * w.w); }
	v_pk_fma_f32 v[130:131], v[54:55], v[66:67], v[70:71]
	v_lshl_add_u64 v[52:53], v[22:23], 0, s[30:31]
	v_cvt_pk_bf16_f32 v54, v84, v85
	v_cvt_pk_bf16_f32 v55, v86, v87
	flat_store_dwordx2 v[52:53], v[54:55]
	v_cvt_pk_bf16_f32 v54, v88, v89
	v_cvt_pk_bf16_f32 v55, v90, v91
	flat_store_dwordx2 v[52:53], v[54:55] offset:512
	v_cvt_pk_bf16_f32 v54, v94, v95
	v_cvt_pk_bf16_f32 v55, v92, v93
	flat_store_dwordx2 v[52:53], v[54:55] offset:1024
	v_cvt_pk_bf16_f32 v54, v128, v129
	v_cvt_pk_bf16_f32 v55, v126, v127
	flat_store_dwordx2 v[52:53], v[54:55] offset:1536
	v_cvt_pk_bf16_f32 v54, v116, v117
	v_cvt_pk_bf16_f32 v55, v96, v97
	flat_store_dwordx2 v[52:53], v[54:55] offset:2048
	v_cvt_pk_bf16_f32 v54, v120, v121
	v_cvt_pk_bf16_f32 v55, v118, v119
	v_pk_fma_f32 v[122:123], v[76:77], v[60:61], v[64:65]
	v_pk_fma_f32 v[124:125], v[74:75], v[58:59], v[62:63]
	flat_store_dwordx2 v[52:53], v[54:55] offset:2560
	v_cvt_pk_bf16_f32 v54, v124, v125
	v_cvt_pk_bf16_f32 v55, v122, v123
	v_pk_fma_f32 v[12:13], v[12:13], v[68:69], v[72:73]
	flat_store_dwordx2 v[52:53], v[54:55] offset:3072
	v_cvt_pk_bf16_f32 v54, v130, v131
	v_cvt_pk_bf16_f32 v55, v12, v13
	flat_store_dwordx2 v[52:53], v[54:55] offset:3584
	v_mov_b32_e32 v52, v130
	v_mov_b32_e32 v53, v11
	v_mov_b32_e32 v54, v12
	v_mov_b32_e32 v55, v9
	v_mov_b32_e32 v56, v122
	v_mov_b32_e32 v57, v49
	v_mov_b32_e32 v58, v124
	v_mov_b32_e32 v59, v51
	v_mov_b32_e32 v60, v118
	v_mov_b32_e32 v61, v45
	v_mov_b32_e32 v62, v120
	v_mov_b32_e32 v63, v47
	v_mov_b32_e32 v64, v116
	v_mov_b32_e32 v65, v43
	v_mov_b32_e32 v66, v96
	v_mov_b32_e32 v67, v41
	v_mov_b32_e32 v68, v84
	v_mov_b32_e32 v69, v3
	v_mov_b32_e32 v70, v86
	v_mov_b32_e32 v71, v1
	v_mov_b32_e32 v72, v88
	v_mov_b32_e32 v73, v7
	v_mov_b32_e32 v74, v90
	v_mov_b32_e32 v75, v5
	v_mov_b32_e32 v76, v94
	v_mov_b32_e32 v77, v35
	v_mov_b32_e32 v78, v92
	v_mov_b32_e32 v79, v15
	v_mov_b32_e32 v80, v128
	v_mov_b32_e32 v81, v39
	v_mov_b32_e32 v82, v126
	v_mov_b32_e32 v83, v37
	v_pk_mov_b32 v[84:85], v[84:85], v[2:3] op_sel:[1,0]
	v_pk_mov_b32 v[86:87], v[86:87], v[0:1] op_sel:[1,0]
	v_pk_mov_b32 v[88:89], v[88:89], v[6:7] op_sel:[1,0]
	v_pk_mov_b32 v[90:91], v[90:91], v[4:5] op_sel:[1,0]
	v_pk_mov_b32 v[34:35], v[94:95], v[34:35] op_sel:[1,0]
	v_pk_mov_b32 v[92:93], v[92:93], v[14:15] op_sel:[1,0]
	v_pk_mov_b32 v[38:39], v[128:129], v[38:39] op_sel:[1,0]
	v_pk_mov_b32 v[36:37], v[126:127], v[36:37] op_sel:[1,0]
	v_pk_mov_b32 v[42:43], v[116:117], v[42:43] op_sel:[1,0]
	v_pk_mov_b32 v[40:41], v[96:97], v[40:41] op_sel:[1,0]
	v_pk_mov_b32 v[46:47], v[120:121], v[46:47] op_sel:[1,0]
	v_pk_mov_b32 v[44:45], v[118:119], v[44:45] op_sel:[1,0]
	v_pk_mov_b32 v[50:51], v[124:125], v[50:51] op_sel:[1,0]
	v_pk_mov_b32 v[48:49], v[122:123], v[48:49] op_sel:[1,0]
	v_pk_mov_b32 v[94:95], v[130:131], v[10:11] op_sel:[1,0]
	v_pk_mov_b32 v[96:97], v[12:13], v[8:9] op_sel:[1,0]
	v_mov_b32_e32 v117, v110
	v_mov_b32_e32 v118, v29
	v_mov_b32_e32 v116, 0
.LBB0_641:
	ds_read_b128 v[12:15], v117
	ds_read_b128 v[8:11], v117 offset:1024
	ds_read_b128 v[4:7], v117 offset:2048
	ds_read_b128 v[0:3], v117 offset:3072
	ds_read_b128 v[120:123], v117 offset:4096
	ds_read_b128 v[124:127], v117 offset:5120
	ds_read_b128 v[128:131], v117 offset:6144
	ds_read_b128 v[132:135], v117 offset:7168
	s_waitcnt lgkmcnt(0)
	v_pk_mul_f32 v[168:169], v[68:69], v[12:13]
	v_pk_mul_f32 v[170:171], v[70:71], v[14:15]
	ds_read_b128 v[136:139], v117 offset:8208
	ds_read_b128 v[140:143], v117 offset:9232
	ds_read_b128 v[144:147], v117 offset:10256
	ds_read_b128 v[148:151], v117 offset:11280
	ds_read_b128 v[152:155], v117 offset:12304
	ds_read_b128 v[156:159], v117 offset:13328
	ds_read_b128 v[160:163], v117 offset:14352
	ds_read_b128 v[164:167], v117 offset:15376
	v_pk_mul_f32 v[172:173], v[72:73], v[8:9]
	v_pk_mul_f32 v[174:175], v[74:75], v[10:11]
	v_pk_mul_f32 v[180:181], v[80:81], v[0:1]
	v_pk_mul_f32 v[182:183], v[82:83], v[2:3]
	v_pk_mul_f32 v[184:185], v[64:65], v[120:121]
	v_pk_mul_f32 v[186:187], v[66:67], v[122:123]
	s_waitcnt lgkmcnt(0)
	v_pk_mul_f32 v[202:203], v[68:69], v[136:137]
	v_pk_mul_f32 v[204:205], v[70:71], v[138:139]
	v_pk_fma_f32 v[12:13], v[84:85], v[12:13], v[168:169] op_sel:[0,1,0] op_sel_hi:[1,0,1]
	v_pk_fma_f32 v[14:15], v[86:87], v[14:15], v[170:171] op_sel:[0,1,0] op_sel_hi:[1,0,1]
	v_pk_mul_f32 v[176:177], v[76:77], v[4:5]
	v_pk_mul_f32 v[178:179], v[78:79], v[6:7]
	v_pk_mul_f32 v[206:207], v[72:73], v[140:141]
	v_pk_mul_f32 v[208:209], v[74:75], v[142:143]
	v_pk_fma_f32 v[8:9], v[88:89], v[8:9], v[172:173] op_sel:[0,1,0] op_sel_hi:[1,0,1]
	v_pk_fma_f32 v[10:11], v[90:91], v[10:11], v[174:175] op_sel:[0,1,0] op_sel_hi:[1,0,1]
	v_pk_fma_f32 v[0:1], v[38:39], v[0:1], v[180:181] op_sel:[0,1,0] op_sel_hi:[1,0,1]
	v_pk_fma_f32 v[2:3], v[36:37], v[2:3], v[182:183] op_sel:[0,1,0] op_sel_hi:[1,0,1]
	v_pk_fma_f32 v[120:121], v[42:43], v[120:121], v[184:185] op_sel:[0,1,0] op_sel_hi:[1,0,1]
	v_pk_fma_f32 v[122:123], v[40:41], v[122:123], v[186:187] op_sel:[0,1,0] op_sel_hi:[1,0,1]
	v_pk_fma_f32 v[136:137], v[84:85], v[136:137], v[202:203] op_sel:[0,1,0] op_sel_hi:[1,0,1]
	v_pk_fma_f32 v[138:139], v[86:87], v[138:139], v[204:205] op_sel:[0,1,0] op_sel_hi:[1,0,1]
	v_pk_add_f32 v[12:13], v[12:13], v[14:15]
	v_pk_mul_f32 v[188:189], v[62:63], v[124:125]
	v_pk_mul_f32 v[190:191], v[60:61], v[126:127]
	v_pk_mul_f32 v[210:211], v[76:77], v[144:145]
	v_pk_mul_f32 v[212:213], v[78:79], v[146:147]
	v_pk_fma_f32 v[4:5], v[34:35], v[4:5], v[176:177] op_sel:[0,1,0] op_sel_hi:[1,0,1]
	v_pk_fma_f32 v[6:7], v[92:93], v[6:7], v[178:179] op_sel:[0,1,0] op_sel_hi:[1,0,1]
	v_pk_fma_f32 v[140:141], v[88:89], v[140:141], v[206:207] op_sel:[0,1,0] op_sel_hi:[1,0,1]
; #define LAS __attribute__((address_space(3)))
; template <int MODE, bool INBF> ...
;     ...
;                 for (int hh = 0; hh < 16; ++hh) { float a[RB];
; #pragma unroll
;                     for (int q = 0; q < RB; ++q) a[q] = 0.f;
; #pragma unroll
;                     for (int j = 0; j < 8; ++j) { const f32x4 w = *(const LAS f32x4*)(wT + hh * WTP + 4 * (64 * j + lane));
; #pragma unroll
;                         for (int q = 0; q < RB; ++q) a[q] += (v[q][j].x * w.x + v[q][j].y * w.y) + (v[q][j].z * w.z + v[q][j].w * w.w); }
; #pragma unroll
;                     for (int q = 0; q < RB; ++q) { const float s = wave_sum(a[q]); mine[q] = (lane == hh) ? s : mine[q]; } }
	v_pk_fma_f32 v[142:143], v[90:91], v[142:143], v[208:209] op_sel:[0,1,0] op_sel_hi:[1,0,1]
	v_pk_add_f32 v[8:9], v[8:9], v[10:11]
	v_pk_add_f32 v[0:1], v[0:1], v[2:3]
	v_pk_add_f32 v[2:3], v[120:121], v[122:123]
	v_pk_add_f32 v[120:121], v[136:137], v[138:139]
	v_pk_add_f32 v[12:13], v[12:13], 0 op_sel_hi:[1,0]
	v_pk_mul_f32 v[214:215], v[80:81], v[148:149]
	v_pk_mul_f32 v[216:217], v[82:83], v[150:151]
	v_pk_fma_f32 v[124:125], v[46:47], v[124:125], v[188:189] op_sel:[0,1,0] op_sel_hi:[1,0,1]
	v_pk_fma_f32 v[126:127], v[44:45], v[126:127], v[190:191] op_sel:[0,1,0] op_sel_hi:[1,0,1]
	v_pk_fma_f32 v[144:145], v[34:35], v[144:145], v[210:211] op_sel:[0,1,0] op_sel_hi:[1,0,1]
	v_pk_fma_f32 v[146:147], v[92:93], v[146:147], v[212:213] op_sel:[0,1,0] op_sel_hi:[1,0,1]
	v_pk_add_f32 v[4:5], v[4:5], v[6:7]
	v_pk_add_f32 v[122:123], v[140:141], v[142:143]
	v_pk_add_f32 v[120:121], v[120:121], 0 op_sel_hi:[1,0]
	v_pk_add_f32 v[8:9], v[12:13], v[8:9]
	v_pk_mul_f32 v[194:195], v[58:59], v[128:129]
	v_pk_mul_f32 v[196:197], v[56:57], v[130:131]
	v_pk_mul_f32 v[218:219], v[64:65], v[152:153]
	v_pk_mul_f32 v[220:221], v[66:67], v[154:155]
	v_pk_fma_f32 v[148:149], v[38:39], v[148:149], v[214:215] op_sel:[0,1,0] op_sel_hi:[1,0,1]
	v_pk_fma_f32 v[150:151], v[36:37], v[150:151], v[216:217] op_sel:[0,1,0] op_sel_hi:[1,0,1]
	v_pk_add_f32 v[6:7], v[124:125], v[126:127]
	v_pk_add_f32 v[124:125], v[144:145], v[146:147]
	v_pk_add_f32 v[12:13], v[120:121], v[122:123]
	v_pk_add_f32 v[4:5], v[8:9], v[4:5]
	v_pk_mul_f32 v[222:223], v[62:63], v[156:157]
	v_pk_mul_f32 v[224:225], v[60:61], v[158:159]
	v_pk_fma_f32 v[128:129], v[50:51], v[128:129], v[194:195] op_sel:[0,1,0] op_sel_hi:[1,0,1]
	v_pk_fma_f32 v[130:131], v[48:49], v[130:131], v[196:197] op_sel:[0,1,0] op_sel_hi:[1,0,1]
	v_pk_fma_f32 v[152:153], v[42:43], v[152:153], v[218:219] op_sel:[0,1,0] op_sel_hi:[1,0,1]
	v_pk_fma_f32 v[154:155], v[40:41], v[154:155], v[220:221] op_sel:[0,1,0] op_sel_hi:[1,0,1]
	v_pk_add_f32 v[126:127], v[148:149], v[150:151]
	v_pk_add_f32 v[8:9], v[12:13], v[124:125]
	v_pk_add_f32 v[0:1], v[4:5], v[0:1]
	v_pk_mul_f32 v[198:199], v[52:53], v[132:133]
	v_pk_mul_f32 v[200:201], v[54:55], v[134:135]
	v_pk_mul_f32 v[226:227], v[58:59], v[160:161]
	v_pk_mul_f32 v[228:229], v[56:57], v[162:163]
	v_pk_fma_f32 v[156:157], v[46:47], v[156:157], v[222:223] op_sel:[0,1,0] op_sel_hi:[1,0,1]
	v_pk_fma_f32 v[158:159], v[44:45], v[158:159], v[224:225] op_sel:[0,1,0] op_sel_hi:[1,0,1]
	v_pk_add_f32 v[10:11], v[128:129], v[130:131]
	v_pk_add_f32 v[128:129], v[152:153], v[154:155]
	v_pk_add_f32 v[4:5], v[8:9], v[126:127]
	v_pk_add_f32 v[0:1], v[0:1], v[2:3]
	v_pk_mul_f32 v[230:231], v[52:53], v[164:165]
	v_pk_mul_f32 v[232:233], v[54:55], v[166:167]
	v_pk_fma_f32 v[132:133], v[94:95], v[132:133], v[198:199] op_sel:[0,1,0] op_sel_hi:[1,0,1]
	v_pk_fma_f32 v[134:135], v[96:97], v[134:135], v[200:201] op_sel:[0,1,0] op_sel_hi:[1,0,1]
	v_pk_fma_f32 v[160:161], v[50:51], v[160:161], v[226:227] op_sel:[0,1,0] op_sel_hi:[1,0,1]
	v_pk_fma_f32 v[162:163], v[48:49], v[162:163], v[228:229] op_sel:[0,1,0] op_sel_hi:[1,0,1]
	v_pk_add_f32 v[130:131], v[156:157], v[158:159]
	v_pk_add_f32 v[2:3], v[4:5], v[128:129]
	v_pk_add_f32 v[0:1], v[0:1], v[6:7]
	v_pk_fma_f32 v[164:165], v[94:95], v[164:165], v[230:231] op_sel:[0,1,0] op_sel_hi:[1,0,1]
	v_pk_fma_f32 v[166:167], v[96:97], v[166:167], v[232:233] op_sel:[0,1,0] op_sel_hi:[1,0,1]
	v_pk_add_f32 v[14:15], v[132:133], v[134:135]
	v_pk_add_f32 v[132:133], v[160:161], v[162:163]
	v_pk_add_f32 v[2:3], v[2:3], v[130:131]
	v_pk_add_f32 v[0:1], v[0:1], v[10:11]
	v_pk_add_f32 v[134:135], v[164:165], v[166:167]
	v_pk_add_f32 v[2:3], v[2:3], v[132:133]
	v_pk_add_f32 v[0:1], v[0:1], v[14:15]
	v_pk_add_f32 v[2:3], v[2:3], v[134:135]
	s_nop 0
	s_nop 0
	s_nop 0
	s_nop 0
	s_or_b32 s19, s18, 1
	v_cmp_eq_u32_e32 vcc, 0, v118
	s_waitcnt lgkmcnt(0)
	s_nop 1
	v_add_f32_dpp v0, v0, v0 quad_perm:[1,0,3,2] row_mask:0xf bank_mask:0xf
	v_add_f32_dpp v1, v1, v1 quad_perm:[1,0,3,2] row_mask:0xf bank_mask:0xf
	s_nop 0
	s_nop 1
	v_add_f32_dpp v2, v2, v2 quad_perm:[1,0,3,2] row_mask:0xf bank_mask:0xf
	v_add_f32_dpp v3, v3, v3 quad_perm:[1,0,3,2] row_mask:0xf bank_mask:0xf
	s_nop 0
	s_nop 0
	s_nop 0
	s_add_i32 s18, s18, 2
	v_add_u32_e32 v117, 0x4020, v117
	s_waitcnt lgkmcnt(0)
	s_nop 1
	v_add_f32_dpp v0, v0, v0 quad_perm:[2,3,0,1] row_mask:0xf bank_mask:0xf
	v_add_f32_dpp v1, v1, v1 quad_perm:[2,3,0,1] row_mask:0xf bank_mask:0xf
	s_nop 0
	s_nop 1
	v_add_f32_dpp v2, v2, v2 quad_perm:[2,3,0,1] row_mask:0xf bank_mask:0xf
	v_add_f32_dpp v3, v3, v3 quad_perm:[2,3,0,1] row_mask:0xf bank_mask:0xf
	s_nop 0
	s_nop 0
	s_nop 0
	s_cmp_lg_u32 s18, 16
	v_add_u32_e32 v118, -2, v118
	s_waitcnt lgkmcnt(0)
	s_nop 1
	v_add_f32_dpp v0, v0, v0 row_half_mirror row_mask:0xf bank_mask:0xf
	v_add_f32_dpp v1, v1, v1 row_half_mirror row_mask:0xf bank_mask:0xf
	s_nop 0
	s_nop 1
	v_add_f32_dpp v2, v2, v2 row_half_mirror row_mask:0xf bank_mask:0xf
	v_add_f32_dpp v3, v3, v3 row_half_mirror row_mask:0xf bank_mask:0xf
	s_nop 0
	s_nop 0
	s_nop 0
	s_waitcnt lgkmcnt(0)
	s_nop 1
	v_add_f32_dpp v0, v0, v0 row_mirror row_mask:0xf bank_mask:0xf
	v_add_f32_dpp v1, v1, v1 row_mirror row_mask:0xf bank_mask:0xf
	v_mov_b32_e32 v5, v1
	s_nop 1
	v_add_f32_dpp v2, v2, v2 row_mirror row_mask:0xf bank_mask:0xf
	v_add_f32_dpp v3, v3, v3 row_mirror row_mask:0xf bank_mask:0xf
	v_mov_b32_e32 v4, v0
	v_mov_b32_e32 v7, v3
	v_mov_b32_e32 v6, v2
	s_waitcnt lgkmcnt(0)
	s_nop 1
	v_permlane16_swap_b32_e32 v0, v4
	v_permlane16_swap_b32_e32 v1, v5
	v_pk_add_f32 v[0:1], v[0:1], v[4:5]
	v_mov_b32_e32 v5, v1
	s_nop 1
	v_permlane16_swap_b32_e32 v2, v6
	v_permlane16_swap_b32_e32 v3, v7
	v_pk_add_f32 v[2:3], v[2:3], v[6:7]
	v_mov_b32_e32 v4, v0
	v_mov_b32_e32 v7, v3
	v_mov_b32_e32 v6, v2
	s_waitcnt lgkmcnt(0)
	s_nop 1
	v_permlane32_swap_b32_e32 v0, v4
	v_permlane32_swap_b32_e32 v1, v5
	v_pk_add_f32 v[0:1], v[0:1], v[4:5]
	s_nop 0
	v_cndmask_b32_e32 v1, v116, v1, vcc
	s_nop 1
	v_permlane32_swap_b32_e32 v2, v6
	v_permlane32_swap_b32_e32 v3, v7
	v_pk_add_f32 v[2:3], v[2:3], v[6:7]
	v_cndmask_b32_e32 v0, v18, v0, vcc
	v_cmp_eq_u32_e32 vcc, s19, v29
	s_nop 1
	v_cndmask_b32_e32 v18, v0, v2, vcc
	v_cndmask_b32_e32 v116, v1, v3, vcc
	s_cbranch_scc1 .LBB0_641
; template <int MODE, bool INBF> ...
;     ...
; #pragma unroll
;                 for (int q = 0; q < RB; ++q) if (lane < 16) { const int row = blk * 64 + wave + 8 * (i0 + q); const float xx = mine[q] + bfv[lane]; const float lf = fminf(xx, 0.f) - log1pf(expf(-fabsf(xx))); logf_out[(size_t)row * 16 + lane] = lf; }
	s_and_saveexec_b64 s[18:19], s[8:9]
	s_cbranch_execz .LBB0_639
	flat_load_dword v2, v[24:25]
	s_lshl_b64 s[28:29], s[28:29], 6
	v_lshl_add_u64 v[0:1], v[26:27], 0, s[28:29]
	s_lshl_b64 s[26:27], s[26:27], 6
	s_waitcnt vmcnt(0) lgkmcnt(0)
	v_add_f32_e32 v3, v116, v2
	v_add_f32_e32 v2, v18, v2
	v_mul_f32_e64 v4, |v3|, s52
	v_mul_f32_e64 v5, |v2|, s52
	v_fma_f32 v6, |v3|, s52, -v4
	v_rndne_f32_e32 v7, v4
	v_fma_f32 v8, |v2|, s52, -v5
	v_rndne_f32_e32 v9, v5
	v_fma_f32 v6, |v3|, s53, v6
	v_sub_f32_e32 v4, v4, v7
	v_fma_f32 v8, |v2|, s53, v8
	v_sub_f32_e32 v5, v5, v9
	v_add_f32_e32 v4, v4, v6
	v_cvt_i32_f32_e32 v7, v7
	v_add_f32_e32 v5, v5, v8
	v_exp_f32_e32 v4, v4
	v_cvt_i32_f32_e32 v9, v9
	v_exp_f32_e32 v5, v5
	v_cmp_ngt_f32_e64 vcc, |v3|, s54
	v_ldexp_f32 v4, v4, v7
	v_min_f32_e32 v6, 0, v3
	v_ldexp_f32 v5, v5, v9
	v_cndmask_b32_e32 v4, 0, v4, vcc
	v_cmp_ngt_f32_e64 vcc, |v2|, s54
	v_min_f32_e32 v8, 0, v2
	s_nop 0
	v_cndmask_b32_e32 v5, 0, v5, vcc
	v_cmp_nlt_f32_e64 vcc, |v3|, s55
	s_nop 1
	v_cndmask_b32_e32 v7, v115, v4, vcc
	v_cmp_nlt_f32_e64 vcc, |v2|, s55
	v_add_f32_e32 v10, 1.0, v7
	v_add_f32_e32 v12, -1.0, v10
	v_cndmask_b32_e32 v9, v115, v5, vcc
	v_add_f32_e32 v11, 1.0, v9
	v_frexp_mant_f32_e32 v13, v10
	v_cvt_f64_f32_e32 v[2:3], v10
	v_cvt_f64_f32_e32 v[4:5], v11
	v_sub_f32_e32 v18, v12, v10
	v_frexp_exp_i32_f64_e32 v2, v[2:3]
	v_cmp_gt_f32_e32 vcc, s57, v13
	v_sub_f32_e32 v12, v7, v12
	v_frexp_exp_i32_f64_e32 v4, v[4:5]
	v_add_f32_e32 v5, 1.0, v18
	v_subbrev_co_u32_e32 v2, vcc, 0, v2, vcc
	v_add_f32_e32 v14, -1.0, v11
	v_add_f32_e32 v5, v12, v5
	v_sub_u32_e32 v12, 0, v2
	v_sub_f32_e32 v3, v14, v11
	v_cvt_f32_i32_e32 v2, v2
	v_ldexp_f32 v10, v10, v12
	v_frexp_mant_f32_e32 v15, v11
	v_sub_f32_e32 v14, v9, v14
	v_add_f32_e32 v3, 1.0, v3
	v_ldexp_f32 v5, v5, v12
	v_add_f32_e32 v12, -1.0, v10
	v_add_f32_e32 v13, 1.0, v10
	v_cmp_gt_f32_e32 vcc, s57, v15
	v_add_f32_e32 v3, v14, v3
	v_add_f32_e32 v14, 1.0, v12
	v_add_f32_e32 v15, -1.0, v13
	v_sub_f32_e32 v14, v10, v14
	v_sub_f32_e32 v10, v10, v15
	v_mul_f32_e32 v15, 0x3f317218, v2
	v_add_f32_e32 v14, v5, v14
	v_add_f32_e32 v5, v5, v10
	v_fma_f32 v10, v2, s58, -v15
	v_add_f32_e32 v18, v12, v14
	v_add_f32_e32 v34, v13, v5
	v_fmac_f32_e32 v10, 0xb102e308, v2
	v_sub_f32_e32 v2, v12, v18
	v_sub_f32_e32 v12, v13, v34
	v_rcp_f32_e32 v13, v34
	v_add_f32_e32 v35, v15, v10
	v_add_f32_e32 v5, v5, v12
	v_sub_f32_e32 v12, v35, v15
	v_sub_f32_e32 v10, v10, v12
	v_mul_f32_e32 v12, v18, v13
	v_add_f32_e32 v2, v14, v2
	v_mul_f32_e32 v14, v34, v12
	v_fma_f32 v15, v12, v34, -v14
	v_fmac_f32_e32 v15, v12, v5
	v_add_f32_e32 v36, v14, v15
	v_sub_f32_e32 v37, v18, v36
	v_sub_f32_e32 v14, v36, v14
	v_sub_f32_e32 v18, v18, v37
	v_sub_f32_e32 v14, v14, v15
	v_sub_f32_e32 v15, v18, v36
	v_add_f32_e32 v2, v2, v15
	v_add_f32_e32 v2, v14, v2
	v_add_f32_e32 v14, v37, v2
	v_mul_f32_e32 v15, v13, v14
	v_sub_f32_e32 v18, v37, v14
	v_mul_f32_e32 v36, v34, v15
	v_add_f32_e32 v2, v2, v18
	v_add_f32_e32 v18, v12, v15
	v_fma_f32 v34, v15, v34, -v36
	v_sub_f32_e32 v12, v18, v12
	v_fmac_f32_e32 v34, v15, v5
	v_sub_f32_e32 v5, v15, v12
	v_add_f32_e32 v12, v36, v34
	v_sub_f32_e32 v15, v12, v36
	v_sub_f32_e32 v36, v14, v12
	v_sub_f32_e32 v14, v14, v36
	v_sub_f32_e32 v12, v14, v12
	v_sub_f32_e32 v15, v15, v34
	v_add_f32_e32 v2, v2, v12
	v_add_f32_e32 v2, v15, v2
	v_add_f32_e32 v2, v36, v2
	v_mul_f32_e32 v2, v13, v2
	v_add_f32_e32 v2, v5, v2
	v_add_f32_e32 v5, v18, v2
	v_mul_f32_e32 v12, v5, v5
	v_fmamk_f32 v15, v12, 0x3e9b6dac, v113
	v_sub_f32_e32 v13, v5, v18
	v_ldexp_f32 v14, v5, 1
	v_mul_f32_e32 v5, v5, v12
	v_fmaak_f32 v12, v12, v15, 0x3f2aaada
	v_mul_f32_e32 v5, v5, v12
	v_add_f32_e32 v12, v14, v5
	v_sub_f32_e32 v2, v2, v13
; template <int MODE, bool INBF> ...
;     ...
;                 for (int q = 0; q < RB; ++q) if (lane < 16) { const int row = blk * 64 + wave + 8 * (i0 + q); const float xx = mine[q] + bfv[lane]; const float lf = fminf(xx, 0.f) - log1pf(expf(-fabsf(xx))); logf_out[(size_t)row * 16 + lane] = lf; }
	v_sub_f32_e32 v13, v12, v14
	v_ldexp_f32 v2, v2, 1
	v_sub_f32_e32 v5, v5, v13
	v_add_f32_e32 v2, v2, v5
	v_add_f32_e32 v5, v12, v2
	v_sub_f32_e32 v12, v5, v12
	v_add_f32_e32 v13, v35, v5
	v_sub_f32_e32 v2, v2, v12
	v_sub_f32_e32 v12, v13, v35
	v_sub_f32_e32 v14, v13, v12
	v_sub_f32_e32 v5, v5, v12
	v_add_f32_e32 v12, v10, v2
	v_sub_f32_e32 v14, v35, v14
	v_sub_f32_e32 v15, v12, v10
	v_add_f32_e32 v5, v5, v14
	v_sub_f32_e32 v14, v12, v15
	v_sub_f32_e32 v2, v2, v15
	v_sub_f32_e32 v10, v10, v14
	v_add_f32_e32 v5, v12, v5
	v_add_f32_e32 v2, v2, v10
	v_add_f32_e32 v10, v13, v5
	v_sub_f32_e32 v12, v10, v13
	v_sub_f32_e32 v5, v5, v12
	v_subbrev_co_u32_e32 v4, vcc, 0, v4, vcc
	v_add_f32_e32 v2, v2, v5
	v_add_f32_e32 v2, v10, v2
	v_cmp_neq_f32_e32 vcc, s56, v7
	s_nop 1
	v_cndmask_b32_e32 v2, v115, v2, vcc
	v_cmp_lt_f32_e64 vcc, |v7|, s59
	s_nop 1
	v_cndmask_b32_e32 v2, v2, v7, vcc
	v_sub_f32_e32 v2, v6, v2
	flat_store_dword v[0:1], v2
	v_sub_u32_e32 v0, 0, v4
	v_ldexp_f32 v1, v11, v0
	v_add_f32_e32 v2, -1.0, v1
	v_add_f32_e32 v6, 1.0, v1
	v_ldexp_f32 v0, v3, v0
	v_add_f32_e32 v3, 1.0, v2
	v_add_f32_e32 v7, -1.0, v6
	v_sub_f32_e32 v3, v1, v3
	v_sub_f32_e32 v1, v1, v7
	v_add_f32_e32 v3, v0, v3
	v_add_f32_e32 v0, v0, v1
	v_add_f32_e32 v1, v6, v0
	v_rcp_f32_e32 v7, v1
	v_add_f32_e32 v5, v2, v3
	v_sub_f32_e32 v2, v2, v5
	v_add_f32_e32 v2, v3, v2
	v_sub_f32_e32 v3, v6, v1
	v_add_f32_e32 v0, v0, v3
	v_mul_f32_e32 v3, v5, v7
	v_mul_f32_e32 v6, v1, v3
	v_fma_f32 v10, v3, v1, -v6
	v_fmac_f32_e32 v10, v3, v0
	v_add_f32_e32 v11, v6, v10
	v_sub_f32_e32 v12, v5, v11
	v_sub_f32_e32 v5, v5, v12
	v_sub_f32_e32 v6, v11, v6
	v_sub_f32_e32 v5, v5, v11
	v_add_f32_e32 v2, v2, v5
	v_sub_f32_e32 v5, v6, v10
	v_add_f32_e32 v2, v5, v2
	v_add_f32_e32 v5, v12, v2
	v_mul_f32_e32 v6, v7, v5
	v_mul_f32_e32 v10, v1, v6
	v_fma_f32 v1, v6, v1, -v10
	v_fmac_f32_e32 v1, v6, v0
	v_sub_f32_e32 v0, v12, v5
	v_add_f32_e32 v0, v2, v0
	v_add_f32_e32 v2, v10, v1
	v_sub_f32_e32 v11, v5, v2
	v_sub_f32_e32 v5, v5, v11
	v_sub_f32_e32 v10, v2, v10
	v_sub_f32_e32 v2, v5, v2
	v_add_f32_e32 v0, v0, v2
	v_sub_f32_e32 v1, v10, v1
	v_add_f32_e32 v0, v1, v0
	v_add_f32_e32 v1, v3, v6
	v_sub_f32_e32 v2, v1, v3
	v_cvt_f32_i32_e32 v3, v4
	v_add_f32_e32 v0, v11, v0
	v_mul_f32_e32 v0, v7, v0
	v_sub_f32_e32 v2, v6, v2
	v_add_f32_e32 v0, v2, v0
	v_mul_f32_e32 v6, 0x3f317218, v3
	v_add_f32_e32 v2, v1, v0
	v_fma_f32 v7, v3, s58, -v6
	v_mul_f32_e32 v4, v2, v2
	v_fmac_f32_e32 v7, 0xb102e308, v3
	v_sub_f32_e32 v1, v2, v1
	v_fmamk_f32 v5, v4, 0x3e9b6dac, v113
	v_sub_f32_e32 v0, v0, v1
	v_add_f32_e32 v1, v6, v7
	v_fmaak_f32 v5, v4, v5, 0x3f2aaada
	v_sub_f32_e32 v3, v1, v6
	v_ldexp_f32 v6, v2, 1
	v_mul_f32_e32 v2, v2, v4
	v_mul_f32_e32 v2, v2, v5
	v_add_f32_e32 v4, v6, v2
	v_sub_f32_e32 v5, v4, v6
	v_ldexp_f32 v0, v0, 1
	v_sub_f32_e32 v2, v2, v5
	v_add_f32_e32 v0, v0, v2
	v_add_f32_e32 v2, v4, v0
	v_sub_f32_e32 v4, v2, v4
	v_sub_f32_e32 v0, v0, v4
	v_add_f32_e32 v4, v1, v2
	v_sub_f32_e32 v5, v4, v1
	v_sub_f32_e32 v6, v4, v5
	v_sub_f32_e32 v3, v7, v3
	v_sub_f32_e32 v1, v1, v6
	v_sub_f32_e32 v2, v2, v5
	v_add_f32_e32 v1, v2, v1
	v_add_f32_e32 v2, v3, v0
	v_sub_f32_e32 v5, v2, v3
	v_sub_f32_e32 v6, v2, v5
	v_add_f32_e32 v1, v2, v1
	v_sub_f32_e32 v3, v3, v6
	v_sub_f32_e32 v0, v0, v5
	v_add_f32_e32 v2, v4, v1
	v_add_f32_e32 v0, v0, v3
	v_sub_f32_e32 v3, v2, v4
	v_sub_f32_e32 v1, v1, v3
	v_add_f32_e32 v0, v0, v1
	v_add_f32_e32 v0, v2, v0
	v_cmp_neq_f32_e32 vcc, s56, v9
	s_nop 1
	v_cndmask_b32_e32 v0, v115, v0, vcc
	v_cmp_lt_f32_e64 vcc, |v9|, s59
	s_nop 1
	v_cndmask_b32_e32 v0, v0, v9, vcc
	v_sub_f32_e32 v2, v8, v0
	v_lshl_add_u64 v[0:1], v[26:27], 0, s[26:27]
	flat_store_dword v[0:1], v2
	s_branch .LBB0_639

; #define PG8_STAGE(bufoff, gbase, voff) do { _Pragma("unroll") for (int _i = 0; _i < 2; ++_i) \
;         __builtin_amdgcn_global_load_lds((const unsigned*)((const char*)(gbase) + (voff)[_i]), (PG8_LAS unsigned*)(lds + (bufoff) + ldsw + _i * 8192), 16, 0, 0); } while (0)
; #define PG8_WAIT_V(n) asm volatile("s_waitcnt vmcnt(" #n ")" ::: "memory")
; #define PG8_BAR __builtin_amdgcn_s_barrier()
; template <class Epi, class Sched, bool ALIGN_EPI = false, bool SP2 = false>
; __device__ __forceinline__ void gemm_phase(PG8_LAS unsigned char* lds, const Gemm g, const Sched& S, const Epi& E) {
;     ...
;     if constexpr (SP2) {
;         PG8_STAGE(PG8_SB(0, 0), cB, voffB); PG8_STAGE(PG8_SB(0, 1), cB + hstep, voffB); PG8_STAGE(PG8_SA(0, 0), cA, voffA); PG8_STAGE(PG8_SA(0, 1), cA + hstep, voffA);
;         if (wr == 1) PG8_BAR;
;         PG8_WAIT_V(2); PG8_BAR;
;         PG8_STAGE(PG8_SB(1, 0), cB + kstep, voffB); PG8_STAGE(PG8_SA(1, 0), cA + kstep, voffA); PG8_STAGE(PG8_SB(1, 1), cB + hstep + kstep, voffB);
;         PG8_WAIT_V(6); PG8_BAR;
.LBB0_720:
	s_lshl_b32 s8, s8, 5
	s_and_b32 s8, s8, 0x60
	s_lshl_b32 s16, s7, 13
	s_lshl_b32 s17, s8, 7
	s_add_u32 s48, s48, 0x10400000
	s_mov_b64 s[12:13], 0x80
	s_addc_u32 s49, s49, 0
	s_add_i32 m0, s25, 0x18000
	v_lshl_add_u64 v[6:7], v[6:7], 0, s[12:13]
	global_load_lds_dwordx4 v[6:7], off
	v_lshl_add_u64 v[4:5], v[4:5], 0, s[12:13]
	s_add_i32 m0, s25, 0x1a000
	s_add_i32 s59, s25, 0x8000
	s_add_i32 s60, s25, 0xa000
	global_load_lds_dwordx4 v[4:5], off
	v_lshl_add_u64 v[0:1], v[0:1], 0, s[12:13]
	s_mov_b32 m0, s59
	s_add_u32 s14, s28, 0x80080
	global_load_lds_dwordx4 v[0:1], off
	v_lshl_add_u64 v[0:1], v[2:3], 0, s[12:13]
	s_mov_b32 m0, s60
	s_addc_u32 s15, s29, 0
	global_load_lds_dwordx4 v[0:1], off
	s_add_i32 m0, s25, 0x1c000
	v_lshl_add_u64 v[0:1], s[14:15], 0, v[132:133]
	global_load_lds_dwordx4 v[0:1], off
	v_lshl_add_u64 v[0:1], s[14:15], 0, v[128:129]
	s_add_i32 m0, s25, 0x1e000
	s_cmpk_lt_u32 s6, 0x100
	global_load_lds_dwordx4 v[0:1], off
	s_waitcnt vmcnt(8)
	s_barrier
	v_lshrrev_b32_e32 v0, 1, v9
	v_and_b32_e32 v0, 24, v0
	v_and_b32_e32 v1, 15, v9
	v_lshlrev_b32_e32 v2, 1, v0
	v_lshl_or_b32 v148, s7, 6, v1
	v_lshl_or_b32 v1, v1, 6, v2
	v_lshlrev_b32_e32 v2, 2, v9
	v_and_b32_e32 v2, 32, v2
	v_bitop3_b32 v3, v1, s16, v2 bitop3:0xde
	v_bitop3_b32 v149, v1, s17, v2 bitop3:0xde
	v_lshlrev_b32_e32 v1, 15, v8
	v_and_b32_e32 v1, 0xffff0000, v1
	v_lshl_add_u32 v1, v10, 12, v1
	v_and_b32_e32 v2, 1, v8
	v_lshl_or_b32 v1, v2, 6, v1
	v_lshl_add_u32 v138, v11, 1, v1
	v_lshlrev_b32_e32 v1, 15, v13
	v_and_b32_e32 v1, 0xffff0000, v1
	s_waitcnt vmcnt(6)
	v_lshl_add_u32 v1, v12, 12, v1
	v_and_b32_e32 v2, 1, v13
	s_cselect_b64 s[14:15], -1, 0
	v_lshl_or_b32 v1, v2, 6, v1
	s_add_i32 s64, 0, 0x10000
	s_add_i32 s65, 0, 0x14000
	s_mov_b32 s61, 0x8000
	s_mov_b32 s62, 0xa000
	s_ashr_i32 s63, s3, 31
	v_mov_b32_e32 v139, v137
	v_lshl_add_u32 v140, v14, 1, v1
	v_mov_b32_e32 v141, v137
	v_mov_b64_e32 v[142:143], 0x600
	v_mov_b64_e32 v[144:145], 0x5ff
	v_add_u32_e32 v150, s64, v149
	v_add_u32_e32 v151, s65, v149
	v_add_u32_e32 v152, 0, v3
	s_lshl_b32 s8, s8, 1
	v_lshlrev_b32_e32 v136, 1, v0
	s_mov_b32 s66, 0x100000
	s_movk_i32 s67, 0x1000
	s_mov_b32 s68, 0x101000
	s_mov_b32 s69, 0x102000
	s_movk_i32 s70, 0x3000
	s_mov_b32 s71, 0x103000
	s_mov_b32 s72, 0x108000
	s_mov_b32 s73, 0x9000
	s_mov_b32 s74, 0x109000
	s_mov_b32 s75, 0x10a000
	s_mov_b32 s76, 0xb000
	s_mov_b32 s77, s9
	s_barrier
	s_branch .LBB0_723

; #define PG8_STAGE(bufoff, gbase, voff) do { _Pragma("unroll") for (int _i = 0; _i < 2; ++_i) \
;         __builtin_amdgcn_global_load_lds((const unsigned*)((const char*)(gbase) + (voff)[_i]), (PG8_LAS unsigned*)(lds + (bufoff) + ldsw + _i * 8192), 16, 0, 0); } while (0)
; #define PG8_WAIT_V(n) asm volatile("s_waitcnt vmcnt(" #n ")" ::: "memory")
; #define PG8_BAR __builtin_amdgcn_s_barrier()
; template <class Epi, class Sched, bool ALIGN_EPI = false, bool SP2 = false>
; __device__ __forceinline__ void gemm_phase(PG8_LAS unsigned char* lds, const Gemm g, const Sched& S, const Epi& E) {
;     ...
;     if constexpr (SP2) {
;         PG8_STAGE(PG8_SB(0, 0), cB, voffB); PG8_STAGE(PG8_SB(0, 1), cB + hstep, voffB); PG8_STAGE(PG8_SA(0, 0), cA, voffA); PG8_STAGE(PG8_SA(0, 1), cA + hstep, voffA);
;         if (wr == 1) PG8_BAR;
;         PG8_WAIT_V(2); PG8_BAR;
;         PG8_STAGE(PG8_SB(1, 0), cB + kstep, voffB); PG8_STAGE(PG8_SA(1, 0), cA + kstep, voffA); PG8_STAGE(PG8_SB(1, 1), cB + hstep + kstep, voffB);
;         PG8_WAIT_V(6); PG8_BAR;
.LBB0_1032:
	s_add_u32 s12, s6, 0x27400000
	s_addc_u32 s13, s7, 0
	s_add_u32 s62, s6, 0x134000
	s_addc_u32 s63, s7, 0
	s_lshl_b32 s6, s14, 5
	s_mov_b64 s[14:15], 0x80
	s_and_b32 s19, s6, 0x60
	s_add_i32 m0, s35, 0x18000
	v_lshl_add_u64 v[6:7], v[6:7], 0, s[14:15]
	s_lshl_b32 s18, s17, 13
	s_lshl_b32 s20, s19, 7
	global_load_lds_dwordx4 v[6:7], off
	v_lshl_add_u64 v[2:3], v[2:3], 0, s[14:15]
	s_add_i32 m0, s35, 0x1a000
	s_add_i32 s64, s35, 0x8000
	s_add_i32 s65, s35, 0xa000
	global_load_lds_dwordx4 v[2:3], off
	v_lshl_add_u64 v[0:1], v[0:1], 0, s[14:15]
	s_mov_b32 m0, s64
	s_add_u32 s6, s46, 0x80080
	global_load_lds_dwordx4 v[0:1], off
	v_lshl_add_u64 v[0:1], v[4:5], 0, s[14:15]
	s_mov_b32 m0, s65
	s_addc_u32 s7, s47, 0
	global_load_lds_dwordx4 v[0:1], off
	s_add_i32 m0, s35, 0x1c000
	v_lshl_add_u64 v[0:1], s[6:7], 0, v[146:147]
	global_load_lds_dwordx4 v[0:1], off
	v_lshl_add_u64 v[0:1], s[6:7], 0, v[150:151]
	s_add_i32 m0, s35, 0x1e000
	s_cmpk_lt_u32 s16, 0x100
	global_load_lds_dwordx4 v[0:1], off
	s_waitcnt vmcnt(8)
	s_barrier
	v_lshrrev_b32_e32 v1, 1, v8
	v_and_b32_e32 v1, 24, v1
	v_and_b32_e32 v0, 15, v8
	v_lshlrev_b32_e32 v2, 1, v1
	v_lshl_or_b32 v166, s17, 6, v0
	v_lshl_or_b32 v0, v0, 6, v2
	v_lshlrev_b32_e32 v2, 2, v8
	v_and_b32_e32 v2, 32, v2
	v_bitop3_b32 v3, v0, s18, v2 bitop3:0xde
	v_bitop3_b32 v167, v0, s20, v2 bitop3:0xde
	v_lshlrev_b32_e32 v0, 15, v12
	v_and_b32_e32 v0, 0xffff0000, v0
	v_or_b32_e32 v168, s19, v1
	v_lshl_add_u32 v0, v13, 12, v0
	v_and_b32_e32 v1, 1, v12
	v_lshl_or_b32 v0, v1, 6, v0
	v_lshl_add_u32 v152, v14, 1, v0
	v_lshlrev_b32_e32 v0, 15, v9
	v_and_b32_e32 v0, 0xffff0000, v0
	s_waitcnt vmcnt(6)
	v_lshl_add_u32 v0, v10, 12, v0
	v_and_b32_e32 v1, 1, v9
	s_cselect_b64 s[16:17], -1, 0
	v_lshl_or_b32 v0, v1, 6, v0
	s_add_i32 s67, 0, 0x10000
	s_add_i32 s68, 0, 0x14000
	s_ashr_i32 s66, s3, 31
	v_mov_b32_e32 v153, v147
	v_lshl_add_u32 v154, v11, 1, v0
	v_mov_b32_e32 v155, v147
	v_mov_b64_e32 v[156:157], 0x200
	v_mov_b64_e32 v[158:159], 0x1ff
	v_add_u32_e32 v169, s67, v167
	v_add_u32_e32 v170, s68, v167
	v_add_u32_e32 v171, 0, v3
	s_mov_b32 s69, 0x80000
	s_mov_b64 s[18:19], 0x90000
	s_mov_b32 s70, 0x90000
	s_mov_b64 s[20:21], 0xa0000
	s_mov_b32 s71, 0xa0000
	s_mov_b64 s[22:23], 0xb0000
	s_mov_b32 s72, 0xb0000
	s_barrier
	s_branch .LBB0_1035

; #define PG8_STAGE(bufoff, gbase, voff) do { _Pragma("unroll") for (int _i = 0; _i < 2; ++_i) \
;         __builtin_amdgcn_global_load_lds((const unsigned*)((const char*)(gbase) + (voff)[_i]), (PG8_LAS unsigned*)(lds + (bufoff) + ldsw + _i * 8192), 16, 0, 0); } while (0)
; #define PG8_WAIT_V(n) asm volatile("s_waitcnt vmcnt(" #n ")" ::: "memory")
; #define PG8_BAR __builtin_amdgcn_s_barrier()
; template <class Epi, class Sched, bool ALIGN_EPI = false, bool SP2 = false>
; __device__ __forceinline__ void gemm_phase(PG8_LAS unsigned char* lds, const Gemm g, const Sched& S, const Epi& E) {
;     ...
;     if constexpr (SP2) {
;         PG8_STAGE(PG8_SB(0, 0), cB, voffB); PG8_STAGE(PG8_SB(0, 1), cB + hstep, voffB); PG8_STAGE(PG8_SA(0, 0), cA, voffA); PG8_STAGE(PG8_SA(0, 1), cA + hstep, voffA);
;         if (wr == 1) PG8_BAR;
;         PG8_WAIT_V(2); PG8_BAR;
;         PG8_STAGE(PG8_SB(1, 0), cB + kstep, voffB); PG8_STAGE(PG8_SA(1, 0), cA + kstep, voffA); PG8_STAGE(PG8_SB(1, 1), cB + hstep + kstep, voffB);
;         PG8_WAIT_V(6); PG8_BAR;
.LBB0_1164:
	s_add_u32 s10, s6, 0x1c400000
	s_addc_u32 s11, s7, 0
	s_lshl_b32 s6, s12, 5
	s_mov_b64 s[12:13], 0x80
	s_and_b32 s17, s6, 0x60
	s_add_i32 m0, s25, 0x18000
	v_lshl_add_u64 v[6:7], v[6:7], 0, s[12:13]
	s_lshl_b32 s16, s15, 13
	s_lshl_b32 s18, s17, 7
	global_load_lds_dwordx4 v[6:7], off
	v_lshl_add_u64 v[4:5], v[4:5], 0, s[12:13]
	s_add_i32 m0, s25, 0x1a000
	s_add_i32 s55, s25, 0x8000
	s_add_i32 s56, s25, 0xa000
	global_load_lds_dwordx4 v[4:5], off
	v_lshl_add_u64 v[0:1], v[0:1], 0, s[12:13]
	s_mov_b32 m0, s55
	s_add_u32 s6, s28, 0x80080
	global_load_lds_dwordx4 v[0:1], off
	v_lshl_add_u64 v[0:1], v[2:3], 0, s[12:13]
	s_mov_b32 m0, s56
	s_addc_u32 s7, s29, 0
	global_load_lds_dwordx4 v[0:1], off
	s_add_i32 m0, s25, 0x1c000
	v_lshl_add_u64 v[0:1], s[6:7], 0, v[132:133]
	global_load_lds_dwordx4 v[0:1], off
	v_lshl_add_u64 v[0:1], s[6:7], 0, v[128:129]
	s_add_i32 m0, s25, 0x1e000
	s_cmpk_lt_u32 s14, 0x100
	global_load_lds_dwordx4 v[0:1], off
	s_waitcnt vmcnt(8)
	s_barrier
	v_lshrrev_b32_e32 v1, 1, v8
	v_and_b32_e32 v1, 24, v1
	v_and_b32_e32 v0, 15, v8
	v_lshlrev_b32_e32 v2, 1, v1
	v_lshl_or_b32 v148, s15, 6, v0
	v_lshl_or_b32 v0, v0, 6, v2
	v_lshlrev_b32_e32 v2, 2, v8
	v_and_b32_e32 v2, 32, v2
	v_bitop3_b32 v3, v0, s16, v2 bitop3:0xde
	v_bitop3_b32 v149, v0, s18, v2 bitop3:0xde
	v_lshlrev_b32_e32 v0, 15, v9
	v_and_b32_e32 v0, 0xffff0000, v0
	v_or_b32_e32 v150, s17, v1
	v_lshl_add_u32 v0, v10, 12, v0
	v_and_b32_e32 v1, 1, v9
	v_lshl_or_b32 v0, v1, 6, v0
	v_lshl_add_u32 v136, v11, 1, v0
	v_lshlrev_b32_e32 v0, 15, v13
	v_and_b32_e32 v0, 0xffff0000, v0
	s_waitcnt vmcnt(6)
	v_lshl_add_u32 v0, v12, 12, v0
	v_and_b32_e32 v1, 1, v13
	s_cselect_b64 s[14:15], -1, 0
	v_lshl_or_b32 v0, v1, 6, v0
	s_add_i32 s58, 0, 0x10000
	s_add_i32 s59, 0, 0x14000
	s_ashr_i32 s57, s3, 31
	v_mov_b32_e32 v137, v133
	v_lshl_add_u32 v138, v14, 1, v0
	v_mov_b32_e32 v139, v133
	v_mov_b64_e32 v[140:141], 0xb00
	v_mov_b64_e32 v[142:143], 0xaff
	v_add_u32_e32 v151, s58, v149
	v_add_u32_e32 v152, s59, v149
	v_add_u32_e32 v153, 0, v3
	s_movk_i32 s60, 0x2c00
	s_barrier
	s_branch .LBB0_1167

; #define PG8_STAGE(bufoff, gbase, voff) do { _Pragma("unroll") for (int _i = 0; _i < 2; ++_i) \
;         __builtin_amdgcn_global_load_lds((const unsigned*)((const char*)(gbase) + (voff)[_i]), (PG8_LAS unsigned*)(lds + (bufoff) + ldsw + _i * 8192), 16, 0, 0); } while (0)
; #define PG8_WAIT_V(n) asm volatile("s_waitcnt vmcnt(" #n ")" ::: "memory")
; #define PG8_BAR __builtin_amdgcn_s_barrier()
; template <class Epi, class Sched, bool ALIGN_EPI = false, bool SP2 = false>
; __device__ __forceinline__ void gemm_phase(PG8_LAS unsigned char* lds, const Gemm g, const Sched& S, const Epi& E) {
;     ...
;     if constexpr (SP2) {
;         PG8_STAGE(PG8_SB(0, 0), cB, voffB); PG8_STAGE(PG8_SB(0, 1), cB + hstep, voffB); PG8_STAGE(PG8_SA(0, 0), cA, voffA); PG8_STAGE(PG8_SA(0, 1), cA + hstep, voffA);
;         if (wr == 1) PG8_BAR;
;         PG8_WAIT_V(2); PG8_BAR;
;         PG8_STAGE(PG8_SB(1, 0), cB + kstep, voffB); PG8_STAGE(PG8_SA(1, 0), cA + kstep, voffA); PG8_STAGE(PG8_SB(1, 1), cB + hstep + kstep, voffB);
;         PG8_WAIT_V(6); PG8_BAR;
.LBB0_1236:
	s_add_u32 s12, s6, 0x27400000
	s_addc_u32 s13, s7, 0
	s_add_u32 s14, s6, 0x10400000
	s_addc_u32 s15, s7, 0
	s_add_u32 s60, s6, 0x13a000
	s_addc_u32 s61, s7, 0
	s_lshl_b32 s6, s16, 5
	s_mov_b64 s[16:17], 0x80
	s_and_b32 s21, s6, 0x60
	s_add_i32 m0, s55, 0x18000
	v_lshl_add_u64 v[6:7], v[6:7], 0, s[16:17]
	s_lshl_b32 s19, s8, 13
	s_lshl_b32 s22, s21, 7
	global_load_lds_dwordx4 v[6:7], off
	v_lshl_add_u64 v[2:3], v[2:3], 0, s[16:17]
	s_add_i32 m0, s55, 0x1a000
	s_add_i32 s62, s55, 0x8000
	s_add_i32 s63, s55, 0xa000
	global_load_lds_dwordx4 v[2:3], off
	v_lshl_add_u64 v[0:1], v[0:1], 0, s[16:17]
	s_mov_b32 m0, s62
	s_add_u32 s6, s34, 0x160080
	global_load_lds_dwordx4 v[0:1], off
	v_lshl_add_u64 v[0:1], v[4:5], 0, s[16:17]
	s_mov_b32 m0, s63
	s_addc_u32 s7, s35, 0
	global_load_lds_dwordx4 v[0:1], off
	s_add_i32 m0, s55, 0x1c000
	v_lshl_add_u64 v[0:1], s[6:7], 0, v[146:147]
	global_load_lds_dwordx4 v[0:1], off
	v_lshl_add_u64 v[0:1], s[6:7], 0, v[150:151]
	s_add_i32 m0, s55, 0x1e000
	s_mov_b64 s[6:7], 0x160080
	global_load_lds_dwordx4 v[0:1], off
	s_waitcnt vmcnt(8)
	s_barrier
	v_lshrrev_b32_e32 v1, 1, v8
	v_and_b32_e32 v1, 24, v1
	v_and_b32_e32 v0, 15, v8
	v_lshlrev_b32_e32 v2, 1, v1
	v_lshl_or_b32 v166, s8, 6, v0
	v_lshl_or_b32 v0, v0, 6, v2
	v_lshlrev_b32_e32 v2, 2, v8
	v_and_b32_e32 v2, 32, v2
	v_bitop3_b32 v3, v0, s19, v2 bitop3:0xde
	v_bitop3_b32 v167, v0, s22, v2 bitop3:0xde
	v_or_b32_e32 v168, s21, v1
	v_lshrrev_b32_e32 v1, 1, v13
	v_mul_lo_u32 v0, v14, s9
	v_mad_u64_u32 v[0:1], s[22:23], v1, s20, v[0:1]
	v_or_b32_e32 v0, v0, v15
	v_add_lshl_u32 v0, v0, v16, 1
	v_mov_b32_e32 v1, v147
	v_lshl_add_u64 v[152:153], v[0:1], 0, s[6:7]
	v_lshrrev_b32_e32 v1, 1, v9
	v_mul_lo_u32 v0, v10, s9
	v_mad_u64_u32 v[0:1], s[8:9], v1, s20, v[0:1]
	s_waitcnt vmcnt(6)
	s_cmpk_lt_u32 s18, 0x100
	v_or_b32_e32 v0, v0, v11
	s_cselect_b64 s[18:19], -1, 0
	v_add_lshl_u32 v0, v0, v12, 1
	v_mov_b32_e32 v1, v147
	s_add_i32 s65, 0, 0x10000
	s_add_i32 s66, 0, 0x14000
	s_ashr_i32 s64, s3, 31
	v_lshl_add_u64 v[154:155], v[0:1], 0, s[6:7]
	v_mov_b64_e32 v[156:157], 0x200
	v_mov_b64_e32 v[158:159], 0x1ff
	v_add_u32_e32 v169, s65, v167
	v_add_u32_e32 v170, s66, v167
	v_add_u32_e32 v171, 0, v3
	s_mov_b64 s[20:21], 0x40000
	s_mov_b64 s[22:23], 0x48000
	s_mov_b64 s[24:25], 0x50000
	s_mov_b64 s[26:27], 0x58000
	s_barrier
	s_branch .LBB0_1239

; __device__ __forceinline__ float bf_lo(unsigned w) { return __uint_as_float(w << 16); }
; __device__ __forceinline__ float bf_hi(unsigned w) { return __uint_as_float(w & 0xffff0000u); }
; template <int MODE, bool INBF> ...
;     ...
;                     for (int j = 0; j < 8; ++j) { const u32x2 w = xr[64 * j]; v[q][j] = (f32x4){bf_lo(w.x), bf_hi(w.x), bf_lo(w.y), bf_hi(w.y)}; }
;                 } else { const f32x4* xr = (const f32x4*)((const float*)xin_ + (size_t)row * DM) + lane;
; #pragma unroll
;                     for (int j = 0; j < 8; ++j) v[q][j] = xr[64 * j]; } }
; #pragma unroll
;             for (int q = 0; q < RB; ++q) { const int row = blk * 64 + wave + 8 * (i0 + q); float ss = 0.f;
; #pragma unroll
;                 for (int j = 0; j < 8; ++j) ss += (v[q][j].x * v[q][j].x + v[q][j].y * v[q][j].y) + (v[q][j].z * v[q][j].z + v[q][j].w * v[q][j].w);
;                 const float rstd = 1.0f / sqrtf(wave_sum(ss) * (1.0f / DM) + EPS);
.LBB0_1327:
	v_lshl_add_u64 v[30:31], v[28:29], 0, s[20:21]
	v_add_co_u32_e32 v106, vcc, 0x10400000, v30
	ds_read_b128 v[0:3], v38
	ds_read_b128 v[4:7], v38 offset:1024
	ds_read_b128 v[12:15], v38 offset:8192
	ds_read_b128 v[8:11], v38 offset:9216
	ds_read_b128 v[16:19], v38 offset:2048
	ds_read_b128 v[46:49], v38 offset:3072
	ds_read_b128 v[50:53], v38 offset:10240
	ds_read_b128 v[54:57], v38 offset:11264
	ds_read_b128 v[58:61], v38 offset:4096
	ds_read_b128 v[62:65], v38 offset:5120
	ds_read_b128 v[66:69], v38 offset:12288
	ds_read_b128 v[70:73], v38 offset:13312
	ds_read_b128 v[74:77], v38 offset:6144
	ds_read_b128 v[78:81], v38 offset:7168
	ds_read_b128 v[82:85], v38 offset:14336
	ds_read_b128 v[86:89], v38 offset:15360
	v_addc_co_u32_e32 v107, vcc, 0, v31, vcc
	flat_load_dwordx4 v[90:93], v[106:107]
	flat_load_dwordx4 v[94:97], v[106:107] offset:1024
	flat_load_dwordx4 v[98:101], v[106:107] offset:2048
	flat_load_dwordx4 v[102:105], v[106:107] offset:3072
	v_add_co_u32_e32 v30, vcc, 0x10401000, v30
	v_lshl_add_u64 v[122:123], v[26:27], 0, s[20:21]
	s_nop 0
	v_addc_co_u32_e32 v31, vcc, 0, v31, vcc
	flat_load_dwordx4 v[106:109], v[30:31]
	flat_load_dwordx4 v[110:113], v[30:31] offset:1024
	flat_load_dwordx4 v[114:117], v[30:31] offset:3072
	flat_load_dwordx4 v[118:121], v[30:31] offset:2048
	s_add_u32 s20, s20, 0x10000
	s_addc_u32 s21, s21, 0
	s_cmp_lg_u32 s20, 0x80000
	s_waitcnt vmcnt(0) lgkmcnt(0)
	v_mov_b32_e32 v124, v91
	v_mov_b32_e32 v125, v95
	v_mov_b32_e32 v128, v93
	v_mov_b32_e32 v129, v97
	v_mov_b32_e32 v30, v90
	v_mov_b32_e32 v31, v94
	v_mov_b32_e32 v126, v92
	v_mov_b32_e32 v127, v96
	v_pk_mul_f32 v[130:131], v[100:101], v[100:101]
	v_pk_mul_f32 v[132:133], v[98:99], v[98:99]
	v_pk_mul_f32 v[124:125], v[124:125], v[124:125]
	v_pk_mul_f32 v[128:129], v[128:129], v[128:129]
	v_pk_mov_b32 v[138:139], v[132:133], v[130:131] op_sel:[1,0]
	v_mov_b32_e32 v133, v131
	v_pk_fma_f32 v[30:31], v[30:31], v[30:31], v[124:125]
	v_pk_fma_f32 v[124:125], v[126:127], v[126:127], v[128:129]
	v_mul_f32_e32 v134, v103, v103
	v_mul_f32_e32 v136, v105, v105
	v_pk_add_f32 v[126:127], v[138:139], v[132:133]
	v_pk_add_f32 v[30:31], v[30:31], v[124:125]
	v_mul_f32_e32 v45, v106, v106
	v_mul_f32_e32 v143, v107, v107
	v_mul_f32_e32 v145, v108, v108
	v_mul_f32_e32 v146, v109, v109
	v_pk_fma_f32 v[130:131], v[102:103], v[102:103], v[134:135] op_sel_hi:[1,1,0]
	v_pk_fma_f32 v[134:135], v[104:105], v[104:105], v[136:137] op_sel_hi:[1,1,0]
	v_pk_add_f32 v[124:125], v[126:127], v[126:127] op_sel:[0,1] op_sel_hi:[1,0]
	v_pk_add_f32 v[30:31], v[30:31], v[30:31] op_sel:[0,1] op_sel_hi:[1,0]
	v_pk_mul_f32 v[136:137], v[112:113], v[112:113]
	v_pk_mul_f32 v[140:141], v[110:111], v[110:111]
	v_mov_b32_e32 v131, v145
	v_mov_b32_e32 v135, v146
	v_mov_b32_e32 v125, v143
	v_mov_b32_e32 v31, v45
	v_pk_mov_b32 v[128:129], v[140:141], v[136:137] op_sel:[1,0]
	v_mov_b32_e32 v141, v137
	v_pk_add_f32 v[126:127], v[130:131], v[134:135]
	v_pk_add_f32 v[30:31], v[30:31], v[124:125]
	v_mul_f32_e32 v142, v119, v119
	v_mul_f32_e32 v144, v121, v121
	v_pk_add_f32 v[128:129], v[128:129], v[140:141]
	v_pk_add_f32 v[30:31], v[30:31], v[126:127]
	v_mul_f32_e32 v147, v114, v114
	v_mul_f32_e32 v148, v115, v115
	v_mul_f32_e32 v149, v116, v116
	v_mul_f32_e32 v150, v117, v117
	v_pk_fma_f32 v[132:133], v[118:119], v[118:119], v[142:143] op_sel_hi:[1,1,0]
	v_pk_fma_f32 v[136:137], v[120:121], v[120:121], v[144:145] op_sel_hi:[1,1,0]
	v_pk_add_f32 v[128:129], v[128:129], v[128:129] op_sel:[0,1] op_sel_hi:[1,0]
	v_pk_add_f32 v[30:31], v[30:31], v[30:31] op_sel:[0,1] op_sel_hi:[1,0]
	v_mov_b32_e32 v133, v149
	v_mov_b32_e32 v137, v150
	v_mov_b32_e32 v129, v148
	v_mov_b32_e32 v31, v147
	v_pk_add_f32 v[130:131], v[132:133], v[136:137]
	v_pk_add_f32 v[30:31], v[30:31], v[128:129]
	s_nop 0
	v_pk_add_f32 v[30:31], v[30:31], v[130:131]
	s_nop 0
	v_add_f32_e32 v30, v30, v31
	s_nop 0
	s_waitcnt lgkmcnt(0)
	s_nop 1
	v_add_f32_dpp v30, v30, v30 quad_perm:[1,0,3,2] row_mask:0xf bank_mask:0xf
	s_nop 0
	s_waitcnt lgkmcnt(0)
; #define LAS __attribute__((address_space(3)))
; template <int MODE, bool INBF> ...
;     ...
;                 const float rstd = 1.0f / sqrtf(wave_sum(ss) * (1.0f / DM) + EPS);
; #pragma unroll
;                 for (int j = 0; j < 8; ++j) { const f32x4 a = *(const LAS f32x4*)(cA + 4 * (64 * j + lane)), bb = *(const LAS f32x4*)(cB + 4 * (64 * j + lane)); v[q][j] = (v[q][j] * rstd) * a + bb; }
;                 if (MODE == 1) { f32x4* o = (f32x4*)(outf + (size_t)row * DM) + lane;
; #pragma unroll
;                     for (int j = 0; j < 8; ++j) o[64 * j] = v[q][j];
	s_nop 1
	v_add_f32_dpp v30, v30, v30 quad_perm:[2,3,0,1] row_mask:0xf bank_mask:0xf
	s_nop 0
	s_waitcnt lgkmcnt(0)
	s_nop 1
	v_add_f32_dpp v30, v30, v30 row_half_mirror row_mask:0xf bank_mask:0xf
	s_nop 0
	s_waitcnt lgkmcnt(0)
	s_nop 1
	v_add_f32_dpp v30, v30, v30 row_mirror row_mask:0xf bank_mask:0xf
	v_mov_b32_e32 v31, v30
	s_waitcnt lgkmcnt(0)
	s_nop 1
	v_permlane16_swap_b32_e32 v30, v31
	v_add_f32_e32 v30, v30, v31
	v_mov_b32_e32 v31, v30
	s_waitcnt lgkmcnt(0)
	s_nop 1
	v_permlane32_swap_b32_e32 v30, v31
	v_add_f32_e32 v30, v30, v31
	v_fmamk_f32 v30, v30, 0x3a000000, v20
	v_mul_f32_e32 v31, 0x4f800000, v30
	v_cmp_gt_f32_e32 vcc, s29, v30
	s_nop 1
	v_cndmask_b32_e32 v30, v30, v31, vcc
	v_sqrt_f32_e32 v31, v30
	s_nop 0
	v_add_u32_e32 v45, -1, v31
	v_add_u32_e32 v124, 1, v31
	v_fma_f32 v125, -v45, v31, v30
	v_fma_f32 v126, -v124, v31, v30
	v_cmp_ge_f32_e64 s[12:13], 0, v125
	s_nop 1
	v_cndmask_b32_e64 v31, v31, v45, s[12:13]
	v_cmp_lt_f32_e64 s[12:13], 0, v126
	s_nop 1
	v_cndmask_b32_e64 v31, v31, v124, s[12:13]
	v_mul_f32_e32 v45, 0x37800000, v31
	v_cndmask_b32_e32 v31, v31, v45, vcc
	v_cmp_class_f32_e32 vcc, v30, v44
	s_nop 1
	v_cndmask_b32_e32 v31, v31, v30, vcc
	v_div_scale_f32 v30, s[12:13], v31, v31, 1.0
	v_rcp_f32_e32 v124, v30
	v_div_scale_f32 v45, vcc, 1.0, v31, 1.0
	v_fma_f32 v125, -v30, v124, 1.0
	v_fmac_f32_e32 v124, v125, v124
	v_mul_f32_e32 v125, v45, v124
	v_fma_f32 v126, -v30, v125, v45
	v_fmac_f32_e32 v125, v126, v124
	v_fma_f32 v30, -v30, v125, v45
	v_div_fmas_f32 v45, v30, v124, v125
	v_div_fixup_f32 v124, v45, v31, 1.0
	v_pk_mul_f32 v[90:91], v[90:91], v[124:125] op_sel_hi:[1,0]
	v_pk_mul_f32 v[92:93], v[92:93], v[124:125] op_sel_hi:[1,0]
	v_add_co_u32_e32 v30, vcc, s27, v122
	v_pk_mul_f32 v[94:95], v[94:95], v[124:125] op_sel_hi:[1,0]
	v_pk_mul_f32 v[96:97], v[96:97], v[124:125] op_sel_hi:[1,0]
	v_pk_mul_f32 v[98:99], v[98:99], v[124:125] op_sel_hi:[1,0]
	v_pk_mul_f32 v[100:101], v[100:101], v[124:125] op_sel_hi:[1,0]
	v_pk_mul_f32 v[102:103], v[102:103], v[124:125] op_sel_hi:[1,0]
	v_pk_mul_f32 v[104:105], v[104:105], v[124:125] op_sel_hi:[1,0]
	v_pk_mul_f32 v[106:107], v[106:107], v[124:125] op_sel_hi:[1,0]
	v_pk_mul_f32 v[108:109], v[108:109], v[124:125] op_sel_hi:[1,0]
	v_pk_mul_f32 v[110:111], v[110:111], v[124:125] op_sel_hi:[1,0]
	v_pk_mul_f32 v[112:113], v[112:113], v[124:125] op_sel_hi:[1,0]
	v_pk_mul_f32 v[118:119], v[118:119], v[124:125] op_sel_hi:[1,0]
	v_pk_mul_f32 v[120:121], v[120:121], v[124:125] op_sel_hi:[1,0]
	v_pk_mul_f32 v[114:115], v[114:115], v[124:125] op_sel_hi:[1,0]
	v_pk_mul_f32 v[116:117], v[116:117], v[124:125] op_sel_hi:[1,0]
	v_pk_fma_f32 v[2:3], v[2:3], v[92:93], v[14:15]
	v_pk_fma_f32 v[0:1], v[0:1], v[90:91], v[12:13]
	v_addc_co_u32_e32 v31, vcc, 0, v123, vcc
	v_pk_fma_f32 v[6:7], v[6:7], v[96:97], v[10:11]
	v_pk_fma_f32 v[4:5], v[4:5], v[94:95], v[8:9]
	v_pk_fma_f32 v[10:11], v[18:19], v[100:101], v[52:53]
	v_pk_fma_f32 v[8:9], v[16:17], v[98:99], v[50:51]
	v_pk_fma_f32 v[14:15], v[48:49], v[104:105], v[56:57]
	v_pk_fma_f32 v[12:13], v[46:47], v[102:103], v[54:55]
	v_pk_fma_f32 v[18:19], v[60:61], v[108:109], v[68:69]
	v_pk_fma_f32 v[16:17], v[58:59], v[106:107], v[66:67]
	v_pk_fma_f32 v[48:49], v[64:65], v[112:113], v[72:73]
	v_pk_fma_f32 v[46:47], v[62:63], v[110:111], v[70:71]
	v_pk_fma_f32 v[52:53], v[120:121], v[76:77], v[84:85]
	v_pk_fma_f32 v[50:51], v[118:119], v[74:75], v[82:83]
	v_pk_fma_f32 v[56:57], v[116:117], v[80:81], v[88:89]
	v_pk_fma_f32 v[54:55], v[114:115], v[78:79], v[86:87]
	flat_store_dwordx4 v[122:123], v[0:3]
	flat_store_dwordx4 v[122:123], v[4:7] offset:1024
	flat_store_dwordx4 v[122:123], v[8:11] offset:2048
	flat_store_dwordx4 v[122:123], v[12:15] offset:3072
	flat_store_dwordx4 v[30:31], v[16:19]
	flat_store_dwordx4 v[30:31], v[46:49] offset:1024
	flat_store_dwordx4 v[30:31], v[50:53] offset:2048
	flat_store_dwordx4 v[30:31], v[54:57] offset:3072
	s_cbranch_scc1 .LBB0_1327
	s_add_i32 s2, s2, s3
	s_add_i32 s14, s14, s26
	s_cmpk_lt_i32 s2, 0x100
	s_cbranch_scc1 .LBB0_1311
